# MFMA issue order in all 10 K-loops: k0/k1 of the same accumulator back-to-back (was k-outer)
# speedup vs baseline: 1.0087x; 1.0049x over previous
.LBB0_170:
	ds_read_b128 v[136:139], v191
	ds_read_b128 v[158:161], v191 offset:1024
	ds_read_b128 v[162:165], v191 offset:2048
	ds_read_b128 v[166:169], v191 offset:3072
	ds_read_b128 v[170:173], v192
	ds_read_b128 v[174:177], v192 offset:1024
	ds_read_b128 v[178:181], v192 offset:2048
	ds_read_b128 v[194:197], v192 offset:3072
	s_add_u32 s0, s42, 0xfff00080
	s_addc_u32 s50, s43, -1
	s_cmp_eq_u32 s70, 60
	s_cselect_b32 s53, s23, s50
	s_cselect_b32 s52, s41, s0
	s_cselect_b32 s51, s21, s68
	s_cselect_b32 s50, s66, s67
	s_add_i32 m0, s31, 0xc000
	ds_read_b128 v[198:201], v193
	ds_read_b128 v[202:205], v193 offset:1024
	ds_read_b128 v[206:209], v193 offset:2048
	ds_read_b128 v[210:213], v193 offset:3072
	ds_read_b128 v[214:217], v193 offset:4096
	ds_read_b128 v[218:221], v193 offset:5120
	ds_read_b128 v[222:225], v193 offset:6144
	ds_read_b128 v[226:229], v193 offset:7168
	global_load_lds_dwordx4 v152, s[42:43]
	s_add_i32 m0, s31, 0xe000
	s_nop 0
	global_load_lds_dwordx4 v154, s[42:43]
	s_waitcnt vmcnt(8)
	s_waitcnt lgkmcnt(0)
	s_setprio 1
	s_barrier
	v_mfma_f32_16x16x32_bf16 v[132:135], v[136:139], v[198:201], v[132:135]
	v_mfma_f32_16x16x32_bf16 v[132:135], v[158:161], v[202:205], v[132:135]
	v_mfma_f32_16x16x32_bf16 v[128:131], v[162:165], v[198:201], v[128:131]
	v_mfma_f32_16x16x32_bf16 v[128:131], v[166:169], v[202:205], v[128:131]
	v_mfma_f32_16x16x32_bf16 v[116:119], v[136:139], v[206:209], v[116:119]
	v_mfma_f32_16x16x32_bf16 v[116:119], v[158:161], v[210:213], v[116:119]
	v_mfma_f32_16x16x32_bf16 v[112:115], v[162:165], v[206:209], v[112:115]
	v_mfma_f32_16x16x32_bf16 v[112:115], v[166:169], v[210:213], v[112:115]
	v_mfma_f32_16x16x32_bf16 v[100:103], v[136:139], v[214:217], v[100:103]
	v_mfma_f32_16x16x32_bf16 v[100:103], v[158:161], v[218:221], v[100:103]
	v_mfma_f32_16x16x32_bf16 v[96:99], v[162:165], v[214:217], v[96:99]
	v_mfma_f32_16x16x32_bf16 v[96:99], v[166:169], v[218:221], v[96:99]
	v_mfma_f32_16x16x32_bf16 v[84:87], v[136:139], v[222:225], v[84:87]
	v_mfma_f32_16x16x32_bf16 v[84:87], v[158:161], v[226:229], v[84:87]
	v_mfma_f32_16x16x32_bf16 v[80:83], v[162:165], v[222:225], v[80:83]
	v_mfma_f32_16x16x32_bf16 v[80:83], v[166:169], v[226:229], v[80:83]
	s_setprio 0
	s_setprio 1
	v_mfma_f32_16x16x32_bf16 v[124:127], v[170:173], v[198:201], v[124:127]
	v_mfma_f32_16x16x32_bf16 v[124:127], v[174:177], v[202:205], v[124:127]
	v_mfma_f32_16x16x32_bf16 v[120:123], v[178:181], v[198:201], v[120:123]
	v_mfma_f32_16x16x32_bf16 v[120:123], v[194:197], v[202:205], v[120:123]
	v_mfma_f32_16x16x32_bf16 v[108:111], v[170:173], v[206:209], v[108:111]
	v_mfma_f32_16x16x32_bf16 v[108:111], v[174:177], v[210:213], v[108:111]
	v_mfma_f32_16x16x32_bf16 v[104:107], v[178:181], v[206:209], v[104:107]
	v_mfma_f32_16x16x32_bf16 v[104:107], v[194:197], v[210:213], v[104:107]
	v_mfma_f32_16x16x32_bf16 v[92:95], v[170:173], v[214:217], v[92:95]
	v_mfma_f32_16x16x32_bf16 v[92:95], v[174:177], v[218:221], v[92:95]
	v_mfma_f32_16x16x32_bf16 v[88:91], v[178:181], v[214:217], v[88:91]
	v_mfma_f32_16x16x32_bf16 v[88:91], v[194:197], v[218:221], v[88:91]
	v_mfma_f32_16x16x32_bf16 v[76:79], v[170:173], v[222:225], v[76:79]
	v_mfma_f32_16x16x32_bf16 v[76:79], v[174:177], v[226:229], v[76:79]
	v_mfma_f32_16x16x32_bf16 v[72:75], v[178:181], v[222:225], v[72:75]
	v_mfma_f32_16x16x32_bf16 v[72:75], v[194:197], v[226:229], v[72:75]
	s_setprio 0
	s_barrier
	s_add_i32 s0, s61, s19
	s_mov_b32 m0, s0
	ds_read_b128 v[198:201], v193 offset:16384
	ds_read_b128 v[202:205], v193 offset:17408
	ds_read_b128 v[206:209], v193 offset:18432
	ds_read_b128 v[210:213], v193 offset:19456
	ds_read_b128 v[214:217], v193 offset:20480
	ds_read_b128 v[218:221], v193 offset:21504
	ds_read_b128 v[222:225], v193 offset:22528
	ds_read_b128 v[226:229], v193 offset:23552
	global_load_lds_dwordx4 v142, s[50:51]
	s_add_i32 m0, s0, 0x2000
	s_add_u32 s72, s50, 0x100000
	s_addc_u32 s73, s51, 0
	s_add_i32 s0, s62, s19
	global_load_lds_dwordx4 v146, s[50:51]
	s_mov_b32 m0, s0
	s_nop 0
	global_load_lds_dwordx4 v142, s[72:73]
	s_add_i32 m0, s0, 0x2000
	s_nop 0
	global_load_lds_dwordx4 v146, s[72:73]
	s_mov_b32 m0, s31
	s_nop 0
	global_load_lds_dwordx4 v140, s[52:53]
	s_mov_b32 m0, s35
	s_nop 0
	global_load_lds_dwordx4 v144, s[52:53]
	s_waitcnt vmcnt(8)
	s_waitcnt lgkmcnt(0)
	s_setprio 1
	s_barrier
	v_mfma_f32_16x16x32_bf16 v[68:71], v[136:139], v[198:201], v[68:71]
	v_mfma_f32_16x16x32_bf16 v[68:71], v[158:161], v[202:205], v[68:71]
	v_mfma_f32_16x16x32_bf16 v[64:67], v[162:165], v[198:201], v[64:67]
	v_mfma_f32_16x16x32_bf16 v[64:67], v[166:169], v[202:205], v[64:67]
	v_mfma_f32_16x16x32_bf16 v[52:55], v[136:139], v[206:209], v[52:55]
	v_mfma_f32_16x16x32_bf16 v[52:55], v[158:161], v[210:213], v[52:55]
	v_mfma_f32_16x16x32_bf16 v[48:51], v[162:165], v[206:209], v[48:51]
	v_mfma_f32_16x16x32_bf16 v[48:51], v[166:169], v[210:213], v[48:51]
	v_mfma_f32_16x16x32_bf16 v[36:39], v[136:139], v[214:217], v[36:39]
	v_mfma_f32_16x16x32_bf16 v[36:39], v[158:161], v[218:221], v[36:39]
	v_mfma_f32_16x16x32_bf16 v[32:35], v[162:165], v[214:217], v[32:35]
	v_mfma_f32_16x16x32_bf16 v[32:35], v[166:169], v[218:221], v[32:35]
	v_mfma_f32_16x16x32_bf16 v[20:23], v[136:139], v[222:225], v[20:23]
	v_mfma_f32_16x16x32_bf16 v[20:23], v[158:161], v[226:229], v[20:23]
	v_mfma_f32_16x16x32_bf16 v[16:19], v[162:165], v[222:225], v[16:19]
	v_mfma_f32_16x16x32_bf16 v[16:19], v[166:169], v[226:229], v[16:19]
	s_setprio 0
	s_setprio 1
	v_mfma_f32_16x16x32_bf16 v[60:63], v[170:173], v[198:201], v[60:63]
	v_mfma_f32_16x16x32_bf16 v[60:63], v[174:177], v[202:205], v[60:63]
	v_mfma_f32_16x16x32_bf16 v[56:59], v[178:181], v[198:201], v[56:59]
	v_mfma_f32_16x16x32_bf16 v[56:59], v[194:197], v[202:205], v[56:59]
	v_mfma_f32_16x16x32_bf16 v[44:47], v[170:173], v[206:209], v[44:47]
	v_mfma_f32_16x16x32_bf16 v[44:47], v[174:177], v[210:213], v[44:47]
	v_mfma_f32_16x16x32_bf16 v[40:43], v[178:181], v[206:209], v[40:43]
	v_mfma_f32_16x16x32_bf16 v[40:43], v[194:197], v[210:213], v[40:43]
	v_mfma_f32_16x16x32_bf16 v[28:31], v[170:173], v[214:217], v[28:31]
	v_mfma_f32_16x16x32_bf16 v[28:31], v[174:177], v[218:221], v[28:31]
	v_mfma_f32_16x16x32_bf16 v[24:27], v[178:181], v[214:217], v[24:27]
	v_mfma_f32_16x16x32_bf16 v[24:27], v[194:197], v[218:221], v[24:27]
	v_mfma_f32_16x16x32_bf16 v[12:15], v[170:173], v[222:225], v[12:15]
	v_mfma_f32_16x16x32_bf16 v[12:15], v[174:177], v[226:229], v[12:15]
	v_mfma_f32_16x16x32_bf16 v[6:9], v[178:181], v[222:225], v[8:11]
	v_mfma_f32_16x16x32_bf16 v[6:9], v[194:197], v[226:229], v[6:9]
	s_setprio 0
	s_barrier
	s_add_i32 s0, 0, 0x18000
	v_add_u32_e32 v5, s0, v1
	s_add_i32 s71, 0, 0x1c000
	ds_read_b128 v[136:139], v5
	ds_read_b128 v[158:161], v5 offset:1024
	ds_read_b128 v[162:165], v5 offset:2048
	ds_read_b128 v[166:169], v5 offset:3072
	v_add_u32_e32 v5, s71, v1
	ds_read_b128 v[170:173], v5
	ds_read_b128 v[174:177], v5 offset:1024
	ds_read_b128 v[178:181], v5 offset:2048
	ds_read_b128 v[194:197], v5 offset:3072
	s_add_u32 s98, s52, 0x100000
	s_addc_u32 s99, s53, 0
	s_mov_b32 m0, s45
	ds_read_b128 v[198:201], v193 offset:32768
	ds_read_b128 v[202:205], v193 offset:33792
	ds_read_b128 v[206:209], v193 offset:34816
	ds_read_b128 v[210:213], v193 offset:35840
	ds_read_b128 v[214:217], v193 offset:36864
	ds_read_b128 v[218:221], v193 offset:37888
	ds_read_b128 v[222:225], v193 offset:38912
	ds_read_b128 v[226:229], v193 offset:39936
	global_load_lds_dwordx4 v140, s[98:99]
	s_mov_b32 m0, s46
	s_nop 0
	global_load_lds_dwordx4 v144, s[98:99]
	s_waitcnt vmcnt(8)
	s_waitcnt lgkmcnt(0)
	s_setprio 1
	s_barrier
	v_mfma_f32_16x16x32_bf16 v[132:135], v[136:139], v[198:201], v[132:135]
	v_mfma_f32_16x16x32_bf16 v[132:135], v[158:161], v[202:205], v[132:135]
	v_mfma_f32_16x16x32_bf16 v[128:131], v[162:165], v[198:201], v[128:131]
	v_mfma_f32_16x16x32_bf16 v[128:131], v[166:169], v[202:205], v[128:131]
	v_mfma_f32_16x16x32_bf16 v[116:119], v[136:139], v[206:209], v[116:119]
	v_mfma_f32_16x16x32_bf16 v[116:119], v[158:161], v[210:213], v[116:119]
	v_mfma_f32_16x16x32_bf16 v[112:115], v[162:165], v[206:209], v[112:115]
	v_mfma_f32_16x16x32_bf16 v[112:115], v[166:169], v[210:213], v[112:115]
	v_mfma_f32_16x16x32_bf16 v[100:103], v[136:139], v[214:217], v[100:103]
	v_mfma_f32_16x16x32_bf16 v[100:103], v[158:161], v[218:221], v[100:103]
	v_mfma_f32_16x16x32_bf16 v[96:99], v[162:165], v[214:217], v[96:99]
	v_mfma_f32_16x16x32_bf16 v[96:99], v[166:169], v[218:221], v[96:99]
	v_mfma_f32_16x16x32_bf16 v[84:87], v[136:139], v[222:225], v[84:87]
	v_mfma_f32_16x16x32_bf16 v[84:87], v[158:161], v[226:229], v[84:87]
	v_mfma_f32_16x16x32_bf16 v[80:83], v[162:165], v[222:225], v[80:83]
	v_mfma_f32_16x16x32_bf16 v[80:83], v[166:169], v[226:229], v[80:83]
	s_setprio 0
	s_setprio 1
	v_mfma_f32_16x16x32_bf16 v[124:127], v[170:173], v[198:201], v[124:127]
	v_mfma_f32_16x16x32_bf16 v[124:127], v[174:177], v[202:205], v[124:127]
	v_mfma_f32_16x16x32_bf16 v[120:123], v[178:181], v[198:201], v[120:123]
	v_mfma_f32_16x16x32_bf16 v[120:123], v[194:197], v[202:205], v[120:123]
	v_mfma_f32_16x16x32_bf16 v[108:111], v[170:173], v[206:209], v[108:111]
	v_mfma_f32_16x16x32_bf16 v[108:111], v[174:177], v[210:213], v[108:111]
	v_mfma_f32_16x16x32_bf16 v[104:107], v[178:181], v[206:209], v[104:107]
	v_mfma_f32_16x16x32_bf16 v[104:107], v[194:197], v[210:213], v[104:107]
	v_mfma_f32_16x16x32_bf16 v[92:95], v[170:173], v[214:217], v[92:95]
	v_mfma_f32_16x16x32_bf16 v[92:95], v[174:177], v[218:221], v[92:95]
	v_mfma_f32_16x16x32_bf16 v[88:91], v[178:181], v[214:217], v[88:91]
	v_mfma_f32_16x16x32_bf16 v[88:91], v[194:197], v[218:221], v[88:91]
	v_mfma_f32_16x16x32_bf16 v[76:79], v[170:173], v[222:225], v[76:79]
	v_mfma_f32_16x16x32_bf16 v[76:79], v[174:177], v[226:229], v[76:79]
	v_mfma_f32_16x16x32_bf16 v[72:75], v[178:181], v[222:225], v[72:75]
	v_mfma_f32_16x16x32_bf16 v[72:75], v[194:197], v[226:229], v[72:75]
	s_setprio 0
	s_barrier
	s_add_i32 s0, s0, s19
	s_add_i32 m0, s0, 0xffffff80
	ds_read_b128 v[198:201], v193 offset:49152
	ds_read_b128 v[202:205], v193 offset:50176
	ds_read_b128 v[206:209], v193 offset:51200
	ds_read_b128 v[210:213], v193 offset:52224
	ds_read_b128 v[214:217], v193 offset:53248
	ds_read_b128 v[218:221], v193 offset:54272
	ds_read_b128 v[222:225], v193 offset:55296
	ds_read_b128 v[226:229], v193 offset:56320
	global_load_lds_dwordx4 v142, s[50:51] offset:128
	s_add_i32 m0, s0, 0x1f80
	s_add_i32 s0, s71, s19
	global_load_lds_dwordx4 v146, s[50:51] offset:128
	s_add_u32 s50, s50, 0x100080
	s_addc_u32 s51, s51, 0
	s_mov_b32 m0, s0
	s_nop 0
	global_load_lds_dwordx4 v142, s[50:51]
	s_add_i32 m0, s0, 0x2000
	s_nop 0
	global_load_lds_dwordx4 v146, s[50:51]
	s_add_i32 m0, s56, 0xffffff80
	s_nop 0
	global_load_lds_dwordx4 v140, s[52:53] offset:128
	s_add_i32 m0, s57, 0xffffff80
	s_nop 0
	global_load_lds_dwordx4 v144, s[52:53] offset:128
	s_waitcnt vmcnt(8)
	s_waitcnt lgkmcnt(0)
	s_setprio 1
	s_barrier
	v_mfma_f32_16x16x32_bf16 v[68:71], v[136:139], v[198:201], v[68:71]
	v_mfma_f32_16x16x32_bf16 v[68:71], v[158:161], v[202:205], v[68:71]
	v_mfma_f32_16x16x32_bf16 v[64:67], v[162:165], v[198:201], v[64:67]
	v_mfma_f32_16x16x32_bf16 v[64:67], v[166:169], v[202:205], v[64:67]
	v_mfma_f32_16x16x32_bf16 v[52:55], v[136:139], v[206:209], v[52:55]
	v_mfma_f32_16x16x32_bf16 v[52:55], v[158:161], v[210:213], v[52:55]
	v_mfma_f32_16x16x32_bf16 v[48:51], v[162:165], v[206:209], v[48:51]
	v_mfma_f32_16x16x32_bf16 v[48:51], v[166:169], v[210:213], v[48:51]
	v_mfma_f32_16x16x32_bf16 v[36:39], v[136:139], v[214:217], v[36:39]
	v_mfma_f32_16x16x32_bf16 v[36:39], v[158:161], v[218:221], v[36:39]
	v_mfma_f32_16x16x32_bf16 v[32:35], v[162:165], v[214:217], v[32:35]
	v_mfma_f32_16x16x32_bf16 v[32:35], v[166:169], v[218:221], v[32:35]
	v_mfma_f32_16x16x32_bf16 v[20:23], v[136:139], v[222:225], v[20:23]
	v_mfma_f32_16x16x32_bf16 v[20:23], v[158:161], v[226:229], v[20:23]
	v_mfma_f32_16x16x32_bf16 v[16:19], v[162:165], v[222:225], v[16:19]
	v_mfma_f32_16x16x32_bf16 v[16:19], v[166:169], v[226:229], v[16:19]
	s_setprio 0
	s_setprio 1
	v_mfma_f32_16x16x32_bf16 v[60:63], v[170:173], v[198:201], v[60:63]
	v_mfma_f32_16x16x32_bf16 v[60:63], v[174:177], v[202:205], v[60:63]
	v_mfma_f32_16x16x32_bf16 v[56:59], v[178:181], v[198:201], v[56:59]
	v_mfma_f32_16x16x32_bf16 v[56:59], v[194:197], v[202:205], v[56:59]
	v_mfma_f32_16x16x32_bf16 v[44:47], v[170:173], v[206:209], v[44:47]
	v_mfma_f32_16x16x32_bf16 v[44:47], v[174:177], v[210:213], v[44:47]
	v_mfma_f32_16x16x32_bf16 v[40:43], v[178:181], v[206:209], v[40:43]
	v_mfma_f32_16x16x32_bf16 v[40:43], v[194:197], v[210:213], v[40:43]
	v_mfma_f32_16x16x32_bf16 v[28:31], v[170:173], v[214:217], v[28:31]
	v_mfma_f32_16x16x32_bf16 v[28:31], v[174:177], v[218:221], v[28:31]
	v_mfma_f32_16x16x32_bf16 v[24:27], v[178:181], v[214:217], v[24:27]
	v_mfma_f32_16x16x32_bf16 v[24:27], v[194:197], v[218:221], v[24:27]
	v_mfma_f32_16x16x32_bf16 v[10:13], v[170:173], v[222:225], v[12:15]
	v_mfma_f32_16x16x32_bf16 v[12:15], v[174:177], v[226:229], v[10:13]
	v_mfma_f32_16x16x32_bf16 v[6:9], v[178:181], v[222:225], v[6:9]
	v_mfma_f32_16x16x32_bf16 v[8:11], v[194:197], v[226:229], v[6:9]
	s_setprio 0
	s_barrier
	s_add_i32 s70, s70, 2
	s_add_u32 s42, s42, 0x100
	s_addc_u32 s43, s43, 0
	s_add_u32 s67, s67, 0x100
	s_addc_u32 s68, s68, 0
	s_cmp_gt_u32 s70, 61
	s_cbranch_scc0 .LBB0_170
	s_and_b64 vcc, exec, s[16:17]
	s_cbranch_vccz .LBB0_173
	s_barrier

.LBB0_342:
	ds_read_b128 v[132:135], v209
	ds_read_b128 v[136:139], v209 offset:1024
	ds_read_b128 v[140:143], v209 offset:2048
	ds_read_b128 v[144:147], v209 offset:3072
	ds_read_b128 v[148:151], v210
	ds_read_b128 v[152:155], v210 offset:1024
	ds_read_b128 v[156:159], v210 offset:2048
	ds_read_b128 v[160:163], v210 offset:3072
	s_add_u32 s0, s26, 0xffd50080
	s_addc_u32 s28, s27, -1
	s_cmpk_eq_i32 s62, 0xa8
	s_cselect_b32 s31, s7, s28
	s_cselect_b32 s30, s6, s0
	s_cselect_b32 s29, s25, s61
	s_cselect_b32 s28, s24, s60
	s_add_i32 m0, s43, 0xc000
	ds_read_b128 v[164:167], v211
	ds_read_b128 v[168:171], v211 offset:1024
	ds_read_b128 v[172:175], v211 offset:2048
	ds_read_b128 v[176:179], v211 offset:3072
	ds_read_b128 v[196:199], v211 offset:4096
	ds_read_b128 v[200:203], v211 offset:5120
	ds_read_b128 v[204:207], v211 offset:6144
	ds_read_b128 v[214:217], v211 offset:7168
	global_load_lds_dwordx4 v188, s[26:27]
	s_add_i32 m0, s43, 0xe000
	s_nop 0
	global_load_lds_dwordx4 v190, s[26:27]
	s_waitcnt vmcnt(8)
	s_waitcnt lgkmcnt(0)
	s_setprio 1
	s_barrier
	v_mfma_f32_16x16x32_bf16 v[128:131], v[132:135], v[164:167], v[128:131]
	v_mfma_f32_16x16x32_bf16 v[128:131], v[136:139], v[168:171], v[128:131]
	v_mfma_f32_16x16x32_bf16 v[124:127], v[140:143], v[164:167], v[124:127]
	v_mfma_f32_16x16x32_bf16 v[124:127], v[144:147], v[168:171], v[124:127]
	v_mfma_f32_16x16x32_bf16 v[112:115], v[132:135], v[172:175], v[112:115]
	v_mfma_f32_16x16x32_bf16 v[112:115], v[136:139], v[176:179], v[112:115]
	v_mfma_f32_16x16x32_bf16 v[108:111], v[140:143], v[172:175], v[108:111]
	v_mfma_f32_16x16x32_bf16 v[108:111], v[144:147], v[176:179], v[108:111]
	v_mfma_f32_16x16x32_bf16 v[96:99], v[132:135], v[196:199], v[96:99]
	v_mfma_f32_16x16x32_bf16 v[96:99], v[136:139], v[200:203], v[96:99]
	v_mfma_f32_16x16x32_bf16 v[92:95], v[140:143], v[196:199], v[92:95]
	v_mfma_f32_16x16x32_bf16 v[92:95], v[144:147], v[200:203], v[92:95]
	v_mfma_f32_16x16x32_bf16 v[80:83], v[132:135], v[204:207], v[80:83]
	v_mfma_f32_16x16x32_bf16 v[80:83], v[136:139], v[214:217], v[80:83]
	v_mfma_f32_16x16x32_bf16 v[76:79], v[140:143], v[204:207], v[76:79]
	v_mfma_f32_16x16x32_bf16 v[76:79], v[144:147], v[214:217], v[76:79]
	s_setprio 0
	s_setprio 1
	v_mfma_f32_16x16x32_bf16 v[120:123], v[148:151], v[164:167], v[120:123]
	v_mfma_f32_16x16x32_bf16 v[120:123], v[152:155], v[168:171], v[120:123]
	v_mfma_f32_16x16x32_bf16 v[116:119], v[156:159], v[164:167], v[116:119]
	v_mfma_f32_16x16x32_bf16 v[116:119], v[160:163], v[168:171], v[116:119]
	v_mfma_f32_16x16x32_bf16 v[104:107], v[148:151], v[172:175], v[104:107]
	v_mfma_f32_16x16x32_bf16 v[104:107], v[152:155], v[176:179], v[104:107]
	v_mfma_f32_16x16x32_bf16 v[100:103], v[156:159], v[172:175], v[100:103]
	v_mfma_f32_16x16x32_bf16 v[100:103], v[160:163], v[176:179], v[100:103]
	v_mfma_f32_16x16x32_bf16 v[88:91], v[148:151], v[196:199], v[88:91]
	v_mfma_f32_16x16x32_bf16 v[88:91], v[152:155], v[200:203], v[88:91]
	v_mfma_f32_16x16x32_bf16 v[84:87], v[156:159], v[196:199], v[84:87]
	v_mfma_f32_16x16x32_bf16 v[84:87], v[160:163], v[200:203], v[84:87]
	v_mfma_f32_16x16x32_bf16 v[72:75], v[148:151], v[204:207], v[72:75]
	v_mfma_f32_16x16x32_bf16 v[72:75], v[152:155], v[214:217], v[72:75]
	v_mfma_f32_16x16x32_bf16 v[68:71], v[156:159], v[204:207], v[68:71]
	v_mfma_f32_16x16x32_bf16 v[68:71], v[160:163], v[214:217], v[68:71]
	s_setprio 0
	s_barrier
	s_add_i32 s0, s53, s42
	s_mov_b32 m0, s0
	ds_read_b128 v[164:167], v211 offset:16384
	ds_read_b128 v[168:171], v211 offset:17408
	ds_read_b128 v[172:175], v211 offset:18432
	ds_read_b128 v[176:179], v211 offset:19456
	ds_read_b128 v[196:199], v211 offset:20480
	ds_read_b128 v[200:203], v211 offset:21504
	ds_read_b128 v[204:207], v211 offset:22528
	ds_read_b128 v[214:217], v211 offset:23552
	global_load_lds_dwordx4 v182, s[28:29]
	s_add_i32 m0, s0, 0x2000
	s_add_u32 s64, s28, 0x2b0000
	s_addc_u32 s65, s29, 0
	s_add_i32 s0, s54, s42
	global_load_lds_dwordx4 v186, s[28:29]
	s_mov_b32 m0, s0
	s_nop 0
	global_load_lds_dwordx4 v182, s[64:65]
	s_add_i32 m0, s0, 0x2000
	s_nop 0
	global_load_lds_dwordx4 v186, s[64:65]
	s_mov_b32 m0, s43
	s_nop 0
	global_load_lds_dwordx4 v180, s[30:31]
	s_mov_b32 m0, s45
	s_nop 0
	global_load_lds_dwordx4 v184, s[30:31]
	s_waitcnt vmcnt(8)
	s_waitcnt lgkmcnt(0)
	s_setprio 1
	s_barrier
	v_mfma_f32_16x16x32_bf16 v[64:67], v[132:135], v[164:167], v[64:67]
	v_mfma_f32_16x16x32_bf16 v[64:67], v[136:139], v[168:171], v[64:67]
	v_mfma_f32_16x16x32_bf16 v[60:63], v[140:143], v[164:167], v[60:63]
	v_mfma_f32_16x16x32_bf16 v[60:63], v[144:147], v[168:171], v[60:63]
	v_mfma_f32_16x16x32_bf16 v[48:51], v[132:135], v[172:175], v[48:51]
	v_mfma_f32_16x16x32_bf16 v[48:51], v[136:139], v[176:179], v[48:51]
	v_mfma_f32_16x16x32_bf16 v[44:47], v[140:143], v[172:175], v[44:47]
	v_mfma_f32_16x16x32_bf16 v[44:47], v[144:147], v[176:179], v[44:47]
	v_mfma_f32_16x16x32_bf16 v[32:35], v[132:135], v[196:199], v[32:35]
	v_mfma_f32_16x16x32_bf16 v[32:35], v[136:139], v[200:203], v[32:35]
	v_mfma_f32_16x16x32_bf16 v[28:31], v[140:143], v[196:199], v[28:31]
	v_mfma_f32_16x16x32_bf16 v[28:31], v[144:147], v[200:203], v[28:31]
	v_mfma_f32_16x16x32_bf16 v[16:19], v[132:135], v[204:207], v[16:19]
	v_mfma_f32_16x16x32_bf16 v[16:19], v[136:139], v[214:217], v[16:19]
	v_mfma_f32_16x16x32_bf16 v[12:15], v[140:143], v[204:207], v[12:15]
	v_mfma_f32_16x16x32_bf16 v[12:15], v[144:147], v[214:217], v[12:15]
	s_setprio 0
	s_setprio 1
	v_mfma_f32_16x16x32_bf16 v[56:59], v[148:151], v[164:167], v[56:59]
	v_mfma_f32_16x16x32_bf16 v[56:59], v[152:155], v[168:171], v[56:59]
	v_mfma_f32_16x16x32_bf16 v[52:55], v[156:159], v[164:167], v[52:55]
	v_mfma_f32_16x16x32_bf16 v[52:55], v[160:163], v[168:171], v[52:55]
	v_mfma_f32_16x16x32_bf16 v[40:43], v[148:151], v[172:175], v[40:43]
	v_mfma_f32_16x16x32_bf16 v[40:43], v[152:155], v[176:179], v[40:43]
	v_mfma_f32_16x16x32_bf16 v[36:39], v[156:159], v[172:175], v[36:39]
	v_mfma_f32_16x16x32_bf16 v[36:39], v[160:163], v[176:179], v[36:39]
	v_mfma_f32_16x16x32_bf16 v[24:27], v[148:151], v[196:199], v[24:27]
	v_mfma_f32_16x16x32_bf16 v[24:27], v[152:155], v[200:203], v[24:27]
	v_mfma_f32_16x16x32_bf16 v[20:23], v[156:159], v[196:199], v[20:23]
	v_mfma_f32_16x16x32_bf16 v[20:23], v[160:163], v[200:203], v[20:23]
	v_mfma_f32_16x16x32_bf16 v[8:11], v[148:151], v[204:207], v[8:11]
	v_mfma_f32_16x16x32_bf16 v[8:11], v[152:155], v[214:217], v[8:11]
	v_mfma_f32_16x16x32_bf16 v[4:7], v[156:159], v[204:207], v[4:7]
	v_mfma_f32_16x16x32_bf16 v[4:7], v[160:163], v[214:217], v[4:7]
	s_setprio 0
	s_barrier
	s_add_i32 s0, 0, 0x18000
	s_add_i32 s63, 0, 0x1c000
	v_add_u32_e32 v144, s0, v3
	v_add_u32_e32 v160, s63, v3
	ds_read_b128 v[132:135], v144
	ds_read_b128 v[136:139], v144 offset:1024
	ds_read_b128 v[140:143], v144 offset:2048
	ds_read_b128 v[144:147], v144 offset:3072
	ds_read_b128 v[148:151], v160
	ds_read_b128 v[152:155], v160 offset:1024
	ds_read_b128 v[156:159], v160 offset:2048
	ds_read_b128 v[160:163], v160 offset:3072
	s_add_u32 s98, s30, 0x2b0000
	s_addc_u32 s99, s31, 0
	s_mov_b32 m0, s46
	ds_read_b128 v[164:167], v211 offset:32768
	ds_read_b128 v[168:171], v211 offset:33792
	ds_read_b128 v[172:175], v211 offset:34816
	ds_read_b128 v[176:179], v211 offset:35840
	ds_read_b128 v[196:199], v211 offset:36864
	ds_read_b128 v[200:203], v211 offset:37888
	ds_read_b128 v[204:207], v211 offset:38912
	ds_read_b128 v[214:217], v211 offset:39936
	global_load_lds_dwordx4 v180, s[98:99]
	s_mov_b32 m0, s47
	s_nop 0
	global_load_lds_dwordx4 v184, s[98:99]
	s_waitcnt vmcnt(8)
	s_waitcnt lgkmcnt(0)
	s_setprio 1
	s_barrier
	v_mfma_f32_16x16x32_bf16 v[128:131], v[132:135], v[164:167], v[128:131]
	v_mfma_f32_16x16x32_bf16 v[128:131], v[136:139], v[168:171], v[128:131]
	v_mfma_f32_16x16x32_bf16 v[124:127], v[140:143], v[164:167], v[124:127]
	v_mfma_f32_16x16x32_bf16 v[124:127], v[144:147], v[168:171], v[124:127]
	v_mfma_f32_16x16x32_bf16 v[112:115], v[132:135], v[172:175], v[112:115]
	v_mfma_f32_16x16x32_bf16 v[112:115], v[136:139], v[176:179], v[112:115]
	v_mfma_f32_16x16x32_bf16 v[108:111], v[140:143], v[172:175], v[108:111]
	v_mfma_f32_16x16x32_bf16 v[108:111], v[144:147], v[176:179], v[108:111]
	v_mfma_f32_16x16x32_bf16 v[96:99], v[132:135], v[196:199], v[96:99]
	v_mfma_f32_16x16x32_bf16 v[96:99], v[136:139], v[200:203], v[96:99]
	v_mfma_f32_16x16x32_bf16 v[92:95], v[140:143], v[196:199], v[92:95]
	v_mfma_f32_16x16x32_bf16 v[92:95], v[144:147], v[200:203], v[92:95]
	v_mfma_f32_16x16x32_bf16 v[80:83], v[132:135], v[204:207], v[80:83]
	v_mfma_f32_16x16x32_bf16 v[80:83], v[136:139], v[214:217], v[80:83]
	v_mfma_f32_16x16x32_bf16 v[76:79], v[140:143], v[204:207], v[76:79]
	v_mfma_f32_16x16x32_bf16 v[76:79], v[144:147], v[214:217], v[76:79]
	s_setprio 0
	s_setprio 1
	v_mfma_f32_16x16x32_bf16 v[120:123], v[148:151], v[164:167], v[120:123]
	v_mfma_f32_16x16x32_bf16 v[120:123], v[152:155], v[168:171], v[120:123]
	v_mfma_f32_16x16x32_bf16 v[116:119], v[156:159], v[164:167], v[116:119]
	v_mfma_f32_16x16x32_bf16 v[116:119], v[160:163], v[168:171], v[116:119]
	v_mfma_f32_16x16x32_bf16 v[104:107], v[148:151], v[172:175], v[104:107]
	v_mfma_f32_16x16x32_bf16 v[104:107], v[152:155], v[176:179], v[104:107]
	v_mfma_f32_16x16x32_bf16 v[100:103], v[156:159], v[172:175], v[100:103]
	v_mfma_f32_16x16x32_bf16 v[100:103], v[160:163], v[176:179], v[100:103]
	v_mfma_f32_16x16x32_bf16 v[88:91], v[148:151], v[196:199], v[88:91]
	v_mfma_f32_16x16x32_bf16 v[88:91], v[152:155], v[200:203], v[88:91]
	v_mfma_f32_16x16x32_bf16 v[84:87], v[156:159], v[196:199], v[84:87]
	v_mfma_f32_16x16x32_bf16 v[84:87], v[160:163], v[200:203], v[84:87]
	v_mfma_f32_16x16x32_bf16 v[72:75], v[148:151], v[204:207], v[72:75]
	v_mfma_f32_16x16x32_bf16 v[72:75], v[152:155], v[214:217], v[72:75]
	v_mfma_f32_16x16x32_bf16 v[68:71], v[156:159], v[204:207], v[68:71]
	v_mfma_f32_16x16x32_bf16 v[68:71], v[160:163], v[214:217], v[68:71]
	s_setprio 0
	s_barrier
	s_add_i32 s0, s0, s42
	s_add_i32 m0, s0, 0xffffff80
	ds_read_b128 v[164:167], v211 offset:49152
	ds_read_b128 v[168:171], v211 offset:50176
	ds_read_b128 v[172:175], v211 offset:51200
	ds_read_b128 v[176:179], v211 offset:52224
	ds_read_b128 v[196:199], v211 offset:53248
	ds_read_b128 v[200:203], v211 offset:54272
	ds_read_b128 v[204:207], v211 offset:55296
	ds_read_b128 v[214:217], v211 offset:56320
	global_load_lds_dwordx4 v182, s[28:29] offset:128
	s_add_i32 m0, s0, 0x1f80
	s_add_i32 s0, s63, s42
	global_load_lds_dwordx4 v186, s[28:29] offset:128
	s_add_u32 s28, s28, 0x2b0080
	s_addc_u32 s29, s29, 0
	s_mov_b32 m0, s0
	s_nop 0
	global_load_lds_dwordx4 v182, s[28:29]
	s_add_i32 m0, s0, 0x2000
	s_nop 0
	global_load_lds_dwordx4 v186, s[28:29]
	s_add_i32 m0, s51, 0xffffff80
	s_nop 0
	global_load_lds_dwordx4 v180, s[30:31] offset:128
	s_add_i32 m0, s52, 0xffffff80
	s_nop 0
	global_load_lds_dwordx4 v184, s[30:31] offset:128
	s_waitcnt vmcnt(8)
	s_waitcnt lgkmcnt(0)
	s_setprio 1
	s_barrier
	v_mfma_f32_16x16x32_bf16 v[64:67], v[132:135], v[164:167], v[64:67]
	v_mfma_f32_16x16x32_bf16 v[64:67], v[136:139], v[168:171], v[64:67]
	v_mfma_f32_16x16x32_bf16 v[60:63], v[140:143], v[164:167], v[60:63]
	v_mfma_f32_16x16x32_bf16 v[60:63], v[144:147], v[168:171], v[60:63]
	v_mfma_f32_16x16x32_bf16 v[48:51], v[132:135], v[172:175], v[48:51]
	v_mfma_f32_16x16x32_bf16 v[48:51], v[136:139], v[176:179], v[48:51]
	v_mfma_f32_16x16x32_bf16 v[44:47], v[140:143], v[172:175], v[44:47]
	v_mfma_f32_16x16x32_bf16 v[44:47], v[144:147], v[176:179], v[44:47]
	v_mfma_f32_16x16x32_bf16 v[32:35], v[132:135], v[196:199], v[32:35]
	v_mfma_f32_16x16x32_bf16 v[32:35], v[136:139], v[200:203], v[32:35]
	v_mfma_f32_16x16x32_bf16 v[28:31], v[140:143], v[196:199], v[28:31]
	v_mfma_f32_16x16x32_bf16 v[28:31], v[144:147], v[200:203], v[28:31]
	v_mfma_f32_16x16x32_bf16 v[16:19], v[132:135], v[204:207], v[16:19]
	v_mfma_f32_16x16x32_bf16 v[16:19], v[136:139], v[214:217], v[16:19]
	v_mfma_f32_16x16x32_bf16 v[12:15], v[140:143], v[204:207], v[12:15]
	v_mfma_f32_16x16x32_bf16 v[12:15], v[144:147], v[214:217], v[12:15]
	s_setprio 0
	s_setprio 1
	v_mfma_f32_16x16x32_bf16 v[56:59], v[148:151], v[164:167], v[56:59]
	v_mfma_f32_16x16x32_bf16 v[56:59], v[152:155], v[168:171], v[56:59]
	v_mfma_f32_16x16x32_bf16 v[52:55], v[156:159], v[164:167], v[52:55]
	v_mfma_f32_16x16x32_bf16 v[52:55], v[160:163], v[168:171], v[52:55]
	v_mfma_f32_16x16x32_bf16 v[40:43], v[148:151], v[172:175], v[40:43]
	v_mfma_f32_16x16x32_bf16 v[40:43], v[152:155], v[176:179], v[40:43]
	v_mfma_f32_16x16x32_bf16 v[36:39], v[156:159], v[172:175], v[36:39]
	v_mfma_f32_16x16x32_bf16 v[36:39], v[160:163], v[176:179], v[36:39]
	v_mfma_f32_16x16x32_bf16 v[24:27], v[148:151], v[196:199], v[24:27]
	v_mfma_f32_16x16x32_bf16 v[24:27], v[152:155], v[200:203], v[24:27]
	v_mfma_f32_16x16x32_bf16 v[20:23], v[156:159], v[196:199], v[20:23]
	v_mfma_f32_16x16x32_bf16 v[20:23], v[160:163], v[200:203], v[20:23]
	v_mfma_f32_16x16x32_bf16 v[8:11], v[148:151], v[204:207], v[8:11]
	v_mfma_f32_16x16x32_bf16 v[8:11], v[152:155], v[214:217], v[8:11]
	v_mfma_f32_16x16x32_bf16 v[4:7], v[156:159], v[204:207], v[4:7]
	v_mfma_f32_16x16x32_bf16 v[4:7], v[160:163], v[214:217], v[4:7]
	s_setprio 0
	s_barrier
	s_add_i32 s62, s62, 2
	s_add_u32 s26, s26, 0x100
	s_addc_u32 s27, s27, 0
	s_add_u32 s60, s60, 0x100
	s_addc_u32 s61, s61, 0
	s_cmpk_gt_u32 s62, 0xa9
	s_cbranch_scc0 .LBB0_342
	s_and_b64 vcc, exec, s[22:23]
	s_cbranch_vccz .LBB0_345
	s_barrier

.LBB0_429:
	ds_read_b128 v[150:153], v156
	ds_read_b128 v[162:165], v156 offset:1024
	ds_read_b128 v[166:169], v156 offset:2048
	ds_read_b128 v[170:173], v156 offset:3072
	ds_read_b128 v[174:177], v157
	ds_read_b128 v[178:181], v157 offset:1024
	ds_read_b128 v[182:185], v157 offset:2048
	ds_read_b128 v[186:189], v157 offset:3072
	s_add_u32 s0, s50, 0xfff00080
	s_addc_u32 s52, s51, -1
	s_cmp_eq_u32 s72, 60
	s_cselect_b32 s55, s27, s52
	s_cselect_b32 s54, s67, s0
	s_cselect_b32 s53, s25, s71
	s_cselect_b32 s52, s68, s70
	s_add_i32 m0, s43, 0xc000
	ds_read_b128 v[190:193], v158
	ds_read_b128 v[194:197], v158 offset:1024
	ds_read_b128 v[198:201], v158 offset:2048
	ds_read_b128 v[202:205], v158 offset:3072
	ds_read_b128 v[206:209], v158 offset:4096
	ds_read_b128 v[210:213], v158 offset:5120
	ds_read_b128 v[214:217], v158 offset:6144
	ds_read_b128 v[218:221], v158 offset:7168
	global_load_lds_dwordx4 v142, s[50:51]
	s_add_i32 m0, s43, 0xe000
	s_nop 0
	global_load_lds_dwordx4 v144, s[50:51]
	s_waitcnt vmcnt(8)
	s_waitcnt lgkmcnt(0)
	s_setprio 1
	s_barrier
	v_mfma_f32_16x16x32_bf16 v[128:131], v[150:153], v[190:193], v[128:131]
	v_mfma_f32_16x16x32_bf16 v[128:131], v[162:165], v[194:197], v[128:131]
	v_mfma_f32_16x16x32_bf16 v[124:127], v[166:169], v[190:193], v[124:127]
	v_mfma_f32_16x16x32_bf16 v[124:127], v[170:173], v[194:197], v[124:127]
	v_mfma_f32_16x16x32_bf16 v[112:115], v[150:153], v[198:201], v[112:115]
	v_mfma_f32_16x16x32_bf16 v[112:115], v[162:165], v[202:205], v[112:115]
	v_mfma_f32_16x16x32_bf16 v[108:111], v[166:169], v[198:201], v[108:111]
	v_mfma_f32_16x16x32_bf16 v[108:111], v[170:173], v[202:205], v[108:111]
	v_mfma_f32_16x16x32_bf16 v[96:99], v[150:153], v[206:209], v[96:99]
	v_mfma_f32_16x16x32_bf16 v[96:99], v[162:165], v[210:213], v[96:99]
	v_mfma_f32_16x16x32_bf16 v[92:95], v[166:169], v[206:209], v[92:95]
	v_mfma_f32_16x16x32_bf16 v[92:95], v[170:173], v[210:213], v[92:95]
	v_mfma_f32_16x16x32_bf16 v[80:83], v[150:153], v[214:217], v[80:83]
	v_mfma_f32_16x16x32_bf16 v[80:83], v[162:165], v[218:221], v[80:83]
	v_mfma_f32_16x16x32_bf16 v[76:79], v[166:169], v[214:217], v[76:79]
	v_mfma_f32_16x16x32_bf16 v[76:79], v[170:173], v[218:221], v[76:79]
	s_setprio 0
	s_setprio 1
	v_mfma_f32_16x16x32_bf16 v[120:123], v[174:177], v[190:193], v[120:123]
	v_mfma_f32_16x16x32_bf16 v[120:123], v[178:181], v[194:197], v[120:123]
	v_mfma_f32_16x16x32_bf16 v[116:119], v[182:185], v[190:193], v[116:119]
	v_mfma_f32_16x16x32_bf16 v[116:119], v[186:189], v[194:197], v[116:119]
	v_mfma_f32_16x16x32_bf16 v[104:107], v[174:177], v[198:201], v[104:107]
	v_mfma_f32_16x16x32_bf16 v[104:107], v[178:181], v[202:205], v[104:107]
	v_mfma_f32_16x16x32_bf16 v[100:103], v[182:185], v[198:201], v[100:103]
	v_mfma_f32_16x16x32_bf16 v[100:103], v[186:189], v[202:205], v[100:103]
	v_mfma_f32_16x16x32_bf16 v[88:91], v[174:177], v[206:209], v[88:91]
	v_mfma_f32_16x16x32_bf16 v[88:91], v[178:181], v[210:213], v[88:91]
	v_mfma_f32_16x16x32_bf16 v[84:87], v[182:185], v[206:209], v[84:87]
	v_mfma_f32_16x16x32_bf16 v[84:87], v[186:189], v[210:213], v[84:87]
	v_mfma_f32_16x16x32_bf16 v[72:75], v[174:177], v[214:217], v[72:75]
	v_mfma_f32_16x16x32_bf16 v[72:75], v[178:181], v[218:221], v[72:75]
	v_mfma_f32_16x16x32_bf16 v[68:71], v[182:185], v[214:217], v[68:71]
	v_mfma_f32_16x16x32_bf16 v[68:71], v[186:189], v[218:221], v[68:71]
	s_setprio 0
	s_barrier
	s_add_i32 s0, s62, s41
	s_mov_b32 m0, s0
	ds_read_b128 v[190:193], v158 offset:16384
	ds_read_b128 v[194:197], v158 offset:17408
	ds_read_b128 v[198:201], v158 offset:18432
	ds_read_b128 v[202:205], v158 offset:19456
	ds_read_b128 v[206:209], v158 offset:20480
	ds_read_b128 v[210:213], v158 offset:21504
	ds_read_b128 v[214:217], v158 offset:22528
	ds_read_b128 v[218:221], v158 offset:23552
	global_load_lds_dwordx4 v136, s[52:53]
	s_add_i32 m0, s0, 0x2000
	s_add_u32 s74, s52, 0x100000
	s_addc_u32 s75, s53, 0
	s_add_i32 s0, s63, s41
	global_load_lds_dwordx4 v140, s[52:53]
	s_mov_b32 m0, s0
	s_nop 0
	global_load_lds_dwordx4 v136, s[74:75]
	s_add_i32 m0, s0, 0x2000
	s_nop 0
	global_load_lds_dwordx4 v140, s[74:75]
	s_mov_b32 m0, s43
	s_nop 0
	global_load_lds_dwordx4 v134, s[54:55]
	s_mov_b32 m0, s48
	s_nop 0
	global_load_lds_dwordx4 v138, s[54:55]
	s_waitcnt vmcnt(8)
	s_waitcnt lgkmcnt(0)
	s_setprio 1
	s_barrier
	v_mfma_f32_16x16x32_bf16 v[64:67], v[150:153], v[190:193], v[64:67]
	v_mfma_f32_16x16x32_bf16 v[64:67], v[162:165], v[194:197], v[64:67]
	v_mfma_f32_16x16x32_bf16 v[60:63], v[166:169], v[190:193], v[60:63]
	v_mfma_f32_16x16x32_bf16 v[60:63], v[170:173], v[194:197], v[60:63]
	v_mfma_f32_16x16x32_bf16 v[48:51], v[150:153], v[198:201], v[48:51]
	v_mfma_f32_16x16x32_bf16 v[48:51], v[162:165], v[202:205], v[48:51]
	v_mfma_f32_16x16x32_bf16 v[44:47], v[166:169], v[198:201], v[44:47]
	v_mfma_f32_16x16x32_bf16 v[44:47], v[170:173], v[202:205], v[44:47]
	v_mfma_f32_16x16x32_bf16 v[32:35], v[150:153], v[206:209], v[32:35]
	v_mfma_f32_16x16x32_bf16 v[32:35], v[162:165], v[210:213], v[32:35]
	v_mfma_f32_16x16x32_bf16 v[28:31], v[166:169], v[206:209], v[28:31]
	v_mfma_f32_16x16x32_bf16 v[28:31], v[170:173], v[210:213], v[28:31]
	v_mfma_f32_16x16x32_bf16 v[16:19], v[150:153], v[214:217], v[16:19]
	v_mfma_f32_16x16x32_bf16 v[16:19], v[162:165], v[218:221], v[16:19]
	v_mfma_f32_16x16x32_bf16 v[12:15], v[166:169], v[214:217], v[12:15]
	v_mfma_f32_16x16x32_bf16 v[12:15], v[170:173], v[218:221], v[12:15]
	s_setprio 0
	s_setprio 1
	v_mfma_f32_16x16x32_bf16 v[56:59], v[174:177], v[190:193], v[56:59]
	v_mfma_f32_16x16x32_bf16 v[56:59], v[178:181], v[194:197], v[56:59]
	v_mfma_f32_16x16x32_bf16 v[52:55], v[182:185], v[190:193], v[52:55]
	v_mfma_f32_16x16x32_bf16 v[52:55], v[186:189], v[194:197], v[52:55]
	v_mfma_f32_16x16x32_bf16 v[40:43], v[174:177], v[198:201], v[40:43]
	v_mfma_f32_16x16x32_bf16 v[40:43], v[178:181], v[202:205], v[40:43]
	v_mfma_f32_16x16x32_bf16 v[36:39], v[182:185], v[198:201], v[36:39]
	v_mfma_f32_16x16x32_bf16 v[36:39], v[186:189], v[202:205], v[36:39]
	v_mfma_f32_16x16x32_bf16 v[24:27], v[174:177], v[206:209], v[24:27]
	v_mfma_f32_16x16x32_bf16 v[24:27], v[178:181], v[210:213], v[24:27]
	v_mfma_f32_16x16x32_bf16 v[20:23], v[182:185], v[206:209], v[20:23]
	v_mfma_f32_16x16x32_bf16 v[20:23], v[186:189], v[210:213], v[20:23]
	v_mfma_f32_16x16x32_bf16 v[8:11], v[174:177], v[214:217], v[8:11]
	v_mfma_f32_16x16x32_bf16 v[8:11], v[178:181], v[218:221], v[8:11]
	v_mfma_f32_16x16x32_bf16 v[4:7], v[182:185], v[214:217], v[4:7]
	v_mfma_f32_16x16x32_bf16 v[4:7], v[186:189], v[218:221], v[4:7]
	s_setprio 0
	s_barrier
	s_add_i32 s0, 0, 0x18000
	v_add_u32_e32 v161, s0, v133
	s_add_i32 s73, 0, 0x1c000
	ds_read_b128 v[150:153], v161
	ds_read_b128 v[162:165], v161 offset:1024
	ds_read_b128 v[166:169], v161 offset:2048
	ds_read_b128 v[170:173], v161 offset:3072
	v_add_u32_e32 v161, s73, v133
	ds_read_b128 v[174:177], v161
	ds_read_b128 v[178:181], v161 offset:1024
	ds_read_b128 v[182:185], v161 offset:2048
	ds_read_b128 v[186:189], v161 offset:3072
	s_add_u32 s98, s54, 0x100000
	s_addc_u32 s99, s55, 0
	s_mov_b32 m0, s49
	ds_read_b128 v[190:193], v158 offset:32768
	ds_read_b128 v[194:197], v158 offset:33792
	ds_read_b128 v[198:201], v158 offset:34816
	ds_read_b128 v[202:205], v158 offset:35840
	ds_read_b128 v[206:209], v158 offset:36864
	ds_read_b128 v[210:213], v158 offset:37888
	ds_read_b128 v[214:217], v158 offset:38912
	ds_read_b128 v[218:221], v158 offset:39936
	global_load_lds_dwordx4 v134, s[98:99]
	s_mov_b32 m0, s56
	s_nop 0
	global_load_lds_dwordx4 v138, s[98:99]
	s_waitcnt vmcnt(8)
	s_waitcnt lgkmcnt(0)
	s_setprio 1
	s_barrier
	v_mfma_f32_16x16x32_bf16 v[128:131], v[150:153], v[190:193], v[128:131]
	v_mfma_f32_16x16x32_bf16 v[128:131], v[162:165], v[194:197], v[128:131]
	v_mfma_f32_16x16x32_bf16 v[124:127], v[166:169], v[190:193], v[124:127]
	v_mfma_f32_16x16x32_bf16 v[124:127], v[170:173], v[194:197], v[124:127]
	v_mfma_f32_16x16x32_bf16 v[112:115], v[150:153], v[198:201], v[112:115]
	v_mfma_f32_16x16x32_bf16 v[112:115], v[162:165], v[202:205], v[112:115]
	v_mfma_f32_16x16x32_bf16 v[108:111], v[166:169], v[198:201], v[108:111]
	v_mfma_f32_16x16x32_bf16 v[108:111], v[170:173], v[202:205], v[108:111]
	v_mfma_f32_16x16x32_bf16 v[96:99], v[150:153], v[206:209], v[96:99]
	v_mfma_f32_16x16x32_bf16 v[96:99], v[162:165], v[210:213], v[96:99]
	v_mfma_f32_16x16x32_bf16 v[92:95], v[166:169], v[206:209], v[92:95]
	v_mfma_f32_16x16x32_bf16 v[92:95], v[170:173], v[210:213], v[92:95]
	v_mfma_f32_16x16x32_bf16 v[80:83], v[150:153], v[214:217], v[80:83]
	v_mfma_f32_16x16x32_bf16 v[80:83], v[162:165], v[218:221], v[80:83]
	v_mfma_f32_16x16x32_bf16 v[76:79], v[166:169], v[214:217], v[76:79]
	v_mfma_f32_16x16x32_bf16 v[76:79], v[170:173], v[218:221], v[76:79]
	s_setprio 0
	s_setprio 1
	v_mfma_f32_16x16x32_bf16 v[120:123], v[174:177], v[190:193], v[120:123]
	v_mfma_f32_16x16x32_bf16 v[120:123], v[178:181], v[194:197], v[120:123]
	v_mfma_f32_16x16x32_bf16 v[116:119], v[182:185], v[190:193], v[116:119]
	v_mfma_f32_16x16x32_bf16 v[116:119], v[186:189], v[194:197], v[116:119]
	v_mfma_f32_16x16x32_bf16 v[104:107], v[174:177], v[198:201], v[104:107]
	v_mfma_f32_16x16x32_bf16 v[104:107], v[178:181], v[202:205], v[104:107]
	v_mfma_f32_16x16x32_bf16 v[100:103], v[182:185], v[198:201], v[100:103]
	v_mfma_f32_16x16x32_bf16 v[100:103], v[186:189], v[202:205], v[100:103]
	v_mfma_f32_16x16x32_bf16 v[88:91], v[174:177], v[206:209], v[88:91]
	v_mfma_f32_16x16x32_bf16 v[88:91], v[178:181], v[210:213], v[88:91]
	v_mfma_f32_16x16x32_bf16 v[84:87], v[182:185], v[206:209], v[84:87]
	v_mfma_f32_16x16x32_bf16 v[84:87], v[186:189], v[210:213], v[84:87]
	v_mfma_f32_16x16x32_bf16 v[72:75], v[174:177], v[214:217], v[72:75]
	v_mfma_f32_16x16x32_bf16 v[72:75], v[178:181], v[218:221], v[72:75]
	v_mfma_f32_16x16x32_bf16 v[68:71], v[182:185], v[214:217], v[68:71]
	v_mfma_f32_16x16x32_bf16 v[68:71], v[186:189], v[218:221], v[68:71]
	s_setprio 0
	s_barrier
	s_add_i32 s0, s0, s41
	s_add_i32 m0, s0, 0xffffff80
	ds_read_b128 v[190:193], v158 offset:49152
	ds_read_b128 v[194:197], v158 offset:50176
	ds_read_b128 v[198:201], v158 offset:51200
	ds_read_b128 v[202:205], v158 offset:52224
	ds_read_b128 v[206:209], v158 offset:53248
	ds_read_b128 v[210:213], v158 offset:54272
	ds_read_b128 v[214:217], v158 offset:55296
	ds_read_b128 v[218:221], v158 offset:56320
	global_load_lds_dwordx4 v136, s[52:53] offset:128
	s_add_i32 m0, s0, 0x1f80
	s_add_i32 s0, s73, s41
	global_load_lds_dwordx4 v140, s[52:53] offset:128
	s_add_u32 s52, s52, 0x100080
	s_addc_u32 s53, s53, 0
	s_mov_b32 m0, s0
	s_nop 0
	global_load_lds_dwordx4 v136, s[52:53]
	s_add_i32 m0, s0, 0x2000
	s_nop 0
	global_load_lds_dwordx4 v140, s[52:53]
	s_add_i32 m0, s59, 0xffffff80
	s_nop 0
	global_load_lds_dwordx4 v134, s[54:55] offset:128
	s_add_i32 m0, s60, 0xffffff80
	s_nop 0
	global_load_lds_dwordx4 v138, s[54:55] offset:128
	s_waitcnt vmcnt(8)
	s_waitcnt lgkmcnt(0)
	s_setprio 1
	s_barrier
	v_mfma_f32_16x16x32_bf16 v[64:67], v[150:153], v[190:193], v[64:67]
	v_mfma_f32_16x16x32_bf16 v[64:67], v[162:165], v[194:197], v[64:67]
	v_mfma_f32_16x16x32_bf16 v[60:63], v[166:169], v[190:193], v[60:63]
	v_mfma_f32_16x16x32_bf16 v[60:63], v[170:173], v[194:197], v[60:63]
	v_mfma_f32_16x16x32_bf16 v[48:51], v[150:153], v[198:201], v[48:51]
	v_mfma_f32_16x16x32_bf16 v[48:51], v[162:165], v[202:205], v[48:51]
	v_mfma_f32_16x16x32_bf16 v[44:47], v[166:169], v[198:201], v[44:47]
	v_mfma_f32_16x16x32_bf16 v[44:47], v[170:173], v[202:205], v[44:47]
	v_mfma_f32_16x16x32_bf16 v[32:35], v[150:153], v[206:209], v[32:35]
	v_mfma_f32_16x16x32_bf16 v[32:35], v[162:165], v[210:213], v[32:35]
	v_mfma_f32_16x16x32_bf16 v[28:31], v[166:169], v[206:209], v[28:31]
	v_mfma_f32_16x16x32_bf16 v[28:31], v[170:173], v[210:213], v[28:31]
	v_mfma_f32_16x16x32_bf16 v[16:19], v[150:153], v[214:217], v[16:19]
	v_mfma_f32_16x16x32_bf16 v[16:19], v[162:165], v[218:221], v[16:19]
	v_mfma_f32_16x16x32_bf16 v[12:15], v[166:169], v[214:217], v[12:15]
	v_mfma_f32_16x16x32_bf16 v[12:15], v[170:173], v[218:221], v[12:15]
	s_setprio 0
	s_setprio 1
	v_mfma_f32_16x16x32_bf16 v[56:59], v[174:177], v[190:193], v[56:59]
	v_mfma_f32_16x16x32_bf16 v[56:59], v[178:181], v[194:197], v[56:59]
	v_mfma_f32_16x16x32_bf16 v[52:55], v[182:185], v[190:193], v[52:55]
	v_mfma_f32_16x16x32_bf16 v[52:55], v[186:189], v[194:197], v[52:55]
	v_mfma_f32_16x16x32_bf16 v[40:43], v[174:177], v[198:201], v[40:43]
	v_mfma_f32_16x16x32_bf16 v[40:43], v[178:181], v[202:205], v[40:43]
	v_mfma_f32_16x16x32_bf16 v[36:39], v[182:185], v[198:201], v[36:39]
	v_mfma_f32_16x16x32_bf16 v[36:39], v[186:189], v[202:205], v[36:39]
	v_mfma_f32_16x16x32_bf16 v[24:27], v[174:177], v[206:209], v[24:27]
	v_mfma_f32_16x16x32_bf16 v[24:27], v[178:181], v[210:213], v[24:27]
	v_mfma_f32_16x16x32_bf16 v[20:23], v[182:185], v[206:209], v[20:23]
	v_mfma_f32_16x16x32_bf16 v[20:23], v[186:189], v[210:213], v[20:23]
	v_mfma_f32_16x16x32_bf16 v[8:11], v[174:177], v[214:217], v[8:11]
	v_mfma_f32_16x16x32_bf16 v[8:11], v[178:181], v[218:221], v[8:11]
	v_mfma_f32_16x16x32_bf16 v[4:7], v[182:185], v[214:217], v[4:7]
	v_mfma_f32_16x16x32_bf16 v[4:7], v[186:189], v[218:221], v[4:7]
	s_setprio 0
	s_barrier
	s_add_i32 s72, s72, 2
	s_add_u32 s50, s50, 0x100
	s_addc_u32 s51, s51, 0
	s_add_u32 s70, s70, 0x100
	s_addc_u32 s71, s71, 0
	s_cmp_gt_u32 s72, 61
	s_cbranch_scc0 .LBB0_429
	s_and_b64 vcc, exec, s[22:23]
	s_cbranch_vccz .LBB0_432
	s_barrier

.LBB0_1032:
	v_add_u32_e32 v5, s60, v3
	ds_read_b128 v[140:143], v5
	ds_read_b128 v[144:147], v5 offset:1024
	ds_read_b128 v[148:151], v5 offset:2048
	ds_read_b128 v[152:155], v5 offset:3072
	v_add_u32_e32 v5, s61, v3
	ds_read_b128 v[156:159], v5
	ds_read_b128 v[160:163], v5 offset:1024
	ds_read_b128 v[164:167], v5 offset:2048
	ds_read_b128 v[168:171], v5 offset:3072
	s_add_u32 s42, s40, 0xfff80080
	s_addc_u32 s43, s41, -1
	s_cmp_eq_u32 s67, 28
	s_cselect_b32 s51, s5, s43
	s_cselect_b32 s50, s7, s42
	s_cselect_b32 s43, s25, s66
	s_cselect_b32 s42, s27, s65
	s_add_i32 m0, s47, 0xc000
	ds_read_b128 v[172:175], v246
	ds_read_b128 v[176:179], v246 offset:1024
	ds_read_b128 v[180:183], v246 offset:2048
	ds_read_b128 v[184:187], v246 offset:3072
	ds_read_b128 v[188:191], v246 offset:4096
	ds_read_b128 v[192:195], v246 offset:5120
	ds_read_b128 v[196:199], v246 offset:6144
	ds_read_b128 v[200:203], v246 offset:7168
	global_load_lds_dwordx4 v216, s[40:41]
	s_add_i32 m0, s47, 0xe000
	s_nop 0
	global_load_lds_dwordx4 v218, s[40:41]
	s_waitcnt vmcnt(8)
	s_waitcnt lgkmcnt(0)
	s_setprio 1
	s_barrier
	v_mfma_f32_16x16x32_bf16 v[136:139], v[140:143], v[172:175], v[136:139]
	v_mfma_f32_16x16x32_bf16 v[136:139], v[144:147], v[176:179], v[136:139]
	v_mfma_f32_16x16x32_bf16 v[132:135], v[148:151], v[172:175], v[132:135]
	v_mfma_f32_16x16x32_bf16 v[132:135], v[152:155], v[176:179], v[132:135]
	v_mfma_f32_16x16x32_bf16 v[128:131], v[140:143], v[180:183], v[128:131]
	v_mfma_f32_16x16x32_bf16 v[128:131], v[144:147], v[184:187], v[128:131]
	v_mfma_f32_16x16x32_bf16 v[124:127], v[148:151], v[180:183], v[124:127]
	v_mfma_f32_16x16x32_bf16 v[124:127], v[152:155], v[184:187], v[124:127]
	v_mfma_f32_16x16x32_bf16 v[120:123], v[140:143], v[188:191], v[120:123]
	v_mfma_f32_16x16x32_bf16 v[120:123], v[144:147], v[192:195], v[120:123]
	v_mfma_f32_16x16x32_bf16 v[116:119], v[148:151], v[188:191], v[116:119]
	v_mfma_f32_16x16x32_bf16 v[116:119], v[152:155], v[192:195], v[116:119]
	v_mfma_f32_16x16x32_bf16 v[112:115], v[140:143], v[196:199], v[112:115]
	v_mfma_f32_16x16x32_bf16 v[112:115], v[144:147], v[200:203], v[112:115]
	v_mfma_f32_16x16x32_bf16 v[108:111], v[148:151], v[196:199], v[108:111]
	v_mfma_f32_16x16x32_bf16 v[108:111], v[152:155], v[200:203], v[108:111]
	s_setprio 0
	s_setprio 1
	v_mfma_f32_16x16x32_bf16 v[104:107], v[156:159], v[172:175], v[104:107]
	v_mfma_f32_16x16x32_bf16 v[104:107], v[160:163], v[176:179], v[104:107]
	v_mfma_f32_16x16x32_bf16 v[100:103], v[164:167], v[172:175], v[100:103]
	v_mfma_f32_16x16x32_bf16 v[100:103], v[168:171], v[176:179], v[100:103]
	v_mfma_f32_16x16x32_bf16 v[96:99], v[156:159], v[180:183], v[96:99]
	v_mfma_f32_16x16x32_bf16 v[96:99], v[160:163], v[184:187], v[96:99]
	v_mfma_f32_16x16x32_bf16 v[92:95], v[164:167], v[180:183], v[92:95]
	v_mfma_f32_16x16x32_bf16 v[92:95], v[168:171], v[184:187], v[92:95]
	v_mfma_f32_16x16x32_bf16 v[88:91], v[156:159], v[188:191], v[88:91]
	v_mfma_f32_16x16x32_bf16 v[88:91], v[160:163], v[192:195], v[88:91]
	v_mfma_f32_16x16x32_bf16 v[84:87], v[164:167], v[188:191], v[84:87]
	v_mfma_f32_16x16x32_bf16 v[84:87], v[168:171], v[192:195], v[84:87]
	v_mfma_f32_16x16x32_bf16 v[80:83], v[156:159], v[196:199], v[80:83]
	v_mfma_f32_16x16x32_bf16 v[80:83], v[160:163], v[200:203], v[80:83]
	v_mfma_f32_16x16x32_bf16 v[76:79], v[164:167], v[196:199], v[76:79]
	v_mfma_f32_16x16x32_bf16 v[76:79], v[168:171], v[200:203], v[76:79]
	s_setprio 0
	s_barrier
	s_add_i32 s68, s60, s46
	s_mov_b32 m0, s68
	ds_read_b128 v[172:175], v246 offset:16384
	ds_read_b128 v[176:179], v246 offset:17408
	ds_read_b128 v[180:183], v246 offset:18432
	ds_read_b128 v[184:187], v246 offset:19456
	ds_read_b128 v[188:191], v246 offset:20480
	ds_read_b128 v[192:195], v246 offset:21504
	ds_read_b128 v[196:199], v246 offset:22528
	ds_read_b128 v[200:203], v246 offset:23552
	global_load_lds_dwordx4 v210, s[42:43]
	s_add_i32 m0, s68, 0x2000
	s_add_u32 s70, s42, 0x80000
	s_addc_u32 s71, s43, 0
	s_add_i32 s68, s61, s46
	global_load_lds_dwordx4 v214, s[42:43]
	s_mov_b32 m0, s68
	s_nop 0
	global_load_lds_dwordx4 v210, s[70:71]
	s_add_i32 m0, s68, 0x2000
	s_nop 0
	global_load_lds_dwordx4 v214, s[70:71]
	s_mov_b32 m0, s47
	s_nop 0
	global_load_lds_dwordx4 v208, s[50:51]
	s_mov_b32 m0, s48
	s_nop 0
	global_load_lds_dwordx4 v212, s[50:51]
	s_waitcnt vmcnt(8)
	s_waitcnt lgkmcnt(0)
	s_setprio 1
	s_barrier
	v_mfma_f32_16x16x32_bf16 v[72:75], v[140:143], v[172:175], v[72:75]
	v_mfma_f32_16x16x32_bf16 v[72:75], v[144:147], v[176:179], v[72:75]
	v_mfma_f32_16x16x32_bf16 v[68:71], v[148:151], v[172:175], v[68:71]
	v_mfma_f32_16x16x32_bf16 v[68:71], v[152:155], v[176:179], v[68:71]
	v_mfma_f32_16x16x32_bf16 v[64:67], v[140:143], v[180:183], v[64:67]
	v_mfma_f32_16x16x32_bf16 v[64:67], v[144:147], v[184:187], v[64:67]
	v_mfma_f32_16x16x32_bf16 v[60:63], v[148:151], v[180:183], v[60:63]
	v_mfma_f32_16x16x32_bf16 v[60:63], v[152:155], v[184:187], v[60:63]
	v_mfma_f32_16x16x32_bf16 v[56:59], v[140:143], v[188:191], v[56:59]
	v_mfma_f32_16x16x32_bf16 v[56:59], v[144:147], v[192:195], v[56:59]
	v_mfma_f32_16x16x32_bf16 v[52:55], v[148:151], v[188:191], v[52:55]
	v_mfma_f32_16x16x32_bf16 v[52:55], v[152:155], v[192:195], v[52:55]
	v_mfma_f32_16x16x32_bf16 v[48:51], v[140:143], v[196:199], v[48:51]
	v_mfma_f32_16x16x32_bf16 v[48:51], v[144:147], v[200:203], v[48:51]
	v_mfma_f32_16x16x32_bf16 v[44:47], v[148:151], v[196:199], v[44:47]
	v_mfma_f32_16x16x32_bf16 v[44:47], v[152:155], v[200:203], v[44:47]
	s_setprio 0
	s_setprio 1
	v_mfma_f32_16x16x32_bf16 v[40:43], v[156:159], v[172:175], v[40:43]
	v_mfma_f32_16x16x32_bf16 v[40:43], v[160:163], v[176:179], v[40:43]
	v_mfma_f32_16x16x32_bf16 v[36:39], v[164:167], v[172:175], v[36:39]
	v_mfma_f32_16x16x32_bf16 v[36:39], v[168:171], v[176:179], v[36:39]
	v_mfma_f32_16x16x32_bf16 v[32:35], v[156:159], v[180:183], v[32:35]
	v_mfma_f32_16x16x32_bf16 v[32:35], v[160:163], v[184:187], v[32:35]
	v_mfma_f32_16x16x32_bf16 v[28:31], v[164:167], v[180:183], v[28:31]
	v_mfma_f32_16x16x32_bf16 v[28:31], v[168:171], v[184:187], v[28:31]
	v_mfma_f32_16x16x32_bf16 v[24:27], v[156:159], v[188:191], v[24:27]
	v_mfma_f32_16x16x32_bf16 v[24:27], v[160:163], v[192:195], v[24:27]
	v_mfma_f32_16x16x32_bf16 v[20:23], v[164:167], v[188:191], v[20:23]
	v_mfma_f32_16x16x32_bf16 v[20:23], v[168:171], v[192:195], v[20:23]
	v_mfma_f32_16x16x32_bf16 v[16:19], v[156:159], v[196:199], v[16:19]
	v_mfma_f32_16x16x32_bf16 v[16:19], v[160:163], v[200:203], v[16:19]
	v_mfma_f32_16x16x32_bf16 v[12:15], v[164:167], v[196:199], v[12:15]
	v_mfma_f32_16x16x32_bf16 v[12:15], v[168:171], v[200:203], v[12:15]
	s_setprio 0
	s_barrier
	s_add_i32 s68, 0, 0x18000
	v_add_u32_e32 v5, s68, v3
	s_add_i32 s70, 0, 0x1c000
	ds_read_b128 v[140:143], v5
	ds_read_b128 v[144:147], v5 offset:1024
	ds_read_b128 v[148:151], v5 offset:2048
	ds_read_b128 v[152:155], v5 offset:3072
	v_add_u32_e32 v5, s70, v3
	ds_read_b128 v[156:159], v5
	ds_read_b128 v[160:163], v5 offset:1024
	ds_read_b128 v[164:167], v5 offset:2048
	ds_read_b128 v[168:171], v5 offset:3072
	s_add_u32 s98, s50, 0x80000
	s_addc_u32 s99, s51, 0
	s_mov_b64 s[100:101], s[50:51]
	s_mov_b32 m0, s49
	ds_read_b128 v[172:175], v246 offset:32768
	ds_read_b128 v[176:179], v246 offset:33792
	ds_read_b128 v[180:183], v246 offset:34816
	ds_read_b128 v[184:187], v246 offset:35840
	ds_read_b128 v[188:191], v246 offset:36864
	ds_read_b128 v[192:195], v246 offset:37888
	ds_read_b128 v[196:199], v246 offset:38912
	ds_read_b128 v[200:203], v246 offset:39936
	global_load_lds_dwordx4 v208, s[98:99]
	s_mov_b32 m0, s52
	s_nop 0
	global_load_lds_dwordx4 v212, s[98:99]
	s_waitcnt vmcnt(8)
	s_waitcnt lgkmcnt(0)
	s_setprio 1
	s_barrier
	v_mfma_f32_16x16x32_bf16 v[136:139], v[140:143], v[172:175], v[136:139]
	v_mfma_f32_16x16x32_bf16 v[136:139], v[144:147], v[176:179], v[136:139]
	v_mfma_f32_16x16x32_bf16 v[132:135], v[148:151], v[172:175], v[132:135]
	v_mfma_f32_16x16x32_bf16 v[132:135], v[152:155], v[176:179], v[132:135]
	v_mfma_f32_16x16x32_bf16 v[128:131], v[140:143], v[180:183], v[128:131]
	v_mfma_f32_16x16x32_bf16 v[128:131], v[144:147], v[184:187], v[128:131]
	v_mfma_f32_16x16x32_bf16 v[124:127], v[148:151], v[180:183], v[124:127]
	v_mfma_f32_16x16x32_bf16 v[124:127], v[152:155], v[184:187], v[124:127]
	v_mfma_f32_16x16x32_bf16 v[120:123], v[140:143], v[188:191], v[120:123]
	v_mfma_f32_16x16x32_bf16 v[120:123], v[144:147], v[192:195], v[120:123]
	v_mfma_f32_16x16x32_bf16 v[116:119], v[148:151], v[188:191], v[116:119]
	v_mfma_f32_16x16x32_bf16 v[116:119], v[152:155], v[192:195], v[116:119]
	v_mfma_f32_16x16x32_bf16 v[112:115], v[140:143], v[196:199], v[112:115]
	v_mfma_f32_16x16x32_bf16 v[112:115], v[144:147], v[200:203], v[112:115]
	v_mfma_f32_16x16x32_bf16 v[108:111], v[148:151], v[196:199], v[108:111]
	v_mfma_f32_16x16x32_bf16 v[108:111], v[152:155], v[200:203], v[108:111]
	s_setprio 0
	s_setprio 1
	v_mfma_f32_16x16x32_bf16 v[104:107], v[156:159], v[172:175], v[104:107]
	v_mfma_f32_16x16x32_bf16 v[104:107], v[160:163], v[176:179], v[104:107]
	v_mfma_f32_16x16x32_bf16 v[100:103], v[164:167], v[172:175], v[100:103]
	v_mfma_f32_16x16x32_bf16 v[100:103], v[168:171], v[176:179], v[100:103]
	v_mfma_f32_16x16x32_bf16 v[96:99], v[156:159], v[180:183], v[96:99]
	v_mfma_f32_16x16x32_bf16 v[96:99], v[160:163], v[184:187], v[96:99]
	v_mfma_f32_16x16x32_bf16 v[92:95], v[164:167], v[180:183], v[92:95]
	v_mfma_f32_16x16x32_bf16 v[92:95], v[168:171], v[184:187], v[92:95]
	v_mfma_f32_16x16x32_bf16 v[88:91], v[156:159], v[188:191], v[88:91]
	v_mfma_f32_16x16x32_bf16 v[88:91], v[160:163], v[192:195], v[88:91]
	v_mfma_f32_16x16x32_bf16 v[84:87], v[164:167], v[188:191], v[84:87]
	v_mfma_f32_16x16x32_bf16 v[84:87], v[168:171], v[192:195], v[84:87]
	v_mfma_f32_16x16x32_bf16 v[80:83], v[156:159], v[196:199], v[80:83]
	v_mfma_f32_16x16x32_bf16 v[80:83], v[160:163], v[200:203], v[80:83]
	v_mfma_f32_16x16x32_bf16 v[76:79], v[164:167], v[196:199], v[76:79]
	v_mfma_f32_16x16x32_bf16 v[76:79], v[168:171], v[200:203], v[76:79]
	s_setprio 0
	s_barrier
	s_add_i32 s50, s68, s46
	s_add_i32 m0, s50, 0xffffff80
	ds_read_b128 v[172:175], v246 offset:49152
	ds_read_b128 v[176:179], v246 offset:50176
	ds_read_b128 v[180:183], v246 offset:51200
	ds_read_b128 v[184:187], v246 offset:52224
	ds_read_b128 v[188:191], v246 offset:53248
	ds_read_b128 v[192:195], v246 offset:54272
	ds_read_b128 v[196:199], v246 offset:55296
	ds_read_b128 v[200:203], v246 offset:56320
	global_load_lds_dwordx4 v210, s[42:43] offset:128
	s_add_i32 m0, s50, 0x1f80
	s_add_i32 s50, s70, s46
	global_load_lds_dwordx4 v214, s[42:43] offset:128
	s_add_u32 s42, s42, 0x80080
	s_addc_u32 s43, s43, 0
	s_mov_b32 m0, s50
	s_nop 0
	global_load_lds_dwordx4 v210, s[42:43]
	s_add_i32 m0, s50, 0x2000
	s_nop 0
	global_load_lds_dwordx4 v214, s[42:43]
	s_add_i32 m0, s58, 0xffffff80
	s_nop 0
	global_load_lds_dwordx4 v208, s[100:101] offset:128
	s_add_i32 m0, s59, 0xffffff80
	s_nop 0
	global_load_lds_dwordx4 v212, s[100:101] offset:128
	s_waitcnt vmcnt(8)
	s_waitcnt lgkmcnt(0)
	s_setprio 1
	s_barrier
	v_mfma_f32_16x16x32_bf16 v[72:75], v[140:143], v[172:175], v[72:75]
	v_mfma_f32_16x16x32_bf16 v[72:75], v[144:147], v[176:179], v[72:75]
	v_mfma_f32_16x16x32_bf16 v[68:71], v[148:151], v[172:175], v[68:71]
	v_mfma_f32_16x16x32_bf16 v[68:71], v[152:155], v[176:179], v[68:71]
	v_mfma_f32_16x16x32_bf16 v[64:67], v[140:143], v[180:183], v[64:67]
	v_mfma_f32_16x16x32_bf16 v[64:67], v[144:147], v[184:187], v[64:67]
	v_mfma_f32_16x16x32_bf16 v[60:63], v[148:151], v[180:183], v[60:63]
	v_mfma_f32_16x16x32_bf16 v[60:63], v[152:155], v[184:187], v[60:63]
	v_mfma_f32_16x16x32_bf16 v[56:59], v[140:143], v[188:191], v[56:59]
	v_mfma_f32_16x16x32_bf16 v[56:59], v[144:147], v[192:195], v[56:59]
	v_mfma_f32_16x16x32_bf16 v[52:55], v[148:151], v[188:191], v[52:55]
	v_mfma_f32_16x16x32_bf16 v[52:55], v[152:155], v[192:195], v[52:55]
	v_mfma_f32_16x16x32_bf16 v[48:51], v[140:143], v[196:199], v[48:51]
	v_mfma_f32_16x16x32_bf16 v[48:51], v[144:147], v[200:203], v[48:51]
	v_mfma_f32_16x16x32_bf16 v[44:47], v[148:151], v[196:199], v[44:47]
	v_mfma_f32_16x16x32_bf16 v[44:47], v[152:155], v[200:203], v[44:47]
	s_setprio 0
	s_setprio 1
	v_mfma_f32_16x16x32_bf16 v[40:43], v[156:159], v[172:175], v[40:43]
	v_mfma_f32_16x16x32_bf16 v[40:43], v[160:163], v[176:179], v[40:43]
	v_mfma_f32_16x16x32_bf16 v[36:39], v[164:167], v[172:175], v[36:39]
	v_mfma_f32_16x16x32_bf16 v[36:39], v[168:171], v[176:179], v[36:39]
	v_mfma_f32_16x16x32_bf16 v[32:35], v[156:159], v[180:183], v[32:35]
	v_mfma_f32_16x16x32_bf16 v[32:35], v[160:163], v[184:187], v[32:35]
	v_mfma_f32_16x16x32_bf16 v[28:31], v[164:167], v[180:183], v[28:31]
	v_mfma_f32_16x16x32_bf16 v[28:31], v[168:171], v[184:187], v[28:31]
	v_mfma_f32_16x16x32_bf16 v[24:27], v[156:159], v[188:191], v[24:27]
	v_mfma_f32_16x16x32_bf16 v[24:27], v[160:163], v[192:195], v[24:27]
	v_mfma_f32_16x16x32_bf16 v[20:23], v[164:167], v[188:191], v[20:23]
	v_mfma_f32_16x16x32_bf16 v[20:23], v[168:171], v[192:195], v[20:23]
	v_mfma_f32_16x16x32_bf16 v[16:19], v[156:159], v[196:199], v[16:19]
	v_mfma_f32_16x16x32_bf16 v[16:19], v[160:163], v[200:203], v[16:19]
	v_mfma_f32_16x16x32_bf16 v[12:15], v[164:167], v[196:199], v[12:15]
	v_mfma_f32_16x16x32_bf16 v[12:15], v[168:171], v[200:203], v[12:15]
	s_setprio 0
	s_barrier
	s_add_i32 s67, s67, 2
	s_add_u32 s40, s40, 0x100
	s_addc_u32 s41, s41, 0
	s_add_u32 s65, s65, 0x100
	s_addc_u32 s66, s66, 0
	s_cmp_gt_u32 s67, 29
	s_cbranch_scc0 .LBB0_1032
	s_and_b64 vcc, exec, s[22:23]
	s_cbranch_vccz .LBB0_1035
	s_barrier

.LBB0_1203:
	ds_read_b128 v[132:135], v187
	ds_read_b128 v[136:139], v187 offset:1024
	ds_read_b128 v[140:143], v187 offset:2048
	ds_read_b128 v[144:147], v187 offset:3072
	ds_read_b128 v[148:151], v188
	ds_read_b128 v[152:155], v188 offset:1024
	ds_read_b128 v[172:175], v188 offset:2048
	ds_read_b128 v[176:179], v188 offset:3072
	s_add_u32 s0, s42, 0xfff00080
	s_addc_u32 s50, s43, -1
	s_cmp_eq_u32 s65, 60
	s_cselect_b32 s53, s25, s50
	s_cselect_b32 s52, s31, s0
	s_cselect_b32 s51, s23, s64
	s_cselect_b32 s50, s62, s63
	s_add_i32 m0, s41, 0xc000
	ds_read_b128 v[180:183], v189
	ds_read_b128 v[192:195], v189 offset:1024
	ds_read_b128 v[196:199], v189 offset:2048
	ds_read_b128 v[200:203], v189 offset:3072
	ds_read_b128 v[204:207], v189 offset:4096
	ds_read_b128 v[208:211], v189 offset:5120
	ds_read_b128 v[212:215], v189 offset:6144
	ds_read_b128 v[216:219], v189 offset:7168
	global_load_lds_dwordx4 v164, s[42:43]
	s_add_i32 m0, s41, 0xe000
	s_nop 0
	global_load_lds_dwordx4 v166, s[42:43]
	s_waitcnt vmcnt(8)
	s_waitcnt lgkmcnt(0)
	s_setprio 1
	s_barrier
	v_mfma_f32_16x16x32_bf16 v[128:131], v[132:135], v[180:183], v[128:131]
	v_mfma_f32_16x16x32_bf16 v[128:131], v[136:139], v[192:195], v[128:131]
	v_mfma_f32_16x16x32_bf16 v[124:127], v[140:143], v[180:183], v[124:127]
	v_mfma_f32_16x16x32_bf16 v[124:127], v[144:147], v[192:195], v[124:127]
	v_mfma_f32_16x16x32_bf16 v[112:115], v[132:135], v[196:199], v[112:115]
	v_mfma_f32_16x16x32_bf16 v[112:115], v[136:139], v[200:203], v[112:115]
	v_mfma_f32_16x16x32_bf16 v[108:111], v[140:143], v[196:199], v[108:111]
	v_mfma_f32_16x16x32_bf16 v[108:111], v[144:147], v[200:203], v[108:111]
	v_mfma_f32_16x16x32_bf16 v[96:99], v[132:135], v[204:207], v[96:99]
	v_mfma_f32_16x16x32_bf16 v[96:99], v[136:139], v[208:211], v[96:99]
	v_mfma_f32_16x16x32_bf16 v[92:95], v[140:143], v[204:207], v[92:95]
	v_mfma_f32_16x16x32_bf16 v[92:95], v[144:147], v[208:211], v[92:95]
	v_mfma_f32_16x16x32_bf16 v[80:83], v[132:135], v[212:215], v[80:83]
	v_mfma_f32_16x16x32_bf16 v[80:83], v[136:139], v[216:219], v[80:83]
	v_mfma_f32_16x16x32_bf16 v[76:79], v[140:143], v[212:215], v[76:79]
	v_mfma_f32_16x16x32_bf16 v[76:79], v[144:147], v[216:219], v[76:79]
	s_setprio 0
	s_setprio 1
	v_mfma_f32_16x16x32_bf16 v[120:123], v[148:151], v[180:183], v[120:123]
	v_mfma_f32_16x16x32_bf16 v[120:123], v[152:155], v[192:195], v[120:123]
	v_mfma_f32_16x16x32_bf16 v[116:119], v[172:175], v[180:183], v[116:119]
	v_mfma_f32_16x16x32_bf16 v[116:119], v[176:179], v[192:195], v[116:119]
	v_mfma_f32_16x16x32_bf16 v[104:107], v[148:151], v[196:199], v[104:107]
	v_mfma_f32_16x16x32_bf16 v[104:107], v[152:155], v[200:203], v[104:107]
	v_mfma_f32_16x16x32_bf16 v[100:103], v[172:175], v[196:199], v[100:103]
	v_mfma_f32_16x16x32_bf16 v[100:103], v[176:179], v[200:203], v[100:103]
	v_mfma_f32_16x16x32_bf16 v[88:91], v[148:151], v[204:207], v[88:91]
	v_mfma_f32_16x16x32_bf16 v[88:91], v[152:155], v[208:211], v[88:91]
	v_mfma_f32_16x16x32_bf16 v[84:87], v[172:175], v[204:207], v[84:87]
	v_mfma_f32_16x16x32_bf16 v[84:87], v[176:179], v[208:211], v[84:87]
	v_mfma_f32_16x16x32_bf16 v[72:75], v[148:151], v[212:215], v[72:75]
	v_mfma_f32_16x16x32_bf16 v[72:75], v[152:155], v[216:219], v[72:75]
	v_mfma_f32_16x16x32_bf16 v[68:71], v[172:175], v[212:215], v[68:71]
	v_mfma_f32_16x16x32_bf16 v[68:71], v[176:179], v[216:219], v[68:71]
	s_setprio 0
	s_barrier
	s_add_i32 s0, s59, s46
	s_mov_b32 m0, s0
	ds_read_b128 v[180:183], v189 offset:16384
	ds_read_b128 v[192:195], v189 offset:17408
	ds_read_b128 v[196:199], v189 offset:18432
	ds_read_b128 v[200:203], v189 offset:19456
	ds_read_b128 v[204:207], v189 offset:20480
	ds_read_b128 v[208:211], v189 offset:21504
	ds_read_b128 v[212:215], v189 offset:22528
	ds_read_b128 v[216:219], v189 offset:23552
	global_load_lds_dwordx4 v158, s[50:51]
	s_add_i32 m0, s0, 0x2000
	s_add_u32 s66, s50, 0x100000
	s_addc_u32 s67, s51, 0
	s_add_i32 s0, s60, s46
	global_load_lds_dwordx4 v162, s[50:51]
	s_mov_b32 m0, s0
	s_nop 0
	global_load_lds_dwordx4 v158, s[66:67]
	s_add_i32 m0, s0, 0x2000
	s_nop 0
	global_load_lds_dwordx4 v162, s[66:67]
	s_mov_b32 m0, s41
	s_nop 0
	global_load_lds_dwordx4 v156, s[52:53]
	s_mov_b32 m0, s47
	s_nop 0
	global_load_lds_dwordx4 v160, s[52:53]
	s_waitcnt vmcnt(8)
	s_waitcnt lgkmcnt(0)
	s_setprio 1
	s_barrier
	v_mfma_f32_16x16x32_bf16 v[64:67], v[132:135], v[180:183], v[64:67]
	v_mfma_f32_16x16x32_bf16 v[64:67], v[136:139], v[192:195], v[64:67]
	v_mfma_f32_16x16x32_bf16 v[60:63], v[140:143], v[180:183], v[60:63]
	v_mfma_f32_16x16x32_bf16 v[60:63], v[144:147], v[192:195], v[60:63]
	v_mfma_f32_16x16x32_bf16 v[48:51], v[132:135], v[196:199], v[48:51]
	v_mfma_f32_16x16x32_bf16 v[48:51], v[136:139], v[200:203], v[48:51]
	v_mfma_f32_16x16x32_bf16 v[44:47], v[140:143], v[196:199], v[44:47]
	v_mfma_f32_16x16x32_bf16 v[44:47], v[144:147], v[200:203], v[44:47]
	v_mfma_f32_16x16x32_bf16 v[32:35], v[132:135], v[204:207], v[32:35]
	v_mfma_f32_16x16x32_bf16 v[32:35], v[136:139], v[208:211], v[32:35]
	v_mfma_f32_16x16x32_bf16 v[28:31], v[140:143], v[204:207], v[28:31]
	v_mfma_f32_16x16x32_bf16 v[28:31], v[144:147], v[208:211], v[28:31]
	v_mfma_f32_16x16x32_bf16 v[16:19], v[132:135], v[212:215], v[16:19]
	v_mfma_f32_16x16x32_bf16 v[16:19], v[136:139], v[216:219], v[16:19]
	v_mfma_f32_16x16x32_bf16 v[12:15], v[140:143], v[212:215], v[12:15]
	v_mfma_f32_16x16x32_bf16 v[12:15], v[144:147], v[216:219], v[12:15]
	s_setprio 0
	s_setprio 1
	v_mfma_f32_16x16x32_bf16 v[56:59], v[148:151], v[180:183], v[56:59]
	v_mfma_f32_16x16x32_bf16 v[56:59], v[152:155], v[192:195], v[56:59]
	v_mfma_f32_16x16x32_bf16 v[52:55], v[172:175], v[180:183], v[52:55]
	v_mfma_f32_16x16x32_bf16 v[52:55], v[176:179], v[192:195], v[52:55]
	v_mfma_f32_16x16x32_bf16 v[40:43], v[148:151], v[196:199], v[40:43]
	v_mfma_f32_16x16x32_bf16 v[40:43], v[152:155], v[200:203], v[40:43]
	v_mfma_f32_16x16x32_bf16 v[36:39], v[172:175], v[196:199], v[36:39]
	v_mfma_f32_16x16x32_bf16 v[36:39], v[176:179], v[200:203], v[36:39]
	v_mfma_f32_16x16x32_bf16 v[24:27], v[148:151], v[204:207], v[24:27]
	v_mfma_f32_16x16x32_bf16 v[24:27], v[152:155], v[208:211], v[24:27]
	v_mfma_f32_16x16x32_bf16 v[20:23], v[172:175], v[204:207], v[20:23]
	v_mfma_f32_16x16x32_bf16 v[20:23], v[176:179], v[208:211], v[20:23]
	v_mfma_f32_16x16x32_bf16 v[8:11], v[148:151], v[212:215], v[8:11]
	v_mfma_f32_16x16x32_bf16 v[8:11], v[152:155], v[216:219], v[8:11]
	v_mfma_f32_16x16x32_bf16 v[4:7], v[172:175], v[212:215], v[4:7]
	v_mfma_f32_16x16x32_bf16 v[4:7], v[176:179], v[216:219], v[4:7]
	s_setprio 0
	s_barrier
	s_add_i32 s0, 0, 0x18000
	s_add_i32 s66, 0, 0x1c000
	v_add_u32_e32 v144, s0, v3
	v_add_u32_e32 v176, s66, v3
	ds_read_b128 v[132:135], v144
	ds_read_b128 v[136:139], v144 offset:1024
	ds_read_b128 v[140:143], v144 offset:2048
	ds_read_b128 v[144:147], v144 offset:3072
	ds_read_b128 v[148:151], v176
	ds_read_b128 v[152:155], v176 offset:1024
	ds_read_b128 v[172:175], v176 offset:2048
	ds_read_b128 v[176:179], v176 offset:3072
	s_add_u32 s98, s52, 0x100000
	s_addc_u32 s99, s53, 0
	s_mov_b32 m0, s48
	ds_read_b128 v[180:183], v189 offset:32768
	ds_read_b128 v[192:195], v189 offset:33792
	ds_read_b128 v[196:199], v189 offset:34816
	ds_read_b128 v[200:203], v189 offset:35840
	ds_read_b128 v[204:207], v189 offset:36864
	ds_read_b128 v[208:211], v189 offset:37888
	ds_read_b128 v[212:215], v189 offset:38912
	ds_read_b128 v[216:219], v189 offset:39936
	global_load_lds_dwordx4 v156, s[98:99]
	s_mov_b32 m0, s49
	s_nop 0
	global_load_lds_dwordx4 v160, s[98:99]
	s_waitcnt vmcnt(8)
	s_waitcnt lgkmcnt(0)
	s_setprio 1
	s_barrier
	v_mfma_f32_16x16x32_bf16 v[128:131], v[132:135], v[180:183], v[128:131]
	v_mfma_f32_16x16x32_bf16 v[128:131], v[136:139], v[192:195], v[128:131]
	v_mfma_f32_16x16x32_bf16 v[124:127], v[140:143], v[180:183], v[124:127]
	v_mfma_f32_16x16x32_bf16 v[124:127], v[144:147], v[192:195], v[124:127]
	v_mfma_f32_16x16x32_bf16 v[112:115], v[132:135], v[196:199], v[112:115]
	v_mfma_f32_16x16x32_bf16 v[112:115], v[136:139], v[200:203], v[112:115]
	v_mfma_f32_16x16x32_bf16 v[108:111], v[140:143], v[196:199], v[108:111]
	v_mfma_f32_16x16x32_bf16 v[108:111], v[144:147], v[200:203], v[108:111]
	v_mfma_f32_16x16x32_bf16 v[96:99], v[132:135], v[204:207], v[96:99]
	v_mfma_f32_16x16x32_bf16 v[96:99], v[136:139], v[208:211], v[96:99]
	v_mfma_f32_16x16x32_bf16 v[92:95], v[140:143], v[204:207], v[92:95]
	v_mfma_f32_16x16x32_bf16 v[92:95], v[144:147], v[208:211], v[92:95]
	v_mfma_f32_16x16x32_bf16 v[80:83], v[132:135], v[212:215], v[80:83]
	v_mfma_f32_16x16x32_bf16 v[80:83], v[136:139], v[216:219], v[80:83]
	v_mfma_f32_16x16x32_bf16 v[76:79], v[140:143], v[212:215], v[76:79]
	v_mfma_f32_16x16x32_bf16 v[76:79], v[144:147], v[216:219], v[76:79]
	s_setprio 0
	s_setprio 1
	v_mfma_f32_16x16x32_bf16 v[120:123], v[148:151], v[180:183], v[120:123]
	v_mfma_f32_16x16x32_bf16 v[120:123], v[152:155], v[192:195], v[120:123]
	v_mfma_f32_16x16x32_bf16 v[116:119], v[172:175], v[180:183], v[116:119]
	v_mfma_f32_16x16x32_bf16 v[116:119], v[176:179], v[192:195], v[116:119]
	v_mfma_f32_16x16x32_bf16 v[104:107], v[148:151], v[196:199], v[104:107]
	v_mfma_f32_16x16x32_bf16 v[104:107], v[152:155], v[200:203], v[104:107]
	v_mfma_f32_16x16x32_bf16 v[100:103], v[172:175], v[196:199], v[100:103]
	v_mfma_f32_16x16x32_bf16 v[100:103], v[176:179], v[200:203], v[100:103]
	v_mfma_f32_16x16x32_bf16 v[88:91], v[148:151], v[204:207], v[88:91]
	v_mfma_f32_16x16x32_bf16 v[88:91], v[152:155], v[208:211], v[88:91]
	v_mfma_f32_16x16x32_bf16 v[84:87], v[172:175], v[204:207], v[84:87]
	v_mfma_f32_16x16x32_bf16 v[84:87], v[176:179], v[208:211], v[84:87]
	v_mfma_f32_16x16x32_bf16 v[72:75], v[148:151], v[212:215], v[72:75]
	v_mfma_f32_16x16x32_bf16 v[72:75], v[152:155], v[216:219], v[72:75]
	v_mfma_f32_16x16x32_bf16 v[68:71], v[172:175], v[212:215], v[68:71]
	v_mfma_f32_16x16x32_bf16 v[68:71], v[176:179], v[216:219], v[68:71]
	s_setprio 0
	s_barrier
	s_add_i32 s0, s0, s46
	s_add_i32 m0, s0, 0xffffff80
	ds_read_b128 v[180:183], v189 offset:49152
	ds_read_b128 v[192:195], v189 offset:50176
	ds_read_b128 v[196:199], v189 offset:51200
	ds_read_b128 v[200:203], v189 offset:52224
	ds_read_b128 v[204:207], v189 offset:53248
	ds_read_b128 v[208:211], v189 offset:54272
	ds_read_b128 v[212:215], v189 offset:55296
	ds_read_b128 v[216:219], v189 offset:56320
	global_load_lds_dwordx4 v158, s[50:51] offset:128
	s_add_i32 m0, s0, 0x1f80
	s_add_i32 s0, s66, s46
	global_load_lds_dwordx4 v162, s[50:51] offset:128
	s_add_u32 s50, s50, 0x100080
	s_addc_u32 s51, s51, 0
	s_mov_b32 m0, s0
	s_nop 0
	global_load_lds_dwordx4 v158, s[50:51]
	s_add_i32 m0, s0, 0x2000
	s_nop 0
	global_load_lds_dwordx4 v162, s[50:51]
	s_add_i32 m0, s57, 0xffffff80
	s_nop 0
	global_load_lds_dwordx4 v156, s[52:53] offset:128
	s_add_i32 m0, s58, 0xffffff80
	s_nop 0
	global_load_lds_dwordx4 v160, s[52:53] offset:128
	s_waitcnt vmcnt(8)
	s_waitcnt lgkmcnt(0)
	s_setprio 1
	s_barrier
	v_mfma_f32_16x16x32_bf16 v[64:67], v[132:135], v[180:183], v[64:67]
	v_mfma_f32_16x16x32_bf16 v[64:67], v[136:139], v[192:195], v[64:67]
	v_mfma_f32_16x16x32_bf16 v[60:63], v[140:143], v[180:183], v[60:63]
	v_mfma_f32_16x16x32_bf16 v[60:63], v[144:147], v[192:195], v[60:63]
	v_mfma_f32_16x16x32_bf16 v[48:51], v[132:135], v[196:199], v[48:51]
	v_mfma_f32_16x16x32_bf16 v[48:51], v[136:139], v[200:203], v[48:51]
	v_mfma_f32_16x16x32_bf16 v[44:47], v[140:143], v[196:199], v[44:47]
	v_mfma_f32_16x16x32_bf16 v[44:47], v[144:147], v[200:203], v[44:47]
	v_mfma_f32_16x16x32_bf16 v[32:35], v[132:135], v[204:207], v[32:35]
	v_mfma_f32_16x16x32_bf16 v[32:35], v[136:139], v[208:211], v[32:35]
	v_mfma_f32_16x16x32_bf16 v[28:31], v[140:143], v[204:207], v[28:31]
	v_mfma_f32_16x16x32_bf16 v[28:31], v[144:147], v[208:211], v[28:31]
	v_mfma_f32_16x16x32_bf16 v[16:19], v[132:135], v[212:215], v[16:19]
	v_mfma_f32_16x16x32_bf16 v[16:19], v[136:139], v[216:219], v[16:19]
	v_mfma_f32_16x16x32_bf16 v[12:15], v[140:143], v[212:215], v[12:15]
	v_mfma_f32_16x16x32_bf16 v[12:15], v[144:147], v[216:219], v[12:15]
	s_setprio 0
	s_setprio 1
	v_mfma_f32_16x16x32_bf16 v[56:59], v[148:151], v[180:183], v[56:59]
	v_mfma_f32_16x16x32_bf16 v[56:59], v[152:155], v[192:195], v[56:59]
	v_mfma_f32_16x16x32_bf16 v[52:55], v[172:175], v[180:183], v[52:55]
	v_mfma_f32_16x16x32_bf16 v[52:55], v[176:179], v[192:195], v[52:55]
	v_mfma_f32_16x16x32_bf16 v[40:43], v[148:151], v[196:199], v[40:43]
	v_mfma_f32_16x16x32_bf16 v[40:43], v[152:155], v[200:203], v[40:43]
	v_mfma_f32_16x16x32_bf16 v[36:39], v[172:175], v[196:199], v[36:39]
	v_mfma_f32_16x16x32_bf16 v[36:39], v[176:179], v[200:203], v[36:39]
	v_mfma_f32_16x16x32_bf16 v[24:27], v[148:151], v[204:207], v[24:27]
	v_mfma_f32_16x16x32_bf16 v[24:27], v[152:155], v[208:211], v[24:27]
	v_mfma_f32_16x16x32_bf16 v[20:23], v[172:175], v[204:207], v[20:23]
	v_mfma_f32_16x16x32_bf16 v[20:23], v[176:179], v[208:211], v[20:23]
	v_mfma_f32_16x16x32_bf16 v[8:11], v[148:151], v[212:215], v[8:11]
	v_mfma_f32_16x16x32_bf16 v[8:11], v[152:155], v[216:219], v[8:11]
	v_mfma_f32_16x16x32_bf16 v[4:7], v[172:175], v[212:215], v[4:7]
	v_mfma_f32_16x16x32_bf16 v[4:7], v[176:179], v[216:219], v[4:7]
	s_setprio 0
	s_barrier
	s_add_i32 s65, s65, 2
	s_add_u32 s42, s42, 0x100
	s_addc_u32 s43, s43, 0
	s_add_u32 s63, s63, 0x100
	s_addc_u32 s64, s64, 0
	s_cmp_gt_u32 s65, 61
	s_cbranch_scc0 .LBB0_1203
	s_and_b64 vcc, exec, s[20:21]
	s_cbranch_vccz .LBB0_1206
	s_barrier

.LBB0_1288:
	ds_read_b128 v[154:157], v150
	ds_read_b128 v[158:161], v150 offset:1024
	ds_read_b128 v[162:165], v150 offset:2048
	ds_read_b128 v[166:169], v150 offset:3072
	ds_read_b128 v[170:173], v151
	ds_read_b128 v[174:177], v151 offset:1024
	ds_read_b128 v[178:181], v151 offset:2048
	ds_read_b128 v[182:185], v151 offset:3072
	s_add_u32 s0, s42, 0xfff00080
	s_addc_u32 s50, s43, -1
	s_cmp_eq_u32 s70, 12
	s_cselect_b32 s53, s29, s50
	s_cselect_b32 s52, s28, s0
	s_cselect_b32 s51, s5, s41
	s_cselect_b32 s50, s4, s31
	s_add_i32 m0, s17, 0xc000
	ds_read_b128 v[186:189], v152
	ds_read_b128 v[190:193], v152 offset:1024
	ds_read_b128 v[194:197], v152 offset:2048
	ds_read_b128 v[198:201], v152 offset:3072
	ds_read_b128 v[202:205], v152 offset:4096
	ds_read_b128 v[206:209], v152 offset:5120
	ds_read_b128 v[210:213], v152 offset:6144
	ds_read_b128 v[214:217], v152 offset:7168
	global_load_lds_dwordx4 v142, s[42:43]
	s_add_i32 m0, s17, 0xe000
	s_nop 0
	global_load_lds_dwordx4 v144, s[42:43]
	s_waitcnt vmcnt(8)
	s_waitcnt lgkmcnt(0)
	s_setprio 1
	s_barrier
	v_mfma_f32_16x16x32_bf16 v[128:131], v[154:157], v[186:189], v[128:131]
	v_mfma_f32_16x16x32_bf16 v[128:131], v[158:161], v[190:193], v[128:131]
	v_mfma_f32_16x16x32_bf16 v[124:127], v[162:165], v[186:189], v[124:127]
	v_mfma_f32_16x16x32_bf16 v[124:127], v[166:169], v[190:193], v[124:127]
	v_mfma_f32_16x16x32_bf16 v[120:123], v[154:157], v[194:197], v[120:123]
	v_mfma_f32_16x16x32_bf16 v[120:123], v[158:161], v[198:201], v[120:123]
	v_mfma_f32_16x16x32_bf16 v[116:119], v[162:165], v[194:197], v[116:119]
	v_mfma_f32_16x16x32_bf16 v[116:119], v[166:169], v[198:201], v[116:119]
	v_mfma_f32_16x16x32_bf16 v[104:107], v[154:157], v[202:205], v[104:107]
	v_mfma_f32_16x16x32_bf16 v[104:107], v[158:161], v[206:209], v[104:107]
	v_mfma_f32_16x16x32_bf16 v[100:103], v[162:165], v[202:205], v[100:103]
	v_mfma_f32_16x16x32_bf16 v[100:103], v[166:169], v[206:209], v[100:103]
	v_mfma_f32_16x16x32_bf16 v[88:91], v[154:157], v[210:213], v[88:91]
	v_mfma_f32_16x16x32_bf16 v[88:91], v[158:161], v[214:217], v[88:91]
	v_mfma_f32_16x16x32_bf16 v[84:87], v[162:165], v[210:213], v[84:87]
	v_mfma_f32_16x16x32_bf16 v[84:87], v[166:169], v[214:217], v[84:87]
	s_setprio 0
	s_setprio 1
	v_mfma_f32_16x16x32_bf16 v[112:115], v[170:173], v[186:189], v[112:115]
	v_mfma_f32_16x16x32_bf16 v[112:115], v[174:177], v[190:193], v[112:115]
	v_mfma_f32_16x16x32_bf16 v[108:111], v[178:181], v[186:189], v[108:111]
	v_mfma_f32_16x16x32_bf16 v[108:111], v[182:185], v[190:193], v[108:111]
	v_mfma_f32_16x16x32_bf16 v[96:99], v[170:173], v[194:197], v[96:99]
	v_mfma_f32_16x16x32_bf16 v[96:99], v[174:177], v[198:201], v[96:99]
	v_mfma_f32_16x16x32_bf16 v[92:95], v[178:181], v[194:197], v[92:95]
	v_mfma_f32_16x16x32_bf16 v[92:95], v[182:185], v[198:201], v[92:95]
	v_mfma_f32_16x16x32_bf16 v[80:83], v[170:173], v[202:205], v[80:83]
	v_mfma_f32_16x16x32_bf16 v[80:83], v[174:177], v[206:209], v[80:83]
	v_mfma_f32_16x16x32_bf16 v[76:79], v[178:181], v[202:205], v[76:79]
	v_mfma_f32_16x16x32_bf16 v[76:79], v[182:185], v[206:209], v[76:79]
	v_mfma_f32_16x16x32_bf16 v[72:75], v[170:173], v[210:213], v[72:75]
	v_mfma_f32_16x16x32_bf16 v[72:75], v[174:177], v[214:217], v[72:75]
	v_mfma_f32_16x16x32_bf16 v[68:71], v[178:181], v[210:213], v[68:71]
	v_mfma_f32_16x16x32_bf16 v[68:71], v[182:185], v[214:217], v[68:71]
	s_setprio 0
	s_barrier
	s_add_i32 s0, s60, s46
	s_mov_b32 m0, s0
	ds_read_b128 v[186:189], v152 offset:16384
	ds_read_b128 v[190:193], v152 offset:17408
	ds_read_b128 v[194:197], v152 offset:18432
	ds_read_b128 v[198:201], v152 offset:19456
	ds_read_b128 v[202:205], v152 offset:20480
	ds_read_b128 v[206:209], v152 offset:21504
	ds_read_b128 v[210:213], v152 offset:22528
	ds_read_b128 v[214:217], v152 offset:23552
	global_load_lds_dwordx4 v136, s[50:51]
	s_add_i32 m0, s0, 0x2000
	s_add_u32 s72, s50, 0x100000
	s_addc_u32 s73, s51, 0
	s_add_i32 s0, s61, s46
	global_load_lds_dwordx4 v132, s[50:51]
	s_mov_b32 m0, s0
	s_nop 0
	global_load_lds_dwordx4 v136, s[72:73]
	s_add_i32 m0, s0, 0x2000
	s_nop 0
	global_load_lds_dwordx4 v132, s[72:73]
	s_mov_b32 m0, s17
	s_nop 0
	global_load_lds_dwordx4 v138, s[52:53]
	s_mov_b32 m0, s47
	s_nop 0
	global_load_lds_dwordx4 v134, s[52:53]
	s_waitcnt vmcnt(8)
	s_waitcnt lgkmcnt(0)
	s_setprio 1
	s_barrier
	v_mfma_f32_16x16x32_bf16 v[64:67], v[154:157], v[186:189], v[64:67]
	v_mfma_f32_16x16x32_bf16 v[64:67], v[158:161], v[190:193], v[64:67]
	v_mfma_f32_16x16x32_bf16 v[60:63], v[162:165], v[186:189], v[60:63]
	v_mfma_f32_16x16x32_bf16 v[60:63], v[166:169], v[190:193], v[60:63]
	v_mfma_f32_16x16x32_bf16 v[56:59], v[154:157], v[194:197], v[56:59]
	v_mfma_f32_16x16x32_bf16 v[56:59], v[158:161], v[198:201], v[56:59]
	v_mfma_f32_16x16x32_bf16 v[52:55], v[162:165], v[194:197], v[52:55]
	v_mfma_f32_16x16x32_bf16 v[52:55], v[166:169], v[198:201], v[52:55]
	v_mfma_f32_16x16x32_bf16 v[40:43], v[154:157], v[202:205], v[40:43]
	v_mfma_f32_16x16x32_bf16 v[40:43], v[158:161], v[206:209], v[40:43]
	v_mfma_f32_16x16x32_bf16 v[36:39], v[162:165], v[202:205], v[36:39]
	v_mfma_f32_16x16x32_bf16 v[36:39], v[166:169], v[206:209], v[36:39]
	v_mfma_f32_16x16x32_bf16 v[24:27], v[154:157], v[210:213], v[24:27]
	v_mfma_f32_16x16x32_bf16 v[24:27], v[158:161], v[214:217], v[24:27]
	v_mfma_f32_16x16x32_bf16 v[20:23], v[162:165], v[210:213], v[20:23]
	v_mfma_f32_16x16x32_bf16 v[20:23], v[166:169], v[214:217], v[20:23]
	s_setprio 0
	s_setprio 1
	v_mfma_f32_16x16x32_bf16 v[48:51], v[170:173], v[186:189], v[48:51]
	v_mfma_f32_16x16x32_bf16 v[48:51], v[174:177], v[190:193], v[48:51]
	v_mfma_f32_16x16x32_bf16 v[44:47], v[178:181], v[186:189], v[44:47]
	v_mfma_f32_16x16x32_bf16 v[44:47], v[182:185], v[190:193], v[44:47]
	v_mfma_f32_16x16x32_bf16 v[32:35], v[170:173], v[194:197], v[32:35]
	v_mfma_f32_16x16x32_bf16 v[32:35], v[174:177], v[198:201], v[32:35]
	v_mfma_f32_16x16x32_bf16 v[28:31], v[178:181], v[194:197], v[28:31]
	v_mfma_f32_16x16x32_bf16 v[28:31], v[182:185], v[198:201], v[28:31]
	v_mfma_f32_16x16x32_bf16 v[16:19], v[170:173], v[202:205], v[16:19]
	v_mfma_f32_16x16x32_bf16 v[16:19], v[174:177], v[206:209], v[16:19]
	v_mfma_f32_16x16x32_bf16 v[12:15], v[178:181], v[202:205], v[12:15]
	v_mfma_f32_16x16x32_bf16 v[12:15], v[182:185], v[206:209], v[12:15]
	v_mfma_f32_16x16x32_bf16 v[8:11], v[170:173], v[210:213], v[8:11]
	v_mfma_f32_16x16x32_bf16 v[8:11], v[174:177], v[214:217], v[8:11]
	v_mfma_f32_16x16x32_bf16 v[4:7], v[178:181], v[210:213], v[4:7]
	v_mfma_f32_16x16x32_bf16 v[4:7], v[182:185], v[214:217], v[4:7]
	s_setprio 0
	s_barrier
	s_add_i32 s0, 0, 0x18000
	v_add_u32_e32 v140, s0, v3
	s_add_i32 s71, 0, 0x1c000
	ds_read_b128 v[154:157], v140
	ds_read_b128 v[158:161], v140 offset:1024
	ds_read_b128 v[162:165], v140 offset:2048
	ds_read_b128 v[166:169], v140 offset:3072
	v_add_u32_e32 v140, s71, v3
	ds_read_b128 v[170:173], v140
	ds_read_b128 v[174:177], v140 offset:1024
	ds_read_b128 v[178:181], v140 offset:2048
	ds_read_b128 v[182:185], v140 offset:3072
	s_add_u32 s98, s52, 0x100000
	s_addc_u32 s99, s53, 0
	s_mov_b32 m0, s48
	ds_read_b128 v[186:189], v152 offset:32768
	ds_read_b128 v[190:193], v152 offset:33792
	ds_read_b128 v[194:197], v152 offset:34816
	ds_read_b128 v[198:201], v152 offset:35840
	ds_read_b128 v[202:205], v152 offset:36864
	ds_read_b128 v[206:209], v152 offset:37888
	ds_read_b128 v[210:213], v152 offset:38912
	ds_read_b128 v[214:217], v152 offset:39936
	global_load_lds_dwordx4 v138, s[98:99]
	s_mov_b32 m0, s49
	s_nop 0
	global_load_lds_dwordx4 v134, s[98:99]
	s_waitcnt vmcnt(8)
	s_waitcnt lgkmcnt(0)
	s_setprio 1
	s_barrier
	v_mfma_f32_16x16x32_bf16 v[128:131], v[154:157], v[186:189], v[128:131]
	v_mfma_f32_16x16x32_bf16 v[128:131], v[158:161], v[190:193], v[128:131]
	v_mfma_f32_16x16x32_bf16 v[124:127], v[162:165], v[186:189], v[124:127]
	v_mfma_f32_16x16x32_bf16 v[124:127], v[166:169], v[190:193], v[124:127]
	v_mfma_f32_16x16x32_bf16 v[120:123], v[154:157], v[194:197], v[120:123]
	v_mfma_f32_16x16x32_bf16 v[120:123], v[158:161], v[198:201], v[120:123]
	v_mfma_f32_16x16x32_bf16 v[116:119], v[162:165], v[194:197], v[116:119]
	v_mfma_f32_16x16x32_bf16 v[116:119], v[166:169], v[198:201], v[116:119]
	v_mfma_f32_16x16x32_bf16 v[104:107], v[154:157], v[202:205], v[104:107]
	v_mfma_f32_16x16x32_bf16 v[104:107], v[158:161], v[206:209], v[104:107]
	v_mfma_f32_16x16x32_bf16 v[100:103], v[162:165], v[202:205], v[100:103]
	v_mfma_f32_16x16x32_bf16 v[100:103], v[166:169], v[206:209], v[100:103]
	v_mfma_f32_16x16x32_bf16 v[88:91], v[154:157], v[210:213], v[88:91]
	v_mfma_f32_16x16x32_bf16 v[88:91], v[158:161], v[214:217], v[88:91]
	v_mfma_f32_16x16x32_bf16 v[84:87], v[162:165], v[210:213], v[84:87]
	v_mfma_f32_16x16x32_bf16 v[84:87], v[166:169], v[214:217], v[84:87]
	s_setprio 0
	s_setprio 1
	v_mfma_f32_16x16x32_bf16 v[112:115], v[170:173], v[186:189], v[112:115]
	v_mfma_f32_16x16x32_bf16 v[112:115], v[174:177], v[190:193], v[112:115]
	v_mfma_f32_16x16x32_bf16 v[108:111], v[178:181], v[186:189], v[108:111]
	v_mfma_f32_16x16x32_bf16 v[108:111], v[182:185], v[190:193], v[108:111]
	v_mfma_f32_16x16x32_bf16 v[96:99], v[170:173], v[194:197], v[96:99]
	v_mfma_f32_16x16x32_bf16 v[96:99], v[174:177], v[198:201], v[96:99]
	v_mfma_f32_16x16x32_bf16 v[92:95], v[178:181], v[194:197], v[92:95]
	v_mfma_f32_16x16x32_bf16 v[92:95], v[182:185], v[198:201], v[92:95]
	v_mfma_f32_16x16x32_bf16 v[80:83], v[170:173], v[202:205], v[80:83]
	v_mfma_f32_16x16x32_bf16 v[80:83], v[174:177], v[206:209], v[80:83]
	v_mfma_f32_16x16x32_bf16 v[76:79], v[178:181], v[202:205], v[76:79]
	v_mfma_f32_16x16x32_bf16 v[76:79], v[182:185], v[206:209], v[76:79]
	v_mfma_f32_16x16x32_bf16 v[72:75], v[170:173], v[210:213], v[72:75]
	v_mfma_f32_16x16x32_bf16 v[72:75], v[174:177], v[214:217], v[72:75]
	v_mfma_f32_16x16x32_bf16 v[68:71], v[178:181], v[210:213], v[68:71]
	v_mfma_f32_16x16x32_bf16 v[68:71], v[182:185], v[214:217], v[68:71]
	s_setprio 0
	s_barrier
	s_add_i32 s0, s0, s46
	s_add_i32 m0, s0, 0xffffff80
	ds_read_b128 v[186:189], v152 offset:49152
	ds_read_b128 v[190:193], v152 offset:50176
	ds_read_b128 v[194:197], v152 offset:51200
	ds_read_b128 v[198:201], v152 offset:52224
	ds_read_b128 v[202:205], v152 offset:53248
	ds_read_b128 v[206:209], v152 offset:54272
	ds_read_b128 v[210:213], v152 offset:55296
	ds_read_b128 v[214:217], v152 offset:56320
	global_load_lds_dwordx4 v136, s[50:51] offset:128
	s_add_i32 m0, s0, 0x1f80
	s_add_i32 s0, s71, s46
	global_load_lds_dwordx4 v132, s[50:51] offset:128
	s_add_u32 s50, s50, 0x100080
	s_addc_u32 s51, s51, 0
	s_mov_b32 m0, s0
	s_nop 0
	global_load_lds_dwordx4 v136, s[50:51]
	s_add_i32 m0, s0, 0x2000
	s_nop 0
	global_load_lds_dwordx4 v132, s[50:51]
	s_add_i32 m0, s58, 0xffffff80
	s_nop 0
	global_load_lds_dwordx4 v138, s[52:53] offset:128
	s_add_i32 m0, s59, 0xffffff80
	s_nop 0
	global_load_lds_dwordx4 v134, s[52:53] offset:128
	s_waitcnt vmcnt(8)
	s_waitcnt lgkmcnt(0)
	s_setprio 1
	s_barrier
	v_mfma_f32_16x16x32_bf16 v[64:67], v[154:157], v[186:189], v[64:67]
	v_mfma_f32_16x16x32_bf16 v[64:67], v[158:161], v[190:193], v[64:67]
	v_mfma_f32_16x16x32_bf16 v[60:63], v[162:165], v[186:189], v[60:63]
	v_mfma_f32_16x16x32_bf16 v[60:63], v[166:169], v[190:193], v[60:63]
	v_mfma_f32_16x16x32_bf16 v[56:59], v[154:157], v[194:197], v[56:59]
	v_mfma_f32_16x16x32_bf16 v[56:59], v[158:161], v[198:201], v[56:59]
	v_mfma_f32_16x16x32_bf16 v[52:55], v[162:165], v[194:197], v[52:55]
	v_mfma_f32_16x16x32_bf16 v[52:55], v[166:169], v[198:201], v[52:55]
	v_mfma_f32_16x16x32_bf16 v[40:43], v[154:157], v[202:205], v[40:43]
	v_mfma_f32_16x16x32_bf16 v[40:43], v[158:161], v[206:209], v[40:43]
	v_mfma_f32_16x16x32_bf16 v[36:39], v[162:165], v[202:205], v[36:39]
	v_mfma_f32_16x16x32_bf16 v[36:39], v[166:169], v[206:209], v[36:39]
	v_mfma_f32_16x16x32_bf16 v[24:27], v[154:157], v[210:213], v[24:27]
	v_mfma_f32_16x16x32_bf16 v[24:27], v[158:161], v[214:217], v[24:27]
	v_mfma_f32_16x16x32_bf16 v[20:23], v[162:165], v[210:213], v[20:23]
	v_mfma_f32_16x16x32_bf16 v[20:23], v[166:169], v[214:217], v[20:23]
	s_setprio 0
	s_setprio 1
	v_mfma_f32_16x16x32_bf16 v[48:51], v[170:173], v[186:189], v[48:51]
	v_mfma_f32_16x16x32_bf16 v[48:51], v[174:177], v[190:193], v[48:51]
	v_mfma_f32_16x16x32_bf16 v[44:47], v[178:181], v[186:189], v[44:47]
	v_mfma_f32_16x16x32_bf16 v[44:47], v[182:185], v[190:193], v[44:47]
	v_mfma_f32_16x16x32_bf16 v[32:35], v[170:173], v[194:197], v[32:35]
	v_mfma_f32_16x16x32_bf16 v[32:35], v[174:177], v[198:201], v[32:35]
	v_mfma_f32_16x16x32_bf16 v[28:31], v[178:181], v[194:197], v[28:31]
	v_mfma_f32_16x16x32_bf16 v[28:31], v[182:185], v[198:201], v[28:31]
	v_mfma_f32_16x16x32_bf16 v[16:19], v[170:173], v[202:205], v[16:19]
	v_mfma_f32_16x16x32_bf16 v[16:19], v[174:177], v[206:209], v[16:19]
	v_mfma_f32_16x16x32_bf16 v[12:15], v[178:181], v[202:205], v[12:15]
	v_mfma_f32_16x16x32_bf16 v[12:15], v[182:185], v[206:209], v[12:15]
	v_mfma_f32_16x16x32_bf16 v[8:11], v[170:173], v[210:213], v[8:11]
	v_mfma_f32_16x16x32_bf16 v[8:11], v[174:177], v[214:217], v[8:11]
	v_mfma_f32_16x16x32_bf16 v[4:7], v[178:181], v[210:213], v[4:7]
	v_mfma_f32_16x16x32_bf16 v[4:7], v[182:185], v[214:217], v[4:7]
	s_setprio 0
	s_barrier
	s_add_i32 s70, s70, 2
	s_add_u32 s42, s42, 0x100
	s_addc_u32 s43, s43, 0
	s_add_u32 s31, s31, 0x100
	s_addc_u32 s41, s41, 0
	s_cmp_gt_u32 s70, 13
	s_cbranch_scc0 .LBB0_1288
	s_and_b64 vcc, exec, s[14:15]
	s_cbranch_vccz .LBB0_1291
	s_barrier

.LBB0_1415:
	ds_read_b128 v[132:135], v187
	ds_read_b128 v[136:139], v187 offset:1024
	ds_read_b128 v[140:143], v187 offset:2048
	ds_read_b128 v[144:147], v187 offset:3072
	ds_read_b128 v[148:151], v188
	ds_read_b128 v[152:155], v188 offset:1024
	ds_read_b128 v[172:175], v188 offset:2048
	ds_read_b128 v[176:179], v188 offset:3072
	s_add_u32 s0, s42, 0xfffe0080
	s_addc_u32 s50, s43, -1
	s_cmp_eq_u32 s64, 4
	s_cselect_b32 s53, s25, s50
	s_cselect_b32 s52, s31, s0
	s_cselect_b32 s51, s23, s63
	s_cselect_b32 s50, s61, s62
	s_add_i32 m0, s41, 0xc000
	ds_read_b128 v[180:183], v189
	ds_read_b128 v[192:195], v189 offset:1024
	ds_read_b128 v[196:199], v189 offset:2048
	ds_read_b128 v[200:203], v189 offset:3072
	ds_read_b128 v[204:207], v189 offset:4096
	ds_read_b128 v[208:211], v189 offset:5120
	ds_read_b128 v[212:215], v189 offset:6144
	ds_read_b128 v[216:219], v189 offset:7168
	global_load_lds_dwordx4 v164, s[42:43]
	s_add_i32 m0, s41, 0xe000
	s_nop 0
	global_load_lds_dwordx4 v166, s[42:43]
	s_waitcnt vmcnt(8)
	s_waitcnt lgkmcnt(0)
	s_setprio 1
	s_barrier
	v_mfma_f32_16x16x32_bf16 v[128:131], v[132:135], v[180:183], v[128:131]
	v_mfma_f32_16x16x32_bf16 v[128:131], v[136:139], v[192:195], v[128:131]
	v_mfma_f32_16x16x32_bf16 v[124:127], v[140:143], v[180:183], v[124:127]
	v_mfma_f32_16x16x32_bf16 v[124:127], v[144:147], v[192:195], v[124:127]
	v_mfma_f32_16x16x32_bf16 v[112:115], v[132:135], v[196:199], v[112:115]
	v_mfma_f32_16x16x32_bf16 v[112:115], v[136:139], v[200:203], v[112:115]
	v_mfma_f32_16x16x32_bf16 v[108:111], v[140:143], v[196:199], v[108:111]
	v_mfma_f32_16x16x32_bf16 v[108:111], v[144:147], v[200:203], v[108:111]
	v_mfma_f32_16x16x32_bf16 v[96:99], v[132:135], v[204:207], v[96:99]
	v_mfma_f32_16x16x32_bf16 v[96:99], v[136:139], v[208:211], v[96:99]
	v_mfma_f32_16x16x32_bf16 v[92:95], v[140:143], v[204:207], v[92:95]
	v_mfma_f32_16x16x32_bf16 v[92:95], v[144:147], v[208:211], v[92:95]
	v_mfma_f32_16x16x32_bf16 v[80:83], v[132:135], v[212:215], v[80:83]
	v_mfma_f32_16x16x32_bf16 v[80:83], v[136:139], v[216:219], v[80:83]
	v_mfma_f32_16x16x32_bf16 v[76:79], v[140:143], v[212:215], v[76:79]
	v_mfma_f32_16x16x32_bf16 v[76:79], v[144:147], v[216:219], v[76:79]
	s_setprio 0
	s_setprio 1
	v_mfma_f32_16x16x32_bf16 v[120:123], v[148:151], v[180:183], v[120:123]
	v_mfma_f32_16x16x32_bf16 v[120:123], v[152:155], v[192:195], v[120:123]
	v_mfma_f32_16x16x32_bf16 v[116:119], v[172:175], v[180:183], v[116:119]
	v_mfma_f32_16x16x32_bf16 v[116:119], v[176:179], v[192:195], v[116:119]
	v_mfma_f32_16x16x32_bf16 v[104:107], v[148:151], v[196:199], v[104:107]
	v_mfma_f32_16x16x32_bf16 v[104:107], v[152:155], v[200:203], v[104:107]
	v_mfma_f32_16x16x32_bf16 v[100:103], v[172:175], v[196:199], v[100:103]
	v_mfma_f32_16x16x32_bf16 v[100:103], v[176:179], v[200:203], v[100:103]
	v_mfma_f32_16x16x32_bf16 v[88:91], v[148:151], v[204:207], v[88:91]
	v_mfma_f32_16x16x32_bf16 v[88:91], v[152:155], v[208:211], v[88:91]
	v_mfma_f32_16x16x32_bf16 v[84:87], v[172:175], v[204:207], v[84:87]
	v_mfma_f32_16x16x32_bf16 v[84:87], v[176:179], v[208:211], v[84:87]
	v_mfma_f32_16x16x32_bf16 v[72:75], v[148:151], v[212:215], v[72:75]
	v_mfma_f32_16x16x32_bf16 v[72:75], v[152:155], v[216:219], v[72:75]
	v_mfma_f32_16x16x32_bf16 v[68:71], v[172:175], v[212:215], v[68:71]
	v_mfma_f32_16x16x32_bf16 v[68:71], v[176:179], v[216:219], v[68:71]
	s_setprio 0
	s_barrier
	s_add_i32 s0, s58, s45
	s_mov_b32 m0, s0
	ds_read_b128 v[180:183], v189 offset:16384
	ds_read_b128 v[192:195], v189 offset:17408
	ds_read_b128 v[196:199], v189 offset:18432
	ds_read_b128 v[200:203], v189 offset:19456
	ds_read_b128 v[204:207], v189 offset:20480
	ds_read_b128 v[208:211], v189 offset:21504
	ds_read_b128 v[212:215], v189 offset:22528
	ds_read_b128 v[216:219], v189 offset:23552
	global_load_lds_dwordx4 v158, s[50:51]
	s_add_i32 m0, s0, 0x2000
	s_add_u32 s66, s50, 0x20000
	s_addc_u32 s67, s51, 0
	s_add_i32 s0, s59, s45
	global_load_lds_dwordx4 v162, s[50:51]
	s_mov_b32 m0, s0
	s_nop 0
	global_load_lds_dwordx4 v158, s[66:67]
	s_add_i32 m0, s0, 0x2000
	s_nop 0
	global_load_lds_dwordx4 v162, s[66:67]
	s_mov_b32 m0, s41
	s_nop 0
	global_load_lds_dwordx4 v156, s[52:53]
	s_mov_b32 m0, s46
	s_nop 0
	global_load_lds_dwordx4 v160, s[52:53]
	s_waitcnt vmcnt(8)
	s_waitcnt lgkmcnt(0)
	s_setprio 1
	s_barrier
	v_mfma_f32_16x16x32_bf16 v[64:67], v[132:135], v[180:183], v[64:67]
	v_mfma_f32_16x16x32_bf16 v[64:67], v[136:139], v[192:195], v[64:67]
	v_mfma_f32_16x16x32_bf16 v[60:63], v[140:143], v[180:183], v[60:63]
	v_mfma_f32_16x16x32_bf16 v[60:63], v[144:147], v[192:195], v[60:63]
	v_mfma_f32_16x16x32_bf16 v[48:51], v[132:135], v[196:199], v[48:51]
	v_mfma_f32_16x16x32_bf16 v[48:51], v[136:139], v[200:203], v[48:51]
	v_mfma_f32_16x16x32_bf16 v[44:47], v[140:143], v[196:199], v[44:47]
	v_mfma_f32_16x16x32_bf16 v[44:47], v[144:147], v[200:203], v[44:47]
	v_mfma_f32_16x16x32_bf16 v[32:35], v[132:135], v[204:207], v[32:35]
	v_mfma_f32_16x16x32_bf16 v[32:35], v[136:139], v[208:211], v[32:35]
	v_mfma_f32_16x16x32_bf16 v[28:31], v[140:143], v[204:207], v[28:31]
	v_mfma_f32_16x16x32_bf16 v[28:31], v[144:147], v[208:211], v[28:31]
	v_mfma_f32_16x16x32_bf16 v[16:19], v[132:135], v[212:215], v[16:19]
	v_mfma_f32_16x16x32_bf16 v[16:19], v[136:139], v[216:219], v[16:19]
	v_mfma_f32_16x16x32_bf16 v[12:15], v[140:143], v[212:215], v[12:15]
	v_mfma_f32_16x16x32_bf16 v[12:15], v[144:147], v[216:219], v[12:15]
	s_setprio 0
	s_setprio 1
	v_mfma_f32_16x16x32_bf16 v[56:59], v[148:151], v[180:183], v[56:59]
	v_mfma_f32_16x16x32_bf16 v[56:59], v[152:155], v[192:195], v[56:59]
	v_mfma_f32_16x16x32_bf16 v[52:55], v[172:175], v[180:183], v[52:55]
	v_mfma_f32_16x16x32_bf16 v[52:55], v[176:179], v[192:195], v[52:55]
	v_mfma_f32_16x16x32_bf16 v[40:43], v[148:151], v[196:199], v[40:43]
	v_mfma_f32_16x16x32_bf16 v[40:43], v[152:155], v[200:203], v[40:43]
	v_mfma_f32_16x16x32_bf16 v[36:39], v[172:175], v[196:199], v[36:39]
	v_mfma_f32_16x16x32_bf16 v[36:39], v[176:179], v[200:203], v[36:39]
	v_mfma_f32_16x16x32_bf16 v[24:27], v[148:151], v[204:207], v[24:27]
	v_mfma_f32_16x16x32_bf16 v[24:27], v[152:155], v[208:211], v[24:27]
	v_mfma_f32_16x16x32_bf16 v[20:23], v[172:175], v[204:207], v[20:23]
	v_mfma_f32_16x16x32_bf16 v[20:23], v[176:179], v[208:211], v[20:23]
	v_mfma_f32_16x16x32_bf16 v[8:11], v[148:151], v[212:215], v[8:11]
	v_mfma_f32_16x16x32_bf16 v[8:11], v[152:155], v[216:219], v[8:11]
	v_mfma_f32_16x16x32_bf16 v[4:7], v[172:175], v[212:215], v[4:7]
	v_mfma_f32_16x16x32_bf16 v[4:7], v[176:179], v[216:219], v[4:7]
	s_setprio 0
	s_barrier
	s_add_i32 s0, 0, 0x18000
	s_add_i32 s65, 0, 0x1c000
	v_add_u32_e32 v144, s0, v3
	v_add_u32_e32 v176, s65, v3
	ds_read_b128 v[132:135], v144
	ds_read_b128 v[136:139], v144 offset:1024
	ds_read_b128 v[140:143], v144 offset:2048
	ds_read_b128 v[144:147], v144 offset:3072
	ds_read_b128 v[148:151], v176
	ds_read_b128 v[152:155], v176 offset:1024
	ds_read_b128 v[172:175], v176 offset:2048
	ds_read_b128 v[176:179], v176 offset:3072
	s_add_u32 s98, s52, 0x20000
	s_addc_u32 s99, s53, 0
	s_mov_b32 m0, s47
	ds_read_b128 v[180:183], v189 offset:32768
	ds_read_b128 v[192:195], v189 offset:33792
	ds_read_b128 v[196:199], v189 offset:34816
	ds_read_b128 v[200:203], v189 offset:35840
	ds_read_b128 v[204:207], v189 offset:36864
	ds_read_b128 v[208:211], v189 offset:37888
	ds_read_b128 v[212:215], v189 offset:38912
	ds_read_b128 v[216:219], v189 offset:39936
	global_load_lds_dwordx4 v156, s[98:99]
	s_mov_b32 m0, s48
	s_nop 0
	global_load_lds_dwordx4 v160, s[98:99]
	s_waitcnt vmcnt(8)
	s_waitcnt lgkmcnt(0)
	s_setprio 1
	s_barrier
	v_mfma_f32_16x16x32_bf16 v[128:131], v[132:135], v[180:183], v[128:131]
	v_mfma_f32_16x16x32_bf16 v[128:131], v[136:139], v[192:195], v[128:131]
	v_mfma_f32_16x16x32_bf16 v[124:127], v[140:143], v[180:183], v[124:127]
	v_mfma_f32_16x16x32_bf16 v[124:127], v[144:147], v[192:195], v[124:127]
	v_mfma_f32_16x16x32_bf16 v[112:115], v[132:135], v[196:199], v[112:115]
	v_mfma_f32_16x16x32_bf16 v[112:115], v[136:139], v[200:203], v[112:115]
	v_mfma_f32_16x16x32_bf16 v[108:111], v[140:143], v[196:199], v[108:111]
	v_mfma_f32_16x16x32_bf16 v[108:111], v[144:147], v[200:203], v[108:111]
	v_mfma_f32_16x16x32_bf16 v[96:99], v[132:135], v[204:207], v[96:99]
	v_mfma_f32_16x16x32_bf16 v[96:99], v[136:139], v[208:211], v[96:99]
	v_mfma_f32_16x16x32_bf16 v[92:95], v[140:143], v[204:207], v[92:95]
	v_mfma_f32_16x16x32_bf16 v[92:95], v[144:147], v[208:211], v[92:95]
	v_mfma_f32_16x16x32_bf16 v[80:83], v[132:135], v[212:215], v[80:83]
	v_mfma_f32_16x16x32_bf16 v[80:83], v[136:139], v[216:219], v[80:83]
	v_mfma_f32_16x16x32_bf16 v[76:79], v[140:143], v[212:215], v[76:79]
	v_mfma_f32_16x16x32_bf16 v[76:79], v[144:147], v[216:219], v[76:79]
	s_setprio 0
	s_setprio 1
	v_mfma_f32_16x16x32_bf16 v[120:123], v[148:151], v[180:183], v[120:123]
	v_mfma_f32_16x16x32_bf16 v[120:123], v[152:155], v[192:195], v[120:123]
	v_mfma_f32_16x16x32_bf16 v[116:119], v[172:175], v[180:183], v[116:119]
	v_mfma_f32_16x16x32_bf16 v[116:119], v[176:179], v[192:195], v[116:119]
	v_mfma_f32_16x16x32_bf16 v[104:107], v[148:151], v[196:199], v[104:107]
	v_mfma_f32_16x16x32_bf16 v[104:107], v[152:155], v[200:203], v[104:107]
	v_mfma_f32_16x16x32_bf16 v[100:103], v[172:175], v[196:199], v[100:103]
	v_mfma_f32_16x16x32_bf16 v[100:103], v[176:179], v[200:203], v[100:103]
	v_mfma_f32_16x16x32_bf16 v[88:91], v[148:151], v[204:207], v[88:91]
	v_mfma_f32_16x16x32_bf16 v[88:91], v[152:155], v[208:211], v[88:91]
	v_mfma_f32_16x16x32_bf16 v[84:87], v[172:175], v[204:207], v[84:87]
	v_mfma_f32_16x16x32_bf16 v[84:87], v[176:179], v[208:211], v[84:87]
	v_mfma_f32_16x16x32_bf16 v[72:75], v[148:151], v[212:215], v[72:75]
	v_mfma_f32_16x16x32_bf16 v[72:75], v[152:155], v[216:219], v[72:75]
	v_mfma_f32_16x16x32_bf16 v[68:71], v[172:175], v[212:215], v[68:71]
	v_mfma_f32_16x16x32_bf16 v[68:71], v[176:179], v[216:219], v[68:71]
	s_setprio 0
	s_barrier
	s_add_i32 s0, s0, s45
	s_add_i32 m0, s0, 0xffffff80
	ds_read_b128 v[180:183], v189 offset:49152
	ds_read_b128 v[192:195], v189 offset:50176
	ds_read_b128 v[196:199], v189 offset:51200
	ds_read_b128 v[200:203], v189 offset:52224
	ds_read_b128 v[204:207], v189 offset:53248
	ds_read_b128 v[208:211], v189 offset:54272
	ds_read_b128 v[212:215], v189 offset:55296
	ds_read_b128 v[216:219], v189 offset:56320
	global_load_lds_dwordx4 v158, s[50:51] offset:128
	s_add_i32 m0, s0, 0x1f80
	s_add_i32 s0, s65, s45
	global_load_lds_dwordx4 v162, s[50:51] offset:128
	s_add_u32 s50, s50, 0x20080
	s_addc_u32 s51, s51, 0
	s_mov_b32 m0, s0
	s_nop 0
	global_load_lds_dwordx4 v158, s[50:51]
	s_add_i32 m0, s0, 0x2000
	s_nop 0
	global_load_lds_dwordx4 v162, s[50:51]
	s_add_i32 m0, s56, 0xffffff80
	s_nop 0
	global_load_lds_dwordx4 v156, s[52:53] offset:128
	s_add_i32 m0, s57, 0xffffff80
	s_nop 0
	global_load_lds_dwordx4 v160, s[52:53] offset:128
	s_waitcnt vmcnt(8)
	s_waitcnt lgkmcnt(0)
	s_setprio 1
	s_barrier
	v_mfma_f32_16x16x32_bf16 v[64:67], v[132:135], v[180:183], v[64:67]
	v_mfma_f32_16x16x32_bf16 v[64:67], v[136:139], v[192:195], v[64:67]
	v_mfma_f32_16x16x32_bf16 v[60:63], v[140:143], v[180:183], v[60:63]
	v_mfma_f32_16x16x32_bf16 v[60:63], v[144:147], v[192:195], v[60:63]
	v_mfma_f32_16x16x32_bf16 v[48:51], v[132:135], v[196:199], v[48:51]
	v_mfma_f32_16x16x32_bf16 v[48:51], v[136:139], v[200:203], v[48:51]
	v_mfma_f32_16x16x32_bf16 v[44:47], v[140:143], v[196:199], v[44:47]
	v_mfma_f32_16x16x32_bf16 v[44:47], v[144:147], v[200:203], v[44:47]
	v_mfma_f32_16x16x32_bf16 v[32:35], v[132:135], v[204:207], v[32:35]
	v_mfma_f32_16x16x32_bf16 v[32:35], v[136:139], v[208:211], v[32:35]
	v_mfma_f32_16x16x32_bf16 v[28:31], v[140:143], v[204:207], v[28:31]
	v_mfma_f32_16x16x32_bf16 v[28:31], v[144:147], v[208:211], v[28:31]
	v_mfma_f32_16x16x32_bf16 v[16:19], v[132:135], v[212:215], v[16:19]
	v_mfma_f32_16x16x32_bf16 v[16:19], v[136:139], v[216:219], v[16:19]
	v_mfma_f32_16x16x32_bf16 v[12:15], v[140:143], v[212:215], v[12:15]
	v_mfma_f32_16x16x32_bf16 v[12:15], v[144:147], v[216:219], v[12:15]
	s_setprio 0
	s_setprio 1
	v_mfma_f32_16x16x32_bf16 v[56:59], v[148:151], v[180:183], v[56:59]
	v_mfma_f32_16x16x32_bf16 v[56:59], v[152:155], v[192:195], v[56:59]
	v_mfma_f32_16x16x32_bf16 v[52:55], v[172:175], v[180:183], v[52:55]
	v_mfma_f32_16x16x32_bf16 v[52:55], v[176:179], v[192:195], v[52:55]
	v_mfma_f32_16x16x32_bf16 v[40:43], v[148:151], v[196:199], v[40:43]
	v_mfma_f32_16x16x32_bf16 v[40:43], v[152:155], v[200:203], v[40:43]
	v_mfma_f32_16x16x32_bf16 v[36:39], v[172:175], v[196:199], v[36:39]
	v_mfma_f32_16x16x32_bf16 v[36:39], v[176:179], v[200:203], v[36:39]
	v_mfma_f32_16x16x32_bf16 v[24:27], v[148:151], v[204:207], v[24:27]
	v_mfma_f32_16x16x32_bf16 v[24:27], v[152:155], v[208:211], v[24:27]
	v_mfma_f32_16x16x32_bf16 v[20:23], v[172:175], v[204:207], v[20:23]
	v_mfma_f32_16x16x32_bf16 v[20:23], v[176:179], v[208:211], v[20:23]
	v_mfma_f32_16x16x32_bf16 v[8:11], v[148:151], v[212:215], v[8:11]
	v_mfma_f32_16x16x32_bf16 v[8:11], v[152:155], v[216:219], v[8:11]
	v_mfma_f32_16x16x32_bf16 v[4:7], v[172:175], v[212:215], v[4:7]
	v_mfma_f32_16x16x32_bf16 v[4:7], v[176:179], v[216:219], v[4:7]
	s_setprio 0
	s_barrier
	s_add_i32 s64, s64, 2
	s_add_u32 s42, s42, 0x100
	s_addc_u32 s43, s43, 0
	s_add_u32 s62, s62, 0x100
	s_addc_u32 s63, s63, 0
	s_cmp_gt_u32 s64, 5
	s_cbranch_scc0 .LBB0_1415
	s_and_b64 vcc, exec, s[16:17]
	s_cbranch_vccz .LBB0_1418
	s_barrier

.LBB0_1503:
	ds_read_b128 v[132:135], v159
	ds_read_b128 v[164:167], v159 offset:1024
	ds_read_b128 v[168:171], v159 offset:2048
	ds_read_b128 v[172:175], v159 offset:3072
	ds_read_b128 v[176:179], v160
	ds_read_b128 v[180:183], v160 offset:1024
	ds_read_b128 v[184:187], v160 offset:2048
	ds_read_b128 v[188:191], v160 offset:3072
	s_add_u32 s0, s54, 0xfff00080
	s_addc_u32 s56, s55, -1
	s_cmp_eq_u32 s75, 60
	s_cselect_b32 s59, s31, s56
	s_cselect_b32 s58, s71, s0
	s_cselect_b32 s57, s29, s74
	s_cselect_b32 s56, s72, s73
	s_add_i32 m0, s48, 0xc000
	ds_read_b128 v[192:195], v161
	ds_read_b128 v[196:199], v161 offset:1024
	ds_read_b128 v[200:203], v161 offset:2048
	ds_read_b128 v[204:207], v161 offset:3072
	ds_read_b128 v[208:211], v161 offset:4096
	ds_read_b128 v[212:215], v161 offset:5120
	ds_read_b128 v[216:219], v161 offset:6144
	ds_read_b128 v[220:223], v161 offset:7168
	global_load_lds_dwordx4 v148, s[54:55]
	s_add_i32 m0, s48, 0xe000
	s_nop 0
	global_load_lds_dwordx4 v150, s[54:55]
	s_waitcnt vmcnt(8)
	s_waitcnt lgkmcnt(0)
	s_setprio 1
	s_barrier
	v_mfma_f32_16x16x32_bf16 v[136:139], v[132:135], v[192:195], v[136:139]
	v_mfma_f32_16x16x32_bf16 v[136:139], v[164:167], v[196:199], v[136:139]
	v_mfma_f32_16x16x32_bf16 v[128:131], v[168:171], v[192:195], v[128:131]
	v_mfma_f32_16x16x32_bf16 v[128:131], v[172:175], v[196:199], v[128:131]
	v_mfma_f32_16x16x32_bf16 v[116:119], v[132:135], v[200:203], v[116:119]
	v_mfma_f32_16x16x32_bf16 v[116:119], v[164:167], v[204:207], v[116:119]
	v_mfma_f32_16x16x32_bf16 v[112:115], v[168:171], v[200:203], v[112:115]
	v_mfma_f32_16x16x32_bf16 v[112:115], v[172:175], v[204:207], v[112:115]
	v_mfma_f32_16x16x32_bf16 v[100:103], v[132:135], v[208:211], v[100:103]
	v_mfma_f32_16x16x32_bf16 v[100:103], v[164:167], v[212:215], v[100:103]
	v_mfma_f32_16x16x32_bf16 v[96:99], v[168:171], v[208:211], v[96:99]
	v_mfma_f32_16x16x32_bf16 v[96:99], v[172:175], v[212:215], v[96:99]
	v_mfma_f32_16x16x32_bf16 v[84:87], v[132:135], v[216:219], v[84:87]
	v_mfma_f32_16x16x32_bf16 v[84:87], v[164:167], v[220:223], v[84:87]
	v_mfma_f32_16x16x32_bf16 v[80:83], v[168:171], v[216:219], v[80:83]
	v_mfma_f32_16x16x32_bf16 v[80:83], v[172:175], v[220:223], v[80:83]
	s_setprio 0
	s_setprio 1
	v_mfma_f32_16x16x32_bf16 v[124:127], v[176:179], v[192:195], v[124:127]
	v_mfma_f32_16x16x32_bf16 v[124:127], v[180:183], v[196:199], v[124:127]
	v_mfma_f32_16x16x32_bf16 v[120:123], v[184:187], v[192:195], v[120:123]
	v_mfma_f32_16x16x32_bf16 v[120:123], v[188:191], v[196:199], v[120:123]
	v_mfma_f32_16x16x32_bf16 v[108:111], v[176:179], v[200:203], v[108:111]
	v_mfma_f32_16x16x32_bf16 v[108:111], v[180:183], v[204:207], v[108:111]
	v_mfma_f32_16x16x32_bf16 v[104:107], v[184:187], v[200:203], v[104:107]
	v_mfma_f32_16x16x32_bf16 v[104:107], v[188:191], v[204:207], v[104:107]
	v_mfma_f32_16x16x32_bf16 v[92:95], v[176:179], v[208:211], v[92:95]
	v_mfma_f32_16x16x32_bf16 v[92:95], v[180:183], v[212:215], v[92:95]
	v_mfma_f32_16x16x32_bf16 v[88:91], v[184:187], v[208:211], v[88:91]
	v_mfma_f32_16x16x32_bf16 v[88:91], v[188:191], v[212:215], v[88:91]
	v_mfma_f32_16x16x32_bf16 v[76:79], v[176:179], v[216:219], v[76:79]
	v_mfma_f32_16x16x32_bf16 v[76:79], v[180:183], v[220:223], v[76:79]
	v_mfma_f32_16x16x32_bf16 v[72:75], v[184:187], v[216:219], v[72:75]
	v_mfma_f32_16x16x32_bf16 v[72:75], v[188:191], v[220:223], v[72:75]
	s_setprio 0
	s_barrier
	s_add_i32 s0, s65, s47
	s_mov_b32 m0, s0
	ds_read_b128 v[192:195], v161 offset:16384
	ds_read_b128 v[196:199], v161 offset:17408
	ds_read_b128 v[200:203], v161 offset:18432
	ds_read_b128 v[204:207], v161 offset:19456
	ds_read_b128 v[208:211], v161 offset:20480
	ds_read_b128 v[212:215], v161 offset:21504
	ds_read_b128 v[216:219], v161 offset:22528
	ds_read_b128 v[220:223], v161 offset:23552
	global_load_lds_dwordx4 v142, s[56:57]
	s_add_i32 m0, s0, 0x2000
	s_add_u32 s76, s56, 0x100000
	s_addc_u32 s77, s57, 0
	s_add_i32 s0, s66, s47
	global_load_lds_dwordx4 v146, s[56:57]
	s_mov_b32 m0, s0
	s_nop 0
	global_load_lds_dwordx4 v142, s[76:77]
	s_add_i32 m0, s0, 0x2000
	s_nop 0
	global_load_lds_dwordx4 v146, s[76:77]
	s_mov_b32 m0, s48
	s_nop 0
	global_load_lds_dwordx4 v140, s[58:59]
	s_mov_b32 m0, s49
	s_nop 0
	global_load_lds_dwordx4 v144, s[58:59]
	s_waitcnt vmcnt(8)
	s_waitcnt lgkmcnt(0)
	s_setprio 1
	s_barrier
	v_mfma_f32_16x16x32_bf16 v[68:71], v[132:135], v[192:195], v[68:71]
	v_mfma_f32_16x16x32_bf16 v[68:71], v[164:167], v[196:199], v[68:71]
	v_mfma_f32_16x16x32_bf16 v[64:67], v[168:171], v[192:195], v[64:67]
	v_mfma_f32_16x16x32_bf16 v[64:67], v[172:175], v[196:199], v[64:67]
	v_mfma_f32_16x16x32_bf16 v[52:55], v[132:135], v[200:203], v[52:55]
	v_mfma_f32_16x16x32_bf16 v[52:55], v[164:167], v[204:207], v[52:55]
	v_mfma_f32_16x16x32_bf16 v[48:51], v[168:171], v[200:203], v[48:51]
	v_mfma_f32_16x16x32_bf16 v[48:51], v[172:175], v[204:207], v[48:51]
	v_mfma_f32_16x16x32_bf16 v[36:39], v[132:135], v[208:211], v[36:39]
	v_mfma_f32_16x16x32_bf16 v[36:39], v[164:167], v[212:215], v[36:39]
	v_mfma_f32_16x16x32_bf16 v[32:35], v[168:171], v[208:211], v[32:35]
	v_mfma_f32_16x16x32_bf16 v[32:35], v[172:175], v[212:215], v[32:35]
	v_mfma_f32_16x16x32_bf16 v[20:23], v[132:135], v[216:219], v[20:23]
	v_mfma_f32_16x16x32_bf16 v[20:23], v[164:167], v[220:223], v[20:23]
	v_mfma_f32_16x16x32_bf16 v[16:19], v[168:171], v[216:219], v[16:19]
	v_mfma_f32_16x16x32_bf16 v[16:19], v[172:175], v[220:223], v[16:19]
	s_setprio 0
	s_setprio 1
	v_mfma_f32_16x16x32_bf16 v[60:63], v[176:179], v[192:195], v[60:63]
	v_mfma_f32_16x16x32_bf16 v[60:63], v[180:183], v[196:199], v[60:63]
	v_mfma_f32_16x16x32_bf16 v[56:59], v[184:187], v[192:195], v[56:59]
	v_mfma_f32_16x16x32_bf16 v[56:59], v[188:191], v[196:199], v[56:59]
	v_mfma_f32_16x16x32_bf16 v[44:47], v[176:179], v[200:203], v[44:47]
	v_mfma_f32_16x16x32_bf16 v[44:47], v[180:183], v[204:207], v[44:47]
	v_mfma_f32_16x16x32_bf16 v[40:43], v[184:187], v[200:203], v[40:43]
	v_mfma_f32_16x16x32_bf16 v[40:43], v[188:191], v[204:207], v[40:43]
	v_mfma_f32_16x16x32_bf16 v[28:31], v[176:179], v[208:211], v[28:31]
	v_mfma_f32_16x16x32_bf16 v[28:31], v[180:183], v[212:215], v[28:31]
	v_mfma_f32_16x16x32_bf16 v[24:27], v[184:187], v[208:211], v[24:27]
	v_mfma_f32_16x16x32_bf16 v[24:27], v[188:191], v[212:215], v[24:27]
	v_mfma_f32_16x16x32_bf16 v[12:15], v[176:179], v[216:219], v[12:15]
	v_mfma_f32_16x16x32_bf16 v[12:15], v[180:183], v[220:223], v[12:15]
	v_mfma_f32_16x16x32_bf16 v[8:11], v[184:187], v[216:219], v[8:11]
	v_mfma_f32_16x16x32_bf16 v[8:11], v[188:191], v[220:223], v[8:11]
	s_setprio 0
	s_barrier
	s_add_i32 s0, 0, 0x18000
	s_add_i32 s76, 0, 0x1c000
	v_add_u32_e32 v172, s0, v156
	v_add_u32_e32 v188, s76, v156
	ds_read_b128 v[132:135], v172
	ds_read_b128 v[164:167], v172 offset:1024
	ds_read_b128 v[168:171], v172 offset:2048
	ds_read_b128 v[172:175], v172 offset:3072
	ds_read_b128 v[176:179], v188
	ds_read_b128 v[180:183], v188 offset:1024
	ds_read_b128 v[184:187], v188 offset:2048
	ds_read_b128 v[188:191], v188 offset:3072
	s_add_u32 s98, s58, 0x100000
	s_addc_u32 s99, s59, 0
	s_mov_b32 m0, s51
	ds_read_b128 v[192:195], v161 offset:32768
	ds_read_b128 v[196:199], v161 offset:33792
	ds_read_b128 v[200:203], v161 offset:34816
	ds_read_b128 v[204:207], v161 offset:35840
	ds_read_b128 v[208:211], v161 offset:36864
	ds_read_b128 v[212:215], v161 offset:37888
	ds_read_b128 v[216:219], v161 offset:38912
	ds_read_b128 v[220:223], v161 offset:39936
	global_load_lds_dwordx4 v140, s[98:99]
	s_mov_b32 m0, s53
	s_nop 0
	global_load_lds_dwordx4 v144, s[98:99]
	s_waitcnt vmcnt(8)
	s_waitcnt lgkmcnt(0)
	s_setprio 1
	s_barrier
	v_mfma_f32_16x16x32_bf16 v[136:139], v[132:135], v[192:195], v[136:139]
	v_mfma_f32_16x16x32_bf16 v[136:139], v[164:167], v[196:199], v[136:139]
	v_mfma_f32_16x16x32_bf16 v[128:131], v[168:171], v[192:195], v[128:131]
	v_mfma_f32_16x16x32_bf16 v[128:131], v[172:175], v[196:199], v[128:131]
	v_mfma_f32_16x16x32_bf16 v[116:119], v[132:135], v[200:203], v[116:119]
	v_mfma_f32_16x16x32_bf16 v[116:119], v[164:167], v[204:207], v[116:119]
	v_mfma_f32_16x16x32_bf16 v[112:115], v[168:171], v[200:203], v[112:115]
	v_mfma_f32_16x16x32_bf16 v[112:115], v[172:175], v[204:207], v[112:115]
	v_mfma_f32_16x16x32_bf16 v[100:103], v[132:135], v[208:211], v[100:103]
	v_mfma_f32_16x16x32_bf16 v[100:103], v[164:167], v[212:215], v[100:103]
	v_mfma_f32_16x16x32_bf16 v[96:99], v[168:171], v[208:211], v[96:99]
	v_mfma_f32_16x16x32_bf16 v[96:99], v[172:175], v[212:215], v[96:99]
	v_mfma_f32_16x16x32_bf16 v[84:87], v[132:135], v[216:219], v[84:87]
	v_mfma_f32_16x16x32_bf16 v[84:87], v[164:167], v[220:223], v[84:87]
	v_mfma_f32_16x16x32_bf16 v[80:83], v[168:171], v[216:219], v[80:83]
	v_mfma_f32_16x16x32_bf16 v[80:83], v[172:175], v[220:223], v[80:83]
	s_setprio 0
	s_setprio 1
	v_mfma_f32_16x16x32_bf16 v[124:127], v[176:179], v[192:195], v[124:127]
	v_mfma_f32_16x16x32_bf16 v[124:127], v[180:183], v[196:199], v[124:127]
	v_mfma_f32_16x16x32_bf16 v[120:123], v[184:187], v[192:195], v[120:123]
	v_mfma_f32_16x16x32_bf16 v[120:123], v[188:191], v[196:199], v[120:123]
	v_mfma_f32_16x16x32_bf16 v[108:111], v[176:179], v[200:203], v[108:111]
	v_mfma_f32_16x16x32_bf16 v[108:111], v[180:183], v[204:207], v[108:111]
	v_mfma_f32_16x16x32_bf16 v[104:107], v[184:187], v[200:203], v[104:107]
	v_mfma_f32_16x16x32_bf16 v[104:107], v[188:191], v[204:207], v[104:107]
	v_mfma_f32_16x16x32_bf16 v[92:95], v[176:179], v[208:211], v[92:95]
	v_mfma_f32_16x16x32_bf16 v[92:95], v[180:183], v[212:215], v[92:95]
	v_mfma_f32_16x16x32_bf16 v[88:91], v[184:187], v[208:211], v[88:91]
	v_mfma_f32_16x16x32_bf16 v[88:91], v[188:191], v[212:215], v[88:91]
	v_mfma_f32_16x16x32_bf16 v[76:79], v[176:179], v[216:219], v[76:79]
	v_mfma_f32_16x16x32_bf16 v[76:79], v[180:183], v[220:223], v[76:79]
	v_mfma_f32_16x16x32_bf16 v[72:75], v[184:187], v[216:219], v[72:75]
	v_mfma_f32_16x16x32_bf16 v[72:75], v[188:191], v[220:223], v[72:75]
	s_setprio 0
	s_barrier
	s_add_i32 s0, s0, s47
	s_add_i32 m0, s0, 0xffffff80
	ds_read_b128 v[192:195], v161 offset:49152
	ds_read_b128 v[196:199], v161 offset:50176
	ds_read_b128 v[200:203], v161 offset:51200
	ds_read_b128 v[204:207], v161 offset:52224
	ds_read_b128 v[208:211], v161 offset:53248
	ds_read_b128 v[212:215], v161 offset:54272
	ds_read_b128 v[216:219], v161 offset:55296
	ds_read_b128 v[220:223], v161 offset:56320
	global_load_lds_dwordx4 v142, s[56:57] offset:128
	s_add_i32 m0, s0, 0x1f80
	s_add_i32 s0, s76, s47
	global_load_lds_dwordx4 v146, s[56:57] offset:128
	s_add_u32 s56, s56, 0x100080
	s_addc_u32 s57, s57, 0
	s_mov_b32 m0, s0
	s_nop 0
	global_load_lds_dwordx4 v142, s[56:57]
	s_add_i32 m0, s0, 0x2000
	s_nop 0
	global_load_lds_dwordx4 v146, s[56:57]
	s_add_i32 m0, s62, 0xffffff80
	s_nop 0
	global_load_lds_dwordx4 v140, s[58:59] offset:128
	s_add_i32 m0, s63, 0xffffff80
	s_nop 0
	global_load_lds_dwordx4 v144, s[58:59] offset:128
	s_waitcnt vmcnt(8)
	s_waitcnt lgkmcnt(0)
	s_setprio 1
	s_barrier
	v_mfma_f32_16x16x32_bf16 v[68:71], v[132:135], v[192:195], v[68:71]
	v_mfma_f32_16x16x32_bf16 v[68:71], v[164:167], v[196:199], v[68:71]
	v_mfma_f32_16x16x32_bf16 v[64:67], v[168:171], v[192:195], v[64:67]
	v_mfma_f32_16x16x32_bf16 v[64:67], v[172:175], v[196:199], v[64:67]
	v_mfma_f32_16x16x32_bf16 v[52:55], v[132:135], v[200:203], v[52:55]
	v_mfma_f32_16x16x32_bf16 v[52:55], v[164:167], v[204:207], v[52:55]
	v_mfma_f32_16x16x32_bf16 v[48:51], v[168:171], v[200:203], v[48:51]
	v_mfma_f32_16x16x32_bf16 v[48:51], v[172:175], v[204:207], v[48:51]
	v_mfma_f32_16x16x32_bf16 v[36:39], v[132:135], v[208:211], v[36:39]
	v_mfma_f32_16x16x32_bf16 v[36:39], v[164:167], v[212:215], v[36:39]
	v_mfma_f32_16x16x32_bf16 v[32:35], v[168:171], v[208:211], v[32:35]
	v_mfma_f32_16x16x32_bf16 v[32:35], v[172:175], v[212:215], v[32:35]
	v_mfma_f32_16x16x32_bf16 v[20:23], v[132:135], v[216:219], v[20:23]
	v_mfma_f32_16x16x32_bf16 v[20:23], v[164:167], v[220:223], v[20:23]
	v_mfma_f32_16x16x32_bf16 v[16:19], v[168:171], v[216:219], v[16:19]
	v_mfma_f32_16x16x32_bf16 v[16:19], v[172:175], v[220:223], v[16:19]
	s_setprio 0
	s_setprio 1
	v_mfma_f32_16x16x32_bf16 v[60:63], v[176:179], v[192:195], v[60:63]
	v_mfma_f32_16x16x32_bf16 v[60:63], v[180:183], v[196:199], v[60:63]
	v_mfma_f32_16x16x32_bf16 v[56:59], v[184:187], v[192:195], v[56:59]
	v_mfma_f32_16x16x32_bf16 v[56:59], v[188:191], v[196:199], v[56:59]
	v_mfma_f32_16x16x32_bf16 v[44:47], v[176:179], v[200:203], v[44:47]
	v_mfma_f32_16x16x32_bf16 v[44:47], v[180:183], v[204:207], v[44:47]
	v_mfma_f32_16x16x32_bf16 v[40:43], v[184:187], v[200:203], v[40:43]
	v_mfma_f32_16x16x32_bf16 v[40:43], v[188:191], v[204:207], v[40:43]
	v_mfma_f32_16x16x32_bf16 v[28:31], v[176:179], v[208:211], v[28:31]
	v_mfma_f32_16x16x32_bf16 v[28:31], v[180:183], v[212:215], v[28:31]
	v_mfma_f32_16x16x32_bf16 v[24:27], v[184:187], v[208:211], v[24:27]
	v_mfma_f32_16x16x32_bf16 v[24:27], v[188:191], v[212:215], v[24:27]
	v_mfma_f32_16x16x32_bf16 v[12:15], v[176:179], v[216:219], v[12:15]
	v_mfma_f32_16x16x32_bf16 v[12:15], v[180:183], v[220:223], v[12:15]
	v_mfma_f32_16x16x32_bf16 v[8:11], v[184:187], v[216:219], v[8:11]
	v_mfma_f32_16x16x32_bf16 v[8:11], v[188:191], v[220:223], v[8:11]
	s_setprio 0
	s_barrier
	s_add_i32 s75, s75, 2
	s_add_u32 s54, s54, 0x100
	s_addc_u32 s55, s55, 0
	s_add_u32 s73, s73, 0x100
	s_addc_u32 s74, s74, 0
	s_cmp_gt_u32 s75, 61
	s_cbranch_scc0 .LBB0_1503
	s_and_b64 vcc, exec, s[26:27]
	s_cbranch_vccz .LBB0_1506
	s_barrier

.LBB0_1672:
	ds_read_b128 v[132:135], v193
	ds_read_b128 v[136:139], v193 offset:1024
	ds_read_b128 v[140:143], v193 offset:2048
	ds_read_b128 v[144:147], v193 offset:3072
	ds_read_b128 v[148:151], v194
	ds_read_b128 v[152:155], v194 offset:1024
	ds_read_b128 v[172:175], v194 offset:2048
	ds_read_b128 v[176:179], v194 offset:3072
	s_add_u32 s0, s30, 0xffd50080
	s_addc_u32 s42, s31, -1
	s_cmpk_eq_i32 s66, 0xa8
	s_cselect_b32 s51, s7, s42
	s_cselect_b32 s50, s6, s0
	s_cselect_b32 s43, s29, s65
	s_cselect_b32 s42, s28, s64
	s_add_i32 m0, s46, 0xc000
	ds_read_b128 v[180:183], v195
	ds_read_b128 v[198:201], v195 offset:1024
	ds_read_b128 v[202:205], v195 offset:2048
	ds_read_b128 v[206:209], v195 offset:3072
	ds_read_b128 v[210:213], v195 offset:4096
	ds_read_b128 v[214:217], v195 offset:5120
	ds_read_b128 v[218:221], v195 offset:6144
	ds_read_b128 v[222:225], v195 offset:7168
	global_load_lds_dwordx4 v164, s[30:31]
	s_add_i32 m0, s46, 0xe000
	s_nop 0
	global_load_lds_dwordx4 v166, s[30:31]
	s_waitcnt vmcnt(8)
	s_waitcnt lgkmcnt(0)
	s_setprio 1
	s_barrier
	v_mfma_f32_16x16x32_bf16 v[128:131], v[132:135], v[180:183], v[128:131]
	v_mfma_f32_16x16x32_bf16 v[128:131], v[136:139], v[198:201], v[128:131]
	v_mfma_f32_16x16x32_bf16 v[124:127], v[140:143], v[180:183], v[124:127]
	v_mfma_f32_16x16x32_bf16 v[124:127], v[144:147], v[198:201], v[124:127]
	v_mfma_f32_16x16x32_bf16 v[112:115], v[132:135], v[202:205], v[112:115]
	v_mfma_f32_16x16x32_bf16 v[112:115], v[136:139], v[206:209], v[112:115]
	v_mfma_f32_16x16x32_bf16 v[108:111], v[140:143], v[202:205], v[108:111]
	v_mfma_f32_16x16x32_bf16 v[108:111], v[144:147], v[206:209], v[108:111]
	v_mfma_f32_16x16x32_bf16 v[96:99], v[132:135], v[210:213], v[96:99]
	v_mfma_f32_16x16x32_bf16 v[96:99], v[136:139], v[214:217], v[96:99]
	v_mfma_f32_16x16x32_bf16 v[92:95], v[140:143], v[210:213], v[92:95]
	v_mfma_f32_16x16x32_bf16 v[92:95], v[144:147], v[214:217], v[92:95]
	v_mfma_f32_16x16x32_bf16 v[80:83], v[132:135], v[218:221], v[80:83]
	v_mfma_f32_16x16x32_bf16 v[80:83], v[136:139], v[222:225], v[80:83]
	v_mfma_f32_16x16x32_bf16 v[76:79], v[140:143], v[218:221], v[76:79]
	v_mfma_f32_16x16x32_bf16 v[76:79], v[144:147], v[222:225], v[76:79]
	s_setprio 0
	s_setprio 1
	v_mfma_f32_16x16x32_bf16 v[120:123], v[148:151], v[180:183], v[120:123]
	v_mfma_f32_16x16x32_bf16 v[120:123], v[152:155], v[198:201], v[120:123]
	v_mfma_f32_16x16x32_bf16 v[116:119], v[172:175], v[180:183], v[116:119]
	v_mfma_f32_16x16x32_bf16 v[116:119], v[176:179], v[198:201], v[116:119]
	v_mfma_f32_16x16x32_bf16 v[104:107], v[148:151], v[202:205], v[104:107]
	v_mfma_f32_16x16x32_bf16 v[104:107], v[152:155], v[206:209], v[104:107]
	v_mfma_f32_16x16x32_bf16 v[100:103], v[172:175], v[202:205], v[100:103]
	v_mfma_f32_16x16x32_bf16 v[100:103], v[176:179], v[206:209], v[100:103]
	v_mfma_f32_16x16x32_bf16 v[88:91], v[148:151], v[210:213], v[88:91]
	v_mfma_f32_16x16x32_bf16 v[88:91], v[152:155], v[214:217], v[88:91]
	v_mfma_f32_16x16x32_bf16 v[84:87], v[172:175], v[210:213], v[84:87]
	v_mfma_f32_16x16x32_bf16 v[84:87], v[176:179], v[214:217], v[84:87]
	v_mfma_f32_16x16x32_bf16 v[72:75], v[148:151], v[218:221], v[72:75]
	v_mfma_f32_16x16x32_bf16 v[72:75], v[152:155], v[222:225], v[72:75]
	v_mfma_f32_16x16x32_bf16 v[68:71], v[172:175], v[218:221], v[68:71]
	v_mfma_f32_16x16x32_bf16 v[68:71], v[176:179], v[222:225], v[68:71]
	s_setprio 0
	s_barrier
	s_add_i32 s0, s57, s45
	s_mov_b32 m0, s0
	ds_read_b128 v[180:183], v195 offset:16384
	ds_read_b128 v[198:201], v195 offset:17408
	ds_read_b128 v[202:205], v195 offset:18432
	ds_read_b128 v[206:209], v195 offset:19456
	ds_read_b128 v[210:213], v195 offset:20480
	ds_read_b128 v[214:217], v195 offset:21504
	ds_read_b128 v[218:221], v195 offset:22528
	ds_read_b128 v[222:225], v195 offset:23552
	global_load_lds_dwordx4 v158, s[42:43]
	s_add_i32 m0, s0, 0x2000
	s_add_u32 s70, s42, 0x2b0000
	s_addc_u32 s71, s43, 0
	s_add_i32 s0, s58, s45
	global_load_lds_dwordx4 v162, s[42:43]
	s_mov_b32 m0, s0
	s_nop 0
	global_load_lds_dwordx4 v158, s[70:71]
	s_add_i32 m0, s0, 0x2000
	s_nop 0
	global_load_lds_dwordx4 v162, s[70:71]
	s_mov_b32 m0, s46
	s_nop 0
	global_load_lds_dwordx4 v156, s[50:51]
	s_mov_b32 m0, s47
	s_nop 0
	global_load_lds_dwordx4 v160, s[50:51]
	s_waitcnt vmcnt(8)
	s_waitcnt lgkmcnt(0)
	s_setprio 1
	s_barrier
	v_mfma_f32_16x16x32_bf16 v[64:67], v[132:135], v[180:183], v[64:67]
	v_mfma_f32_16x16x32_bf16 v[64:67], v[136:139], v[198:201], v[64:67]
	v_mfma_f32_16x16x32_bf16 v[60:63], v[140:143], v[180:183], v[60:63]
	v_mfma_f32_16x16x32_bf16 v[60:63], v[144:147], v[198:201], v[60:63]
	v_mfma_f32_16x16x32_bf16 v[48:51], v[132:135], v[202:205], v[48:51]
	v_mfma_f32_16x16x32_bf16 v[48:51], v[136:139], v[206:209], v[48:51]
	v_mfma_f32_16x16x32_bf16 v[44:47], v[140:143], v[202:205], v[44:47]
	v_mfma_f32_16x16x32_bf16 v[44:47], v[144:147], v[206:209], v[44:47]
	v_mfma_f32_16x16x32_bf16 v[32:35], v[132:135], v[210:213], v[32:35]
	v_mfma_f32_16x16x32_bf16 v[32:35], v[136:139], v[214:217], v[32:35]
	v_mfma_f32_16x16x32_bf16 v[28:31], v[140:143], v[210:213], v[28:31]
	v_mfma_f32_16x16x32_bf16 v[28:31], v[144:147], v[214:217], v[28:31]
	v_mfma_f32_16x16x32_bf16 v[16:19], v[132:135], v[218:221], v[16:19]
	v_mfma_f32_16x16x32_bf16 v[16:19], v[136:139], v[222:225], v[16:19]
	v_mfma_f32_16x16x32_bf16 v[12:15], v[140:143], v[218:221], v[12:15]
	v_mfma_f32_16x16x32_bf16 v[12:15], v[144:147], v[222:225], v[12:15]
	s_setprio 0
	s_setprio 1
	v_mfma_f32_16x16x32_bf16 v[56:59], v[148:151], v[180:183], v[56:59]
	v_mfma_f32_16x16x32_bf16 v[56:59], v[152:155], v[198:201], v[56:59]
	v_mfma_f32_16x16x32_bf16 v[52:55], v[172:175], v[180:183], v[52:55]
	v_mfma_f32_16x16x32_bf16 v[52:55], v[176:179], v[198:201], v[52:55]
	v_mfma_f32_16x16x32_bf16 v[40:43], v[148:151], v[202:205], v[40:43]
	v_mfma_f32_16x16x32_bf16 v[40:43], v[152:155], v[206:209], v[40:43]
	v_mfma_f32_16x16x32_bf16 v[36:39], v[172:175], v[202:205], v[36:39]
	v_mfma_f32_16x16x32_bf16 v[36:39], v[176:179], v[206:209], v[36:39]
	v_mfma_f32_16x16x32_bf16 v[24:27], v[148:151], v[210:213], v[24:27]
	v_mfma_f32_16x16x32_bf16 v[24:27], v[152:155], v[214:217], v[24:27]
	v_mfma_f32_16x16x32_bf16 v[20:23], v[172:175], v[210:213], v[20:23]
	v_mfma_f32_16x16x32_bf16 v[20:23], v[176:179], v[214:217], v[20:23]
	v_mfma_f32_16x16x32_bf16 v[8:11], v[148:151], v[218:221], v[8:11]
	v_mfma_f32_16x16x32_bf16 v[8:11], v[152:155], v[222:225], v[8:11]
	v_mfma_f32_16x16x32_bf16 v[4:7], v[172:175], v[218:221], v[4:7]
	v_mfma_f32_16x16x32_bf16 v[4:7], v[176:179], v[222:225], v[4:7]
	s_setprio 0
	s_barrier
	s_add_i32 s0, 0, 0x18000
	s_add_i32 s67, 0, 0x1c000
	v_add_u32_e32 v144, s0, v191
	v_add_u32_e32 v176, s67, v191
	ds_read_b128 v[132:135], v144
	ds_read_b128 v[136:139], v144 offset:1024
	ds_read_b128 v[140:143], v144 offset:2048
	ds_read_b128 v[144:147], v144 offset:3072
	ds_read_b128 v[148:151], v176
	ds_read_b128 v[152:155], v176 offset:1024
	ds_read_b128 v[172:175], v176 offset:2048
	ds_read_b128 v[176:179], v176 offset:3072
	s_add_u32 s98, s50, 0x2b0000
	s_addc_u32 s99, s51, 0
	s_mov_b32 m0, s48
	ds_read_b128 v[180:183], v195 offset:32768
	ds_read_b128 v[198:201], v195 offset:33792
	ds_read_b128 v[202:205], v195 offset:34816
	ds_read_b128 v[206:209], v195 offset:35840
	ds_read_b128 v[210:213], v195 offset:36864
	ds_read_b128 v[214:217], v195 offset:37888
	ds_read_b128 v[218:221], v195 offset:38912
	ds_read_b128 v[222:225], v195 offset:39936
	global_load_lds_dwordx4 v156, s[98:99]
	s_mov_b32 m0, s49
	s_nop 0
	global_load_lds_dwordx4 v160, s[98:99]
	s_waitcnt vmcnt(8)
	s_waitcnt lgkmcnt(0)
	s_setprio 1
	s_barrier
	v_mfma_f32_16x16x32_bf16 v[128:131], v[132:135], v[180:183], v[128:131]
	v_mfma_f32_16x16x32_bf16 v[128:131], v[136:139], v[198:201], v[128:131]
	v_mfma_f32_16x16x32_bf16 v[124:127], v[140:143], v[180:183], v[124:127]
	v_mfma_f32_16x16x32_bf16 v[124:127], v[144:147], v[198:201], v[124:127]
	v_mfma_f32_16x16x32_bf16 v[112:115], v[132:135], v[202:205], v[112:115]
	v_mfma_f32_16x16x32_bf16 v[112:115], v[136:139], v[206:209], v[112:115]
	v_mfma_f32_16x16x32_bf16 v[108:111], v[140:143], v[202:205], v[108:111]
	v_mfma_f32_16x16x32_bf16 v[108:111], v[144:147], v[206:209], v[108:111]
	v_mfma_f32_16x16x32_bf16 v[96:99], v[132:135], v[210:213], v[96:99]
	v_mfma_f32_16x16x32_bf16 v[96:99], v[136:139], v[214:217], v[96:99]
	v_mfma_f32_16x16x32_bf16 v[92:95], v[140:143], v[210:213], v[92:95]
	v_mfma_f32_16x16x32_bf16 v[92:95], v[144:147], v[214:217], v[92:95]
	v_mfma_f32_16x16x32_bf16 v[80:83], v[132:135], v[218:221], v[80:83]
	v_mfma_f32_16x16x32_bf16 v[80:83], v[136:139], v[222:225], v[80:83]
	v_mfma_f32_16x16x32_bf16 v[76:79], v[140:143], v[218:221], v[76:79]
	v_mfma_f32_16x16x32_bf16 v[76:79], v[144:147], v[222:225], v[76:79]
	s_setprio 0
	s_setprio 1
	v_mfma_f32_16x16x32_bf16 v[120:123], v[148:151], v[180:183], v[120:123]
	v_mfma_f32_16x16x32_bf16 v[120:123], v[152:155], v[198:201], v[120:123]
	v_mfma_f32_16x16x32_bf16 v[116:119], v[172:175], v[180:183], v[116:119]
	v_mfma_f32_16x16x32_bf16 v[116:119], v[176:179], v[198:201], v[116:119]
	v_mfma_f32_16x16x32_bf16 v[104:107], v[148:151], v[202:205], v[104:107]
	v_mfma_f32_16x16x32_bf16 v[104:107], v[152:155], v[206:209], v[104:107]
	v_mfma_f32_16x16x32_bf16 v[100:103], v[172:175], v[202:205], v[100:103]
	v_mfma_f32_16x16x32_bf16 v[100:103], v[176:179], v[206:209], v[100:103]
	v_mfma_f32_16x16x32_bf16 v[88:91], v[148:151], v[210:213], v[88:91]
	v_mfma_f32_16x16x32_bf16 v[88:91], v[152:155], v[214:217], v[88:91]
	v_mfma_f32_16x16x32_bf16 v[84:87], v[172:175], v[210:213], v[84:87]
	v_mfma_f32_16x16x32_bf16 v[84:87], v[176:179], v[214:217], v[84:87]
	v_mfma_f32_16x16x32_bf16 v[72:75], v[148:151], v[218:221], v[72:75]
	v_mfma_f32_16x16x32_bf16 v[72:75], v[152:155], v[222:225], v[72:75]
	v_mfma_f32_16x16x32_bf16 v[68:71], v[172:175], v[218:221], v[68:71]
	v_mfma_f32_16x16x32_bf16 v[68:71], v[176:179], v[222:225], v[68:71]
	s_setprio 0
	s_barrier
	s_add_i32 s0, s0, s45
	s_add_i32 m0, s0, 0xffffff80
	ds_read_b128 v[180:183], v195 offset:49152
	ds_read_b128 v[198:201], v195 offset:50176
	ds_read_b128 v[202:205], v195 offset:51200
	ds_read_b128 v[206:209], v195 offset:52224
	ds_read_b128 v[210:213], v195 offset:53248
	ds_read_b128 v[214:217], v195 offset:54272
	ds_read_b128 v[218:221], v195 offset:55296
	ds_read_b128 v[222:225], v195 offset:56320
	global_load_lds_dwordx4 v158, s[42:43] offset:128
	s_add_i32 m0, s0, 0x1f80
	s_add_i32 s0, s67, s45
	global_load_lds_dwordx4 v162, s[42:43] offset:128
	s_add_u32 s42, s42, 0x2b0080
	s_addc_u32 s43, s43, 0
	s_mov_b32 m0, s0
	s_nop 0
	global_load_lds_dwordx4 v158, s[42:43]
	s_add_i32 m0, s0, 0x2000
	s_nop 0
	global_load_lds_dwordx4 v162, s[42:43]
	s_add_i32 m0, s55, 0xffffff80
	s_nop 0
	global_load_lds_dwordx4 v156, s[50:51] offset:128
	s_add_i32 m0, s56, 0xffffff80
	s_nop 0
	global_load_lds_dwordx4 v160, s[50:51] offset:128
	s_waitcnt vmcnt(8)
	s_waitcnt lgkmcnt(0)
	s_setprio 1
	s_barrier
	v_mfma_f32_16x16x32_bf16 v[64:67], v[132:135], v[180:183], v[64:67]
	v_mfma_f32_16x16x32_bf16 v[64:67], v[136:139], v[198:201], v[64:67]
	v_mfma_f32_16x16x32_bf16 v[60:63], v[140:143], v[180:183], v[60:63]
	v_mfma_f32_16x16x32_bf16 v[60:63], v[144:147], v[198:201], v[60:63]
	v_mfma_f32_16x16x32_bf16 v[48:51], v[132:135], v[202:205], v[48:51]
	v_mfma_f32_16x16x32_bf16 v[48:51], v[136:139], v[206:209], v[48:51]
	v_mfma_f32_16x16x32_bf16 v[44:47], v[140:143], v[202:205], v[44:47]
	v_mfma_f32_16x16x32_bf16 v[44:47], v[144:147], v[206:209], v[44:47]
	v_mfma_f32_16x16x32_bf16 v[32:35], v[132:135], v[210:213], v[32:35]
	v_mfma_f32_16x16x32_bf16 v[32:35], v[136:139], v[214:217], v[32:35]
	v_mfma_f32_16x16x32_bf16 v[28:31], v[140:143], v[210:213], v[28:31]
	v_mfma_f32_16x16x32_bf16 v[28:31], v[144:147], v[214:217], v[28:31]
	v_mfma_f32_16x16x32_bf16 v[16:19], v[132:135], v[218:221], v[16:19]
	v_mfma_f32_16x16x32_bf16 v[16:19], v[136:139], v[222:225], v[16:19]
	v_mfma_f32_16x16x32_bf16 v[12:15], v[140:143], v[218:221], v[12:15]
	v_mfma_f32_16x16x32_bf16 v[12:15], v[144:147], v[222:225], v[12:15]
	s_setprio 0
	s_setprio 1
	v_mfma_f32_16x16x32_bf16 v[56:59], v[148:151], v[180:183], v[56:59]
	v_mfma_f32_16x16x32_bf16 v[56:59], v[152:155], v[198:201], v[56:59]
	v_mfma_f32_16x16x32_bf16 v[52:55], v[172:175], v[180:183], v[52:55]
	v_mfma_f32_16x16x32_bf16 v[52:55], v[176:179], v[198:201], v[52:55]
	v_mfma_f32_16x16x32_bf16 v[40:43], v[148:151], v[202:205], v[40:43]
	v_mfma_f32_16x16x32_bf16 v[40:43], v[152:155], v[206:209], v[40:43]
	v_mfma_f32_16x16x32_bf16 v[36:39], v[172:175], v[202:205], v[36:39]
	v_mfma_f32_16x16x32_bf16 v[36:39], v[176:179], v[206:209], v[36:39]
	v_mfma_f32_16x16x32_bf16 v[24:27], v[148:151], v[210:213], v[24:27]
	v_mfma_f32_16x16x32_bf16 v[24:27], v[152:155], v[214:217], v[24:27]
	v_mfma_f32_16x16x32_bf16 v[20:23], v[172:175], v[210:213], v[20:23]
	v_mfma_f32_16x16x32_bf16 v[20:23], v[176:179], v[214:217], v[20:23]
	v_mfma_f32_16x16x32_bf16 v[8:11], v[148:151], v[218:221], v[8:11]
	v_mfma_f32_16x16x32_bf16 v[8:11], v[152:155], v[222:225], v[8:11]
	v_mfma_f32_16x16x32_bf16 v[4:7], v[172:175], v[218:221], v[4:7]
	v_mfma_f32_16x16x32_bf16 v[4:7], v[176:179], v[222:225], v[4:7]
	s_setprio 0
	s_barrier
	s_add_i32 s66, s66, 2
	s_add_u32 s30, s30, 0x100
	s_addc_u32 s31, s31, 0
	s_add_u32 s64, s64, 0x100
	s_addc_u32 s65, s65, 0
	s_cmpk_gt_u32 s66, 0xa9
	s_cbranch_scc0 .LBB0_1672
	s_and_b64 vcc, exec, s[24:25]
	s_cbranch_vccz .LBB0_1675
	s_barrier

.LBB0_1703:
	ds_read_b128 v[136:139], v196
	ds_read_b128 v[140:143], v196 offset:1024
	ds_read_b128 v[144:147], v196 offset:2048
	ds_read_b128 v[148:151], v196 offset:3072
	ds_read_b128 v[152:155], v197
	ds_read_b128 v[176:179], v197 offset:1024
	ds_read_b128 v[180:183], v197 offset:2048
	ds_read_b128 v[184:187], v197 offset:3072
	s_add_u32 s8, s6, 0x100
	s_addc_u32 s9, s7, 0
	s_add_u32 s0, s65, s6
	s_addc_u32 s40, s66, s7
	s_cmpk_eq_i32 s67, 0xa8
	s_cselect_b32 s43, s50, s40
	s_cselect_b32 s40, 0, s8
	s_cselect_b32 s42, s51, s0
	s_cselect_b32 s0, 0, s9
	s_add_u32 s40, s16, s40
	s_addc_u32 s41, s17, s0
	s_mov_b32 m0, s58
	v_lshl_add_u64 v[226:227], v[132:133], 0, s[6:7]
	ds_read_b128 v[188:191], v198
	ds_read_b128 v[192:195], v198 offset:1024
	ds_read_b128 v[202:205], v198 offset:2048
	ds_read_b128 v[206:209], v198 offset:3072
	ds_read_b128 v[210:213], v198 offset:4096
	ds_read_b128 v[214:217], v198 offset:5120
	ds_read_b128 v[218:221], v198 offset:6144
	ds_read_b128 v[222:225], v198 offset:7168
	global_load_lds_dwordx4 v[226:227], off
	v_lshl_add_u64 v[226:227], v[134:135], 0, s[6:7]
	s_mov_b32 m0, s59
	s_nop 0
	global_load_lds_dwordx4 v[226:227], off
	s_waitcnt vmcnt(8)
	s_waitcnt lgkmcnt(0)
	s_setprio 1
	s_barrier
	v_mfma_f32_16x16x32_bf16 v[128:131], v[136:139], v[188:191], v[128:131]
	v_mfma_f32_16x16x32_bf16 v[128:131], v[140:143], v[192:195], v[128:131]
	v_mfma_f32_16x16x32_bf16 v[124:127], v[144:147], v[188:191], v[124:127]
	v_mfma_f32_16x16x32_bf16 v[124:127], v[148:151], v[192:195], v[124:127]
	v_mfma_f32_16x16x32_bf16 v[112:115], v[136:139], v[202:205], v[112:115]
	v_mfma_f32_16x16x32_bf16 v[112:115], v[140:143], v[206:209], v[112:115]
	v_mfma_f32_16x16x32_bf16 v[108:111], v[144:147], v[202:205], v[108:111]
	v_mfma_f32_16x16x32_bf16 v[108:111], v[148:151], v[206:209], v[108:111]
	v_mfma_f32_16x16x32_bf16 v[96:99], v[136:139], v[210:213], v[96:99]
	v_mfma_f32_16x16x32_bf16 v[96:99], v[140:143], v[214:217], v[96:99]
	v_mfma_f32_16x16x32_bf16 v[92:95], v[144:147], v[210:213], v[92:95]
	v_mfma_f32_16x16x32_bf16 v[92:95], v[148:151], v[214:217], v[92:95]
	v_mfma_f32_16x16x32_bf16 v[80:83], v[136:139], v[218:221], v[80:83]
	v_mfma_f32_16x16x32_bf16 v[80:83], v[140:143], v[222:225], v[80:83]
	v_mfma_f32_16x16x32_bf16 v[76:79], v[144:147], v[218:221], v[76:79]
	v_mfma_f32_16x16x32_bf16 v[76:79], v[148:151], v[222:225], v[76:79]
	s_setprio 0
	s_setprio 1
	v_mfma_f32_16x16x32_bf16 v[120:123], v[152:155], v[188:191], v[120:123]
	v_mfma_f32_16x16x32_bf16 v[120:123], v[176:179], v[192:195], v[120:123]
	v_mfma_f32_16x16x32_bf16 v[116:119], v[180:183], v[188:191], v[116:119]
	v_mfma_f32_16x16x32_bf16 v[116:119], v[184:187], v[192:195], v[116:119]
	v_mfma_f32_16x16x32_bf16 v[104:107], v[152:155], v[202:205], v[104:107]
	v_mfma_f32_16x16x32_bf16 v[104:107], v[176:179], v[206:209], v[104:107]
	v_mfma_f32_16x16x32_bf16 v[100:103], v[180:183], v[202:205], v[100:103]
	v_mfma_f32_16x16x32_bf16 v[100:103], v[184:187], v[206:209], v[100:103]
	v_mfma_f32_16x16x32_bf16 v[88:91], v[152:155], v[210:213], v[88:91]
	v_mfma_f32_16x16x32_bf16 v[88:91], v[176:179], v[214:217], v[88:91]
	v_mfma_f32_16x16x32_bf16 v[84:87], v[180:183], v[210:213], v[84:87]
	v_mfma_f32_16x16x32_bf16 v[84:87], v[184:187], v[214:217], v[84:87]
	v_mfma_f32_16x16x32_bf16 v[72:75], v[152:155], v[218:221], v[72:75]
	v_mfma_f32_16x16x32_bf16 v[72:75], v[176:179], v[222:225], v[72:75]
	v_mfma_f32_16x16x32_bf16 v[68:71], v[180:183], v[218:221], v[68:71]
	v_mfma_f32_16x16x32_bf16 v[68:71], v[184:187], v[222:225], v[68:71]
	s_setprio 0
	s_barrier
	s_mov_b32 m0, s60
	v_lshl_add_u64 v[226:227], s[40:41], 0, v[158:159]
	s_add_u32 s6, s40, 0x2b0000
	ds_read_b128 v[188:191], v198 offset:16384
	ds_read_b128 v[192:195], v198 offset:17408
	ds_read_b128 v[202:205], v198 offset:18432
	ds_read_b128 v[206:209], v198 offset:19456
	ds_read_b128 v[210:213], v198 offset:20480
	ds_read_b128 v[214:217], v198 offset:21504
	ds_read_b128 v[218:221], v198 offset:22528
	ds_read_b128 v[222:225], v198 offset:23552
	global_load_lds_dwordx4 v[226:227], off
	v_lshl_add_u64 v[228:229], s[40:41], 0, v[162:163]
	s_mov_b32 m0, s61
	s_addc_u32 s7, s41, 0
	global_load_lds_dwordx4 v[228:229], off
	v_lshl_add_u64 v[230:231], s[6:7], 0, v[158:159]
	s_mov_b32 m0, s62
	v_lshl_add_u64 v[232:233], s[42:43], 0, v[160:161]
	global_load_lds_dwordx4 v[230:231], off
	v_lshl_add_u64 v[230:231], s[6:7], 0, v[162:163]
	s_mov_b32 m0, s63
	s_nop 0
	global_load_lds_dwordx4 v[230:231], off
	v_lshl_add_u64 v[230:231], s[42:43], 0, v[156:157]
	s_mov_b32 m0, s46
	s_nop 0
	global_load_lds_dwordx4 v[230:231], off
	s_mov_b32 m0, s47
	s_nop 0
	global_load_lds_dwordx4 v[232:233], off
	s_waitcnt vmcnt(8)
	s_waitcnt lgkmcnt(0)
	s_setprio 1
	s_barrier
	v_mfma_f32_16x16x32_bf16 v[64:67], v[136:139], v[188:191], v[64:67]
	v_mfma_f32_16x16x32_bf16 v[64:67], v[140:143], v[192:195], v[64:67]
	v_mfma_f32_16x16x32_bf16 v[60:63], v[144:147], v[188:191], v[60:63]
	v_mfma_f32_16x16x32_bf16 v[60:63], v[148:151], v[192:195], v[60:63]
	v_mfma_f32_16x16x32_bf16 v[48:51], v[136:139], v[202:205], v[48:51]
	v_mfma_f32_16x16x32_bf16 v[48:51], v[140:143], v[206:209], v[48:51]
	v_mfma_f32_16x16x32_bf16 v[44:47], v[144:147], v[202:205], v[44:47]
	v_mfma_f32_16x16x32_bf16 v[44:47], v[148:151], v[206:209], v[44:47]
	v_mfma_f32_16x16x32_bf16 v[32:35], v[136:139], v[210:213], v[32:35]
	v_mfma_f32_16x16x32_bf16 v[32:35], v[140:143], v[214:217], v[32:35]
	v_mfma_f32_16x16x32_bf16 v[28:31], v[144:147], v[210:213], v[28:31]
	v_mfma_f32_16x16x32_bf16 v[28:31], v[148:151], v[214:217], v[28:31]
	v_mfma_f32_16x16x32_bf16 v[16:19], v[136:139], v[218:221], v[16:19]
	v_mfma_f32_16x16x32_bf16 v[16:19], v[140:143], v[222:225], v[16:19]
	v_mfma_f32_16x16x32_bf16 v[12:15], v[144:147], v[218:221], v[12:15]
	v_mfma_f32_16x16x32_bf16 v[12:15], v[148:151], v[222:225], v[12:15]
	s_setprio 0
	s_setprio 1
	v_mfma_f32_16x16x32_bf16 v[56:59], v[152:155], v[188:191], v[56:59]
	v_mfma_f32_16x16x32_bf16 v[56:59], v[176:179], v[192:195], v[56:59]
	v_mfma_f32_16x16x32_bf16 v[52:55], v[180:183], v[188:191], v[52:55]
	v_mfma_f32_16x16x32_bf16 v[52:55], v[184:187], v[192:195], v[52:55]
	v_mfma_f32_16x16x32_bf16 v[40:43], v[152:155], v[202:205], v[40:43]
	v_mfma_f32_16x16x32_bf16 v[40:43], v[176:179], v[206:209], v[40:43]
	v_mfma_f32_16x16x32_bf16 v[36:39], v[180:183], v[202:205], v[36:39]
	v_mfma_f32_16x16x32_bf16 v[36:39], v[184:187], v[206:209], v[36:39]
	v_mfma_f32_16x16x32_bf16 v[24:27], v[152:155], v[210:213], v[24:27]
	v_mfma_f32_16x16x32_bf16 v[24:27], v[176:179], v[214:217], v[24:27]
	v_mfma_f32_16x16x32_bf16 v[20:23], v[180:183], v[210:213], v[20:23]
	v_mfma_f32_16x16x32_bf16 v[20:23], v[184:187], v[214:217], v[20:23]
	v_mfma_f32_16x16x32_bf16 v[8:11], v[152:155], v[218:221], v[8:11]
	v_mfma_f32_16x16x32_bf16 v[8:11], v[176:179], v[222:225], v[8:11]
	v_mfma_f32_16x16x32_bf16 v[4:7], v[180:183], v[218:221], v[4:7]
	v_mfma_f32_16x16x32_bf16 v[4:7], v[184:187], v[222:225], v[4:7]
	s_setprio 0
	s_barrier
	s_add_i32 s0, 0, 0x18000
	s_add_i32 s68, 0, 0x1c000
	v_add_u32_e32 v148, s0, v3
	v_add_u32_e32 v170, s68, v3
	ds_read_b128 v[136:139], v148
	ds_read_b128 v[140:143], v148 offset:1024
	ds_read_b128 v[144:147], v148 offset:2048
	ds_read_b128 v[148:151], v148 offset:3072
	ds_read_b128 v[152:155], v170
	ds_read_b128 v[176:179], v170 offset:1024
	ds_read_b128 v[180:183], v170 offset:2048
	ds_read_b128 v[184:187], v170 offset:3072
	s_add_u32 s6, s42, 0x2b0000
	s_addc_u32 s7, s43, 0
	s_mov_b32 m0, s48
	v_lshl_add_u64 v[234:235], s[6:7], 0, v[156:157]
	ds_read_b128 v[188:191], v198 offset:32768
	ds_read_b128 v[192:195], v198 offset:33792
	ds_read_b128 v[202:205], v198 offset:34816
	ds_read_b128 v[206:209], v198 offset:35840
	ds_read_b128 v[210:213], v198 offset:36864
	ds_read_b128 v[214:217], v198 offset:37888
	ds_read_b128 v[218:221], v198 offset:38912
	ds_read_b128 v[222:225], v198 offset:39936
	global_load_lds_dwordx4 v[234:235], off
	v_lshl_add_u64 v[234:235], s[6:7], 0, v[160:161]
	s_mov_b32 m0, s49
	s_nop 0
	global_load_lds_dwordx4 v[234:235], off
	s_waitcnt vmcnt(8)
	s_waitcnt lgkmcnt(0)
	s_setprio 1
	s_barrier
	v_mfma_f32_16x16x32_bf16 v[128:131], v[136:139], v[188:191], v[128:131]
	v_mfma_f32_16x16x32_bf16 v[128:131], v[140:143], v[192:195], v[128:131]
	v_mfma_f32_16x16x32_bf16 v[124:127], v[144:147], v[188:191], v[124:127]
	v_mfma_f32_16x16x32_bf16 v[124:127], v[148:151], v[192:195], v[124:127]
	v_mfma_f32_16x16x32_bf16 v[112:115], v[136:139], v[202:205], v[112:115]
	v_mfma_f32_16x16x32_bf16 v[112:115], v[140:143], v[206:209], v[112:115]
	v_mfma_f32_16x16x32_bf16 v[108:111], v[144:147], v[202:205], v[108:111]
	v_mfma_f32_16x16x32_bf16 v[108:111], v[148:151], v[206:209], v[108:111]
	v_mfma_f32_16x16x32_bf16 v[96:99], v[136:139], v[210:213], v[96:99]
	v_mfma_f32_16x16x32_bf16 v[96:99], v[140:143], v[214:217], v[96:99]
	v_mfma_f32_16x16x32_bf16 v[92:95], v[144:147], v[210:213], v[92:95]
	v_mfma_f32_16x16x32_bf16 v[92:95], v[148:151], v[214:217], v[92:95]
	v_mfma_f32_16x16x32_bf16 v[80:83], v[136:139], v[218:221], v[80:83]
	v_mfma_f32_16x16x32_bf16 v[80:83], v[140:143], v[222:225], v[80:83]
	v_mfma_f32_16x16x32_bf16 v[76:79], v[144:147], v[218:221], v[76:79]
	v_mfma_f32_16x16x32_bf16 v[76:79], v[148:151], v[222:225], v[76:79]
	s_setprio 0
	s_setprio 1
	v_mfma_f32_16x16x32_bf16 v[120:123], v[152:155], v[188:191], v[120:123]
	v_mfma_f32_16x16x32_bf16 v[120:123], v[176:179], v[192:195], v[120:123]
	v_mfma_f32_16x16x32_bf16 v[116:119], v[180:183], v[188:191], v[116:119]
	v_mfma_f32_16x16x32_bf16 v[116:119], v[184:187], v[192:195], v[116:119]
	v_mfma_f32_16x16x32_bf16 v[104:107], v[152:155], v[202:205], v[104:107]
	v_mfma_f32_16x16x32_bf16 v[104:107], v[176:179], v[206:209], v[104:107]
	v_mfma_f32_16x16x32_bf16 v[100:103], v[180:183], v[202:205], v[100:103]
	v_mfma_f32_16x16x32_bf16 v[100:103], v[184:187], v[206:209], v[100:103]
	v_mfma_f32_16x16x32_bf16 v[88:91], v[152:155], v[210:213], v[88:91]
	v_mfma_f32_16x16x32_bf16 v[88:91], v[176:179], v[214:217], v[88:91]
	v_mfma_f32_16x16x32_bf16 v[84:87], v[180:183], v[210:213], v[84:87]
	v_mfma_f32_16x16x32_bf16 v[84:87], v[184:187], v[214:217], v[84:87]
	v_mfma_f32_16x16x32_bf16 v[72:75], v[152:155], v[218:221], v[72:75]
	v_mfma_f32_16x16x32_bf16 v[72:75], v[176:179], v[222:225], v[72:75]
	v_mfma_f32_16x16x32_bf16 v[68:71], v[180:183], v[218:221], v[68:71]
	v_mfma_f32_16x16x32_bf16 v[68:71], v[184:187], v[222:225], v[68:71]
	s_setprio 0
	s_barrier
	s_add_i32 s0, s0, s45
	v_lshl_add_u64 v[226:227], v[226:227], 0, s[28:29]
	s_mov_b32 m0, s0
	ds_read_b128 v[188:191], v198 offset:49152
	ds_read_b128 v[192:195], v198 offset:50176
	ds_read_b128 v[202:205], v198 offset:51200
	ds_read_b128 v[206:209], v198 offset:52224
	ds_read_b128 v[210:213], v198 offset:53248
	ds_read_b128 v[214:217], v198 offset:54272
	ds_read_b128 v[218:221], v198 offset:55296
	ds_read_b128 v[222:225], v198 offset:56320
	global_load_lds_dwordx4 v[226:227], off
	s_add_i32 m0, s0, 0x2000
	s_add_u32 s6, s40, 0x2b0080
	v_lshl_add_u64 v[226:227], v[228:229], 0, s[28:29]
	s_addc_u32 s7, s41, 0
	s_add_i32 s0, s68, s45
	global_load_lds_dwordx4 v[226:227], off
	v_lshl_add_u64 v[226:227], s[6:7], 0, v[158:159]
	s_mov_b32 m0, s0
	s_nop 0
	global_load_lds_dwordx4 v[226:227], off
	v_lshl_add_u64 v[226:227], s[6:7], 0, v[162:163]
	s_add_i32 m0, s0, 0x2000
	s_nop 0
	global_load_lds_dwordx4 v[226:227], off
	v_lshl_add_u64 v[226:227], v[230:231], 0, s[28:29]
	s_mov_b32 m0, s54
	s_nop 0
	global_load_lds_dwordx4 v[226:227], off
	v_lshl_add_u64 v[226:227], v[232:233], 0, s[28:29]
	s_mov_b32 m0, s55
	s_nop 0
	global_load_lds_dwordx4 v[226:227], off
	s_waitcnt vmcnt(8)
	s_waitcnt lgkmcnt(0)
	s_setprio 1
	s_barrier
	v_mfma_f32_16x16x32_bf16 v[64:67], v[136:139], v[188:191], v[64:67]
	v_mfma_f32_16x16x32_bf16 v[64:67], v[140:143], v[192:195], v[64:67]
	v_mfma_f32_16x16x32_bf16 v[60:63], v[144:147], v[188:191], v[60:63]
	v_mfma_f32_16x16x32_bf16 v[60:63], v[148:151], v[192:195], v[60:63]
	v_mfma_f32_16x16x32_bf16 v[48:51], v[136:139], v[202:205], v[48:51]
	v_mfma_f32_16x16x32_bf16 v[48:51], v[140:143], v[206:209], v[48:51]
	v_mfma_f32_16x16x32_bf16 v[44:47], v[144:147], v[202:205], v[44:47]
	v_mfma_f32_16x16x32_bf16 v[44:47], v[148:151], v[206:209], v[44:47]
	v_mfma_f32_16x16x32_bf16 v[32:35], v[136:139], v[210:213], v[32:35]
	v_mfma_f32_16x16x32_bf16 v[32:35], v[140:143], v[214:217], v[32:35]
	v_mfma_f32_16x16x32_bf16 v[28:31], v[144:147], v[210:213], v[28:31]
	v_mfma_f32_16x16x32_bf16 v[28:31], v[148:151], v[214:217], v[28:31]
	v_mfma_f32_16x16x32_bf16 v[16:19], v[136:139], v[218:221], v[16:19]
	v_mfma_f32_16x16x32_bf16 v[16:19], v[140:143], v[222:225], v[16:19]
	v_mfma_f32_16x16x32_bf16 v[12:15], v[144:147], v[218:221], v[12:15]
	v_mfma_f32_16x16x32_bf16 v[12:15], v[148:151], v[222:225], v[12:15]
	s_setprio 0
	s_setprio 1
	v_mfma_f32_16x16x32_bf16 v[56:59], v[152:155], v[188:191], v[56:59]
	v_mfma_f32_16x16x32_bf16 v[56:59], v[176:179], v[192:195], v[56:59]
	v_mfma_f32_16x16x32_bf16 v[52:55], v[180:183], v[188:191], v[52:55]
	v_mfma_f32_16x16x32_bf16 v[52:55], v[184:187], v[192:195], v[52:55]
	v_mfma_f32_16x16x32_bf16 v[40:43], v[152:155], v[202:205], v[40:43]
	v_mfma_f32_16x16x32_bf16 v[40:43], v[176:179], v[206:209], v[40:43]
	v_mfma_f32_16x16x32_bf16 v[36:39], v[180:183], v[202:205], v[36:39]
	v_mfma_f32_16x16x32_bf16 v[36:39], v[184:187], v[206:209], v[36:39]
	v_mfma_f32_16x16x32_bf16 v[24:27], v[152:155], v[210:213], v[24:27]
	v_mfma_f32_16x16x32_bf16 v[24:27], v[176:179], v[214:217], v[24:27]
	v_mfma_f32_16x16x32_bf16 v[20:23], v[180:183], v[210:213], v[20:23]
	v_mfma_f32_16x16x32_bf16 v[20:23], v[184:187], v[214:217], v[20:23]
	v_mfma_f32_16x16x32_bf16 v[8:11], v[152:155], v[218:221], v[8:11]
	v_mfma_f32_16x16x32_bf16 v[8:11], v[176:179], v[222:225], v[8:11]
	v_mfma_f32_16x16x32_bf16 v[4:7], v[180:183], v[218:221], v[4:7]
	v_mfma_f32_16x16x32_bf16 v[4:7], v[184:187], v[222:225], v[4:7]
	s_setprio 0
	s_barrier
	s_add_i32 s67, s67, 2
	s_cmpk_gt_u32 s67, 0xa9
	s_mov_b64 s[6:7], s[8:9]
	s_cbranch_scc0 .LBB0_1703
	s_and_b64 vcc, exec, s[30:31]
	s_cbranch_vccz .LBB0_1706
	s_barrier
